# attention loops: cross-half row-max exchange by v_permlane32_swap instead of ds_bpermute
# baseline (speedup 1.0000x reference)
; #define MFMA32(a, b, c) __builtin_amdgcn_mfma_f32_32x32x16_bf16((a), (b), (c), 0, 0, 0)
; template <int D>
; DI void attn_pass(const bfr* __restrict__ P, int b, int tq_wave, int qcol, int kcol, int vcol, int key0, int nkt, char* smem, f32x16 (&o)[2]) {
;     ...
;   for (int kt = 0; kt < nkt; ++kt) {
;     bfr* sK = sbase + (kt & 1) * 9216;
;     bfr* sV = sK + 64 * 72;
;     { int c = gt, row = c >> 3, kc = c & 7; *(u32x4*)(sK + row * KP + kc * 8) = kreg[0]; }
;     for (int i = 0; i < 1; ++i) {
;       int c = gt, row = c >> 3, kc = c & 7;
;       unsigned wds[4] = {vreg[i].x, vreg[i].y, vreg[i].z, vreg[i].w};
; #pragma unroll
;       for (int e = 0; e < 4; ++e) {
;         sV[(kc * 8 + 2 * e) * 72 + (row ^ (kc << 3))] = (bfr)(wds[e] & 0xffffu);
;         sV[(kc * 8 + 2 * e + 1) * 72 + (row ^ (kc << 3))] = (bfr)(wds[e] >> 16);
;       }
;     }
;     __syncthreads();
;     if (kt + 1 < nkt) {
;       const bfr* Pn = Pb + (size_t)(kt + 1) * 64 * PW;
;       { int c = gt, row = c >> 3, kc = c & 7; kreg[0] = *(const u32x4*)(Pn + (size_t)row * PW + kcol + kc * 8); vreg[0] = *(const u32x4*)(Pn + (size_t)row * PW + vcol + kc * 8); }
;     }
;     f32x16 s[2];
; #pragma unroll
;     for (int t2 = 0; t2 < 2; ++t2) {
; #pragma unroll
;       for (int i = 0; i < 16; ++i) s[t2][i] = 0.f;
; #pragma unroll
;       for (int ks = 0; ks < KS; ++ks) {
;         bf16x8 a = *(const bf16x8*)(sK + (t2 * 32 + r) * KP + ks * 16 + h * 8);
;         s[t2] = MFMA32(a, qf[ks], s[t2]);
;       }
;     }
;     float mx = s[0][0];
; #pragma unroll
;     for (int i = 0; i < 16; ++i) { mx = fmaxf(mx, s[0][i]); mx = fmaxf(mx, s[1][i]); }
;     mx = fmaxf(mx, __shfl_xor(mx, 32));
;     float mnew = fmaxf(mrun, mx);
;     float alpha = __builtin_amdgcn_exp2f(mrun - mnew);
;     mrun = mnew;
;     float ps = 0.f;
; #pragma unroll
;     for (int i = 0; i < 16; ++i) {
;       s[0][i] = __builtin_amdgcn_exp2f(s[0][i] - mnew); ps += s[0][i];
;       s[1][i] = __builtin_amdgcn_exp2f(s[1][i] - mnew); ps += s[1][i];
;     }
;     lsum = lsum * alpha + ps;
; #pragma unroll
;     for (int i = 0; i < 16; ++i) { accO[0][i] *= alpha; accO[1][i] *= alpha; }
.LBB0_400:
	s_bitcmp1_b32 s10, 0
	s_cselect_b32 s11, 0x4800, 0
	s_add_i32 s11, s11, 0
	v_add3_u32 v32, s11, v115, v90
	v_add_u32_e32 v121, s11, v114
	v_mov_b32_e32 v120, v113
	s_waitcnt vmcnt(1)
	ds_write_b128 v32, v[84:87]
	v_add3_u32 v32, s11, v117, v118
	v_add3_u32 v33, s11, v118, v117
	v_add_u32_e32 v113, v121, v152
	s_waitcnt vmcnt(0)
	ds_write_b16 v32, v80 offset:9216
	ds_write_b16_d16_hi v33, v80 offset:9360
	ds_write_b16 v32, v81 offset:9504
	ds_write_b16_d16_hi v33, v81 offset:9648
	ds_write_b16 v32, v82 offset:9792
	ds_write_b16_d16_hi v33, v82 offset:9936
	ds_write_b16 v32, v83 offset:10080
	ds_write_b16_d16_hi v33, v83 offset:10224
	s_waitcnt lgkmcnt(0)
	s_barrier
	global_load_dwordx4 v[84:87], v[92:93], off
	global_load_dwordx4 v[80:83], v[94:95], off
	ds_read_b128 v[32:35], v113
	ds_read_b128 v[48:51], v113 offset:32
	s_waitcnt lgkmcnt(1)
	v_mfma_f32_32x32x16_bf16 v[32:47], v[32:35], v[76:79], 0
	ds_read_b128 v[122:125], v113 offset:4640
	v_mov_b32_e32 v96, v119
	s_add_i32 s10, s10, 1
	v_lshl_add_u64 v[92:93], v[92:93], 0, s[12:13]
	v_lshl_add_u64 v[94:95], v[94:95], 0, s[12:13]
	s_cmp_lg_u32 s10, 3
	s_waitcnt lgkmcnt(1)
	v_mfma_f32_32x32x16_bf16 v[32:47], v[48:51], v[72:75], v[32:47]
	ds_read_b128 v[48:51], v113 offset:64
	s_waitcnt lgkmcnt(0)
	v_mfma_f32_32x32x16_bf16 v[32:47], v[48:51], v[68:71], v[32:47]
	ds_read_b128 v[48:51], v113 offset:96
	s_waitcnt lgkmcnt(0)
	v_mfma_f32_32x32x16_bf16 v[32:47], v[48:51], v[64:67], v[32:47]
	ds_read_b128 v[48:51], v113 offset:4608
	s_waitcnt lgkmcnt(0)
	v_mfma_f32_32x32x16_bf16 v[48:63], v[48:51], v[76:79], 0
	s_nop 8
	v_max_f32_e32 v119, v32, v32
	v_mfma_f32_32x32x16_bf16 v[48:63], v[122:125], v[72:75], v[48:63]
	ds_read_b128 v[122:125], v113 offset:4672
	s_waitcnt lgkmcnt(0)
	v_mfma_f32_32x32x16_bf16 v[48:63], v[122:125], v[68:71], v[48:63]
	ds_read_b128 v[122:125], v113 offset:4704
	s_waitcnt lgkmcnt(0)
	v_mfma_f32_32x32x16_bf16 v[48:63], v[122:125], v[64:67], v[48:63]
	s_nop 11
	v_max_f32_e32 v113, v48, v48
	v_max_f32_e32 v113, v119, v113
	v_max3_f32 v113, v113, v33, v49
	v_max3_f32 v113, v113, v34, v50
	v_max3_f32 v113, v113, v35, v51
	v_max3_f32 v113, v113, v36, v52
	v_max3_f32 v113, v113, v37, v53
	v_max3_f32 v113, v113, v38, v54
	v_max3_f32 v113, v113, v39, v55
	v_max3_f32 v113, v113, v40, v56
	v_max3_f32 v113, v113, v41, v57
	v_max3_f32 v113, v113, v42, v58
	v_max3_f32 v113, v113, v43, v59
	v_max3_f32 v113, v113, v44, v60
	v_max3_f32 v113, v113, v45, v61
	v_max3_f32 v113, v113, v46, v62
	v_max3_f32 v113, v113, v47, v63
	v_mov_b32_e32 v119, v113
	s_nop 1
	v_permlane32_swap_b32_e32 v113, v119
	s_waitcnt lgkmcnt(0)
	v_max3_f32 v119, v96, v113, v119
	v_sub_f32_e32 v32, v32, v119
	v_sub_f32_e32 v38, v38, v119
	v_exp_f32_e32 v32, v32
	v_sub_f32_e32 v48, v48, v119
	v_sub_f32_e32 v36, v36, v119
	v_exp_f32_e32 v124, v38
	v_sub_f32_e32 v38, v54, v119
	v_exp_f32_e32 v48, v48
	v_sub_f32_e32 v33, v33, v119
	v_exp_f32_e32 v122, v36
	v_sub_f32_e32 v36, v52, v119
	v_exp_f32_e32 v52, v38
	v_sub_f32_e32 v38, v39, v119
	v_exp_f32_e32 v33, v33
	v_sub_f32_e32 v49, v49, v119
	v_sub_f32_e32 v37, v37, v119
	v_exp_f32_e32 v125, v38
	v_sub_f32_e32 v38, v55, v119
	v_exp_f32_e32 v49, v49
	v_sub_f32_e32 v34, v34, v119
	v_exp_f32_e32 v123, v37
	v_sub_f32_e32 v37, v53, v119
	v_exp_f32_e32 v53, v38
	v_sub_f32_e32 v38, v40, v119
	v_sub_f32_e32 v40, v42, v119
	v_sub_f32_e32 v42, v44, v119
	v_exp_f32_e32 v34, v34
	v_sub_f32_e32 v50, v50, v119
	v_exp_f32_e32 v54, v38
	v_sub_f32_e32 v38, v56, v119
	v_exp_f32_e32 v56, v40
	v_sub_f32_e32 v40, v58, v119
	v_exp_f32_e32 v58, v42
	v_sub_f32_e32 v42, v60, v119
	v_add_f32_e32 v60, 0, v32
	v_exp_f32_e32 v50, v50
	v_sub_f32_e32 v35, v35, v119
	v_add_f32_e32 v60, v48, v60
	v_exp_f32_e32 v35, v35
	v_sub_f32_e32 v51, v51, v119
	v_add_f32_e32 v60, v33, v60
	v_exp_f32_e32 v51, v51
	v_add_f32_e32 v60, v49, v60
	v_add_f32_e32 v60, v34, v60
	v_exp_f32_e32 v36, v36
	v_add_f32_e32 v60, v50, v60
	v_add_f32_e32 v60, v35, v60
	v_exp_f32_e32 v37, v37
	v_add_f32_e32 v60, v51, v60
	v_add_f32_e32 v60, v122, v60
	v_add_f32_e32 v60, v36, v60
	v_add_f32_e32 v60, v123, v60
	v_add_f32_e32 v60, v37, v60
	v_add_f32_e32 v60, v124, v60
	v_exp_f32_e32 v38, v38
	v_sub_f32_e32 v39, v41, v119
	v_add_f32_e32 v60, v52, v60
	v_exp_f32_e32 v55, v39
	v_sub_f32_e32 v39, v57, v119
	v_add_f32_e32 v60, v125, v60
	v_exp_f32_e32 v39, v39
	v_add_f32_e32 v60, v53, v60
	v_add_f32_e32 v60, v54, v60
	v_exp_f32_e32 v40, v40
	v_sub_f32_e32 v41, v43, v119
	v_add_f32_e32 v60, v38, v60
	v_exp_f32_e32 v57, v41
	v_sub_f32_e32 v41, v59, v119
	v_add_f32_e32 v60, v55, v60
	v_exp_f32_e32 v41, v41
	v_add_f32_e32 v60, v39, v60
	v_add_f32_e32 v60, v56, v60
	v_exp_f32_e32 v42, v42
	v_sub_f32_e32 v43, v45, v119
	v_add_f32_e32 v60, v40, v60
	v_exp_f32_e32 v59, v43
	v_sub_f32_e32 v43, v61, v119
	v_add_f32_e32 v60, v57, v60
	v_exp_f32_e32 v43, v43
	v_sub_f32_e32 v44, v46, v119
	v_add_f32_e32 v60, v41, v60
	v_exp_f32_e32 v46, v44
	v_sub_f32_e32 v44, v62, v119
	v_add_f32_e32 v60, v58, v60
	v_exp_f32_e32 v44, v44
	v_sub_f32_e32 v45, v47, v119
	v_add_f32_e32 v60, v42, v60
	v_exp_f32_e32 v47, v45
	v_sub_f32_e32 v45, v63, v119
	v_add_f32_e32 v60, v59, v60
	v_exp_f32_e32 v45, v45
	v_add_f32_e32 v60, v43, v60
	v_add_f32_e32 v60, v46, v60
	v_add_f32_e32 v60, v44, v60
	v_add_f32_e32 v60, v47, v60
	v_add_f32_e32 v113, v45, v60
	v_lshl_add_u32 v60, v112, 1, v121
	v_lshl_add_u32 v61, v111, 1, v121
	v_cvt_pk_bf16_f32 v32, v32, v33
	v_cvt_pk_bf16_f32 v33, v34, v35
	v_cvt_pk_bf16_f32 v34, v122, v123
	v_cvt_pk_bf16_f32 v35, v124, v125
	ds_read_b64 v[122:123], v60 offset:9216
	ds_read_b64 v[124:125], v61 offset:9216
	v_sub_f32_e32 v96, v96, v119
	v_exp_f32_e32 v96, v96
	v_add_u32_e32 v61, s11, v116
	v_lshl_add_u32 v62, v110, 1, v61
	v_pk_mul_f32 v[30:31], v[30:31], v[96:97] op_sel_hi:[1,0]
	v_pk_mul_f32 v[28:29], v[28:29], v[96:97] op_sel_hi:[1,0]
	v_pk_mul_f32 v[26:27], v[26:27], v[96:97] op_sel_hi:[1,0]
	v_pk_mul_f32 v[24:25], v[24:25], v[96:97] op_sel_hi:[1,0]
	v_pk_mul_f32 v[22:23], v[22:23], v[96:97] op_sel_hi:[1,0]
	v_pk_mul_f32 v[20:21], v[20:21], v[96:97] op_sel_hi:[1,0]
	v_pk_mul_f32 v[18:19], v[18:19], v[96:97] op_sel_hi:[1,0]
	v_pk_mul_f32 v[16:17], v[16:17], v[96:97] op_sel_hi:[1,0]
	v_pk_mul_f32 v[14:15], v[14:15], v[96:97] op_sel_hi:[1,0]
	v_pk_mul_f32 v[12:13], v[12:13], v[96:97] op_sel_hi:[1,0]
	s_waitcnt lgkmcnt(0)
; template <int D>
; DI void attn_pass(const bfr* __restrict__ P, int b, int tq_wave, int qcol, int kcol, int vcol, int key0, int nkt, char* smem, f32x16 (&o)[2]) {
;     ...
;   for (int kt = 0; kt < nkt; ++kt) {
;     bfr* sK = sbase + (kt & 1) * 9216;
;     bfr* sV = sK + 64 * 72;
;     { int c = gt, row = c >> 3, kc = c & 7; *(u32x4*)(sK + row * KP + kc * 8) = kreg[0]; }
;     for (int i = 0; i < 1; ++i) {
;       int c = gt, row = c >> 3, kc = c & 7;
;       unsigned wds[4] = {vreg[i].x, vreg[i].y, vreg[i].z, vreg[i].w};
; #pragma unroll
;       for (int e = 0; e < 4; ++e) {
;         sV[(kc * 8 + 2 * e) * 72 + (row ^ (kc << 3))] = (bfr)(wds[e] & 0xffffu);
;         sV[(kc * 8 + 2 * e + 1) * 72 + (row ^ (kc << 3))] = (bfr)(wds[e] >> 16);
;       }
;     }
;     __syncthreads();
;     if (kt + 1 < nkt) {
;       const bfr* Pn = Pb + (size_t)(kt + 1) * 64 * PW;
;       { int c = gt, row = c >> 3, kc = c & 7; kreg[0] = *(const u32x4*)(Pn + (size_t)row * PW + kcol + kc * 8); vreg[0] = *(const u32x4*)(Pn + (size_t)row * PW + vcol + kc * 8); }
;     }
;     f32x16 s[2];
; #pragma unroll
;     for (int t2 = 0; t2 < 2; ++t2) {
; #pragma unroll
;       for (int i = 0; i < 16; ++i) s[t2][i] = 0.f;
; #pragma unroll
;       for (int ks = 0; ks < KS; ++ks) {
;         bf16x8 a = *(const bf16x8*)(sK + (t2 * 32 + r) * KP + ks * 16 + h * 8);
;         s[t2] = MFMA32(a, qf[ks], s[t2]);
;       }
;     }
;     float mx = s[0][0];
; #pragma unroll
;     ...
;     for (int i = 0; i < 16; ++i) { accO[0][i] *= alpha; accO[1][i] *= alpha; }
; #pragma unroll
;     for (int t2 = 0; t2 < 2; ++t2)
; #pragma unroll
;       for (int j = 0; j < 2; ++j) {
;         unsigned pk[4];
; #pragma unroll
;         for (int e = 0; e < 4; ++e) pk[e] = pack2(s[t2][8 * j + 2 * e], s[t2][8 * j + 2 * e + 1]);
;         u32x4 pku = {pk[0], pk[1], pk[2], pk[3]};
;         bf16x8 pf = __builtin_bit_cast(bf16x8, pku);
; #pragma unroll
;         for (int dt = 0; dt < 2; ++dt) {
;           const int vsw = (((dt * 32 + r) >> 3) & 7) << 3;
;           const bfr* vrow = sV + (dt * 32 + r) * 72;
;           s16x4 lo = *(const s16x4*)(vrow + ((t2 * 32 + 16 * j + 4 * h) ^ vsw));
;           s16x4 hi = *(const s16x4*)(vrow + ((t2 * 32 + 16 * j + 4 * h + 8) ^ vsw));
;           bf16x8 vf = __builtin_shufflevector(lo, hi, 0, 1, 2, 3, 4, 5, 6, 7);
;           accO[dt] = MFMA32(vf, pf, accO[dt]);
;         }
;       }
;   }
	v_mfma_f32_32x32x16_bf16 v[16:31], v[122:125], v[32:35], v[16:31]
	ds_read_b64 v[122:123], v62 offset:9216
	v_lshl_add_u32 v62, v109, 1, v61
	ds_read_b64 v[124:125], v62 offset:9216
	v_mul_f32_e64 v10, v10, v96
	v_mul_f32_e64 v11, v11, v96
	v_pk_mul_f32 v[8:9], v[8:9], v[96:97] op_sel_hi:[1,0]
	v_pk_mul_f32 v[6:7], v[6:7], v[96:97] op_sel_hi:[1,0]
	v_pk_mul_f32 v[4:5], v[4:5], v[96:97] op_sel_hi:[1,0]
	v_pk_mul_f32 v[2:3], v[2:3], v[96:97] op_sel_hi:[1,0]
	v_pk_mul_f32 v[0:1], v[0:1], v[96:97] op_sel_hi:[1,0]
	v_fmac_f32_e32 v113, v120, v96
	s_waitcnt lgkmcnt(0)
	v_mfma_f32_32x32x16_bf16 v[0:15], v[122:125], v[32:35], v[0:15]
	v_cvt_pk_bf16_f32 v32, v54, v55
	v_cvt_pk_bf16_f32 v33, v56, v57
	v_cvt_pk_bf16_f32 v34, v58, v59
	v_cvt_pk_bf16_f32 v35, v46, v47
	v_lshl_add_u32 v46, v108, 1, v121
	ds_read_b64 v[54:55], v46 offset:9216
	v_lshl_add_u32 v46, v107, 1, v121
	ds_read_b64 v[56:57], v46 offset:9216
	v_lshl_add_u32 v46, v106, 1, v61
	s_waitcnt lgkmcnt(0)
	v_mfma_f32_32x32x16_bf16 v[16:31], v[54:57], v[32:35], v[16:31]
	ds_read_b64 v[54:55], v46 offset:9216
	v_lshl_add_u32 v46, v105, 1, v61
	ds_read_b64 v[56:57], v46 offset:9216
	s_waitcnt lgkmcnt(0)
	v_mfma_f32_32x32x16_bf16 v[0:15], v[54:57], v[32:35], v[0:15]
	v_cvt_pk_bf16_f32 v32, v48, v49
	v_cvt_pk_bf16_f32 v33, v50, v51
	v_cvt_pk_bf16_f32 v34, v36, v37
	v_lshl_add_u32 v36, v104, 1, v121
	v_cvt_pk_bf16_f32 v35, v52, v53
	ds_read_b64 v[46:47], v60 offset:9280
	ds_read_b64 v[48:49], v36 offset:9216
	v_lshl_add_u32 v36, v103, 1, v61
	s_waitcnt lgkmcnt(0)
	v_mfma_f32_32x32x16_bf16 v[16:31], v[46:49], v[32:35], v[16:31]
	ds_read_b64 v[46:47], v36 offset:9216
	v_lshl_add_u32 v36, v102, 1, v61
	ds_read_b64 v[48:49], v36 offset:9216
	v_lshl_add_u32 v36, v100, 1, v121
	s_waitcnt lgkmcnt(0)
	v_mfma_f32_32x32x16_bf16 v[0:15], v[46:49], v[32:35], v[0:15]
	v_cvt_pk_bf16_f32 v32, v38, v39
	v_lshl_add_u32 v38, v101, 1, v121
	v_cvt_pk_bf16_f32 v33, v40, v41
	v_cvt_pk_bf16_f32 v34, v42, v43
	v_cvt_pk_bf16_f32 v35, v44, v45
	ds_read_b64 v[36:37], v36 offset:9216
	ds_read_b64 v[38:39], v38 offset:9216
	s_waitcnt lgkmcnt(0)
	v_mfma_f32_32x32x16_bf16 v[16:31], v[36:39], v[32:35], v[16:31]
	v_lshl_add_u32 v36, v99, 1, v61
	v_lshl_add_u32 v38, v98, 1, v61
	ds_read_b64 v[36:37], v36 offset:9216
	ds_read_b64 v[38:39], v38 offset:9216
	s_waitcnt lgkmcnt(0)
	v_mfma_f32_32x32x16_bf16 v[0:15], v[36:39], v[32:35], v[0:15]
	s_cbranch_scc1 .LBB0_400
	v_add3_u32 v32, 0, v115, v90
	s_waitcnt vmcnt(1)
	ds_write_b128 v32, v[84:87] offset:18432
	v_add3_u32 v32, 0, v117, v118
	v_add3_u32 v33, 0, v118, v117
	s_waitcnt vmcnt(0)
	ds_write_b16 v32, v80 offset:27648
	ds_write_b16_d16_hi v33, v80 offset:27792
	ds_write_b16 v32, v81 offset:27936
	ds_write_b16_d16_hi v33, v81 offset:28080
	ds_write_b16 v32, v82 offset:28224
	ds_write_b16_d16_hi v33, v82 offset:28368
	ds_write_b16 v32, v83 offset:28512
	ds_write_b16_d16_hi v33, v83 offset:28656
	v_add_u32_e32 v80, 0, v114
	v_add_u32_e32 v81, v80, v152
	s_waitcnt lgkmcnt(0)
	s_barrier
	ds_read_b128 v[32:35], v81 offset:18432
	ds_read_b128 v[48:51], v81 offset:18464
	s_waitcnt lgkmcnt(1)
	v_mfma_f32_32x32x16_bf16 v[32:47], v[32:35], v[76:79], 0
	v_lshlrev_b32_e32 v152, 1, v88
	s_waitcnt lgkmcnt(0)
	v_mfma_f32_32x32x16_bf16 v[32:47], v[48:51], v[72:75], v[32:47]
	ds_read_b128 v[48:51], v81 offset:18496
	s_waitcnt lgkmcnt(0)
	v_mfma_f32_32x32x16_bf16 v[32:47], v[48:51], v[68:71], v[32:47]
	ds_read_b128 v[48:51], v81 offset:18528
	s_waitcnt lgkmcnt(0)
	v_mfma_f32_32x32x16_bf16 v[32:47], v[48:51], v[64:67], v[32:47]
	ds_read_b128 v[48:51], v81 offset:23040
	s_waitcnt lgkmcnt(0)
	v_mfma_f32_32x32x16_bf16 v[48:63], v[48:51], v[76:79], 0
	ds_read_b128 v[76:79], v81 offset:23072
	s_waitcnt lgkmcnt(0)
	v_mfma_f32_32x32x16_bf16 v[48:63], v[76:79], v[72:75], v[48:63]
	ds_read_b128 v[72:75], v81 offset:23104
	s_waitcnt lgkmcnt(0)
	v_mfma_f32_32x32x16_bf16 v[48:63], v[72:75], v[68:71], v[48:63]
	ds_read_b128 v[68:71], v81 offset:23136
	s_waitcnt lgkmcnt(0)
	v_mfma_f32_32x32x16_bf16 v[48:63], v[68:71], v[64:67], v[48:63]
	v_max_f32_e32 v65, v32, v32
	v_lshl_add_u32 v66, v112, 1, v80
	v_add_u32_e32 v67, 0x1200, v80
	s_nop 8
	v_max_f32_e32 v64, v48, v48
	v_max_f32_e32 v64, v65, v64
	v_max3_f32 v64, v64, v33, v49
	v_max3_f32 v64, v64, v34, v50
	v_max3_f32 v64, v64, v35, v51
	v_max3_f32 v64, v64, v36, v52
	v_max3_f32 v64, v64, v37, v53
	v_max3_f32 v64, v64, v38, v54
	v_max3_f32 v64, v64, v39, v55
	v_max3_f32 v64, v64, v40, v56
	v_max3_f32 v64, v64, v41, v57
	v_max3_f32 v64, v64, v42, v58
	v_max3_f32 v64, v64, v43, v59
	v_max3_f32 v64, v64, v44, v60
	v_max3_f32 v64, v64, v45, v61
	v_max3_f32 v64, v64, v46, v62
	v_max3_f32 v64, v64, v47, v63
	ds_bpermute_b32 v65, v91, v64
	s_waitcnt lgkmcnt(0)
; template <int D>
; DI void attn_pass(const bfr* __restrict__ P, int b, int tq_wave, int qcol, int kcol, int vcol, int key0, int nkt, char* smem, f32x16 (&o)[2]) {
;     ...
;     float mx = s[0][0];
; #pragma unroll
;     for (int i = 0; i < 16; ++i) { mx = fmaxf(mx, s[0][i]); mx = fmaxf(mx, s[1][i]); }
;     mx = fmaxf(mx, __shfl_xor(mx, 32));
;     float mnew = fmaxf(mrun, mx);
;     float alpha = __builtin_amdgcn_exp2f(mrun - mnew);
;     mrun = mnew;
;     float ps = 0.f;
; #pragma unroll
;     for (int i = 0; i < 16; ++i) {
;       s[0][i] = __builtin_amdgcn_exp2f(s[0][i] - mnew); ps += s[0][i];
;       s[1][i] = __builtin_amdgcn_exp2f(s[1][i] - mnew); ps += s[1][i];
;     }
;     lsum = lsum * alpha + ps;
; #pragma unroll
;     for (int i = 0; i < 16; ++i) { accO[0][i] *= alpha; accO[1][i] *= alpha; }
	v_max3_f32 v65, v119, v64, v65
	v_sub_f32_e32 v64, v119, v65
	v_sub_f32_e32 v32, v32, v65
	v_exp_f32_e32 v64, v64
	v_exp_f32_e32 v32, v32
	v_sub_f32_e32 v48, v48, v65
	v_exp_f32_e32 v48, v48
	v_sub_f32_e32 v33, v33, v65
	v_exp_f32_e32 v33, v33
	v_sub_f32_e32 v49, v49, v65
	v_exp_f32_e32 v49, v49
	v_sub_f32_e32 v34, v34, v65
	v_exp_f32_e32 v34, v34
	v_sub_f32_e32 v50, v50, v65
	v_sub_f32_e32 v35, v35, v65
	v_sub_f32_e32 v51, v51, v65
	v_sub_f32_e32 v36, v36, v65
	v_sub_f32_e32 v52, v52, v65
	v_sub_f32_e32 v37, v37, v65
	v_sub_f32_e32 v53, v53, v65
	v_sub_f32_e32 v38, v38, v65
	v_sub_f32_e32 v54, v54, v65
	v_sub_f32_e32 v39, v39, v65
	v_sub_f32_e32 v55, v55, v65
	v_sub_f32_e32 v40, v40, v65
	v_sub_f32_e32 v56, v56, v65
	v_sub_f32_e32 v41, v41, v65
	v_sub_f32_e32 v57, v57, v65
	v_sub_f32_e32 v42, v42, v65
	v_sub_f32_e32 v58, v58, v65
	v_sub_f32_e32 v43, v43, v65
	v_sub_f32_e32 v59, v59, v65
	v_sub_f32_e32 v44, v44, v65
	v_sub_f32_e32 v60, v60, v65
	v_sub_f32_e32 v45, v45, v65
	v_sub_f32_e32 v61, v61, v65
	v_sub_f32_e32 v46, v46, v65
	v_sub_f32_e32 v62, v62, v65
	v_sub_f32_e32 v47, v47, v65
	v_sub_f32_e32 v63, v63, v65
	v_pk_mul_f32 v[30:31], v[30:31], v[64:65] op_sel_hi:[1,0]
	v_pk_mul_f32 v[28:29], v[28:29], v[64:65] op_sel_hi:[1,0]
	v_pk_mul_f32 v[26:27], v[26:27], v[64:65] op_sel_hi:[1,0]
	v_pk_mul_f32 v[24:25], v[24:25], v[64:65] op_sel_hi:[1,0]
	v_pk_mul_f32 v[22:23], v[22:23], v[64:65] op_sel_hi:[1,0]
	v_pk_mul_f32 v[20:21], v[20:21], v[64:65] op_sel_hi:[1,0]
	v_pk_mul_f32 v[18:19], v[18:19], v[64:65] op_sel_hi:[1,0]
	v_pk_mul_f32 v[16:17], v[16:17], v[64:65] op_sel_hi:[1,0]
	v_pk_mul_f32 v[14:15], v[14:15], v[64:65] op_sel_hi:[1,0]
	v_pk_mul_f32 v[12:13], v[12:13], v[64:65] op_sel_hi:[1,0]
	v_pk_mul_f32 v[10:11], v[10:11], v[64:65] op_sel_hi:[1,0]
	v_pk_mul_f32 v[8:9], v[8:9], v[64:65] op_sel_hi:[1,0]
	v_pk_mul_f32 v[6:7], v[6:7], v[64:65] op_sel_hi:[1,0]
	v_pk_mul_f32 v[4:5], v[4:5], v[64:65] op_sel_hi:[1,0]
	v_pk_mul_f32 v[2:3], v[2:3], v[64:65] op_sel_hi:[1,0]
	v_pk_mul_f32 v[0:1], v[0:1], v[64:65] op_sel_hi:[1,0]
	v_add_f32_e32 v65, 0, v32
	v_exp_f32_e32 v50, v50
	v_add_f32_e32 v65, v48, v65
	v_exp_f32_e32 v35, v35
	v_add_f32_e32 v65, v33, v65
	v_exp_f32_e32 v51, v51
	v_add_f32_e32 v65, v49, v65
	v_exp_f32_e32 v36, v36
	v_add_f32_e32 v65, v34, v65
	v_exp_f32_e32 v52, v52
	v_add_f32_e32 v65, v50, v65
	v_exp_f32_e32 v37, v37
	v_add_f32_e32 v65, v35, v65
	v_exp_f32_e32 v53, v53
	v_add_f32_e32 v65, v51, v65
	v_exp_f32_e32 v38, v38
	v_add_f32_e32 v65, v36, v65
	v_exp_f32_e32 v54, v54
	v_add_f32_e32 v65, v52, v65
	v_exp_f32_e32 v39, v39
	v_add_f32_e32 v65, v37, v65
	v_add_f32_e32 v65, v53, v65
	v_add_f32_e32 v65, v38, v65
	v_add_f32_e32 v65, v54, v65
	v_cvt_pk_bf16_f32 v32, v32, v33
	v_cvt_pk_bf16_f32 v33, v34, v35
	v_cvt_pk_bf16_f32 v34, v36, v37
	v_cvt_pk_bf16_f32 v35, v38, v39
	v_lshl_add_u32 v38, v111, 1, v80
	v_add_f32_e32 v65, v39, v65
	ds_read_b64 v[36:37], v66 offset:27648
	ds_read_b64 v[38:39], v38 offset:27648
	s_waitcnt lgkmcnt(0)
	v_mfma_f32_32x32x16_bf16 v[16:31], v[36:39], v[32:35], v[16:31]
	v_lshl_add_u32 v36, v110, 1, v67
	v_lshl_add_u32 v38, v109, 1, v67
	ds_read_b64 v[36:37], v36 offset:27648
	ds_read_b64 v[38:39], v38 offset:27648
	v_exp_f32_e32 v40, v40
	v_exp_f32_e32 v41, v41
	v_exp_f32_e32 v42, v42
	s_waitcnt lgkmcnt(0)
	v_mfma_f32_32x32x16_bf16 v[0:15], v[36:39], v[32:35], v[0:15]
	v_lshl_add_u32 v36, v108, 1, v80
	v_lshl_add_u32 v38, v107, 1, v80
	v_exp_f32_e32 v43, v43
	v_exp_f32_e32 v44, v44
	v_exp_f32_e32 v45, v45
	v_exp_f32_e32 v46, v46
	v_exp_f32_e32 v47, v47
	v_cvt_pk_bf16_f32 v32, v40, v41
	v_cvt_pk_bf16_f32 v33, v42, v43
	v_cvt_pk_bf16_f32 v34, v44, v45
	v_cvt_pk_bf16_f32 v35, v46, v47
	ds_read_b64 v[36:37], v36 offset:27648
	ds_read_b64 v[38:39], v38 offset:27648
	s_waitcnt lgkmcnt(0)
	v_mfma_f32_32x32x16_bf16 v[16:31], v[36:39], v[32:35], v[16:31]
	v_lshl_add_u32 v36, v106, 1, v67
	v_lshl_add_u32 v38, v105, 1, v67
	ds_read_b64 v[36:37], v36 offset:27648
	ds_read_b64 v[38:39], v38 offset:27648
	v_exp_f32_e32 v55, v55
	v_exp_f32_e32 v56, v56
	v_exp_f32_e32 v57, v57
	s_waitcnt lgkmcnt(0)
	v_mfma_f32_32x32x16_bf16 v[0:15], v[36:39], v[32:35], v[0:15]
	v_lshl_add_u32 v38, v104, 1, v80
	v_cvt_pk_bf16_f32 v32, v48, v49
	v_cvt_pk_bf16_f32 v33, v50, v51
	v_cvt_pk_bf16_f32 v34, v52, v53
	v_cvt_pk_bf16_f32 v35, v54, v55
	ds_read_b64 v[36:37], v66 offset:27712
	ds_read_b64 v[38:39], v38 offset:27648
	s_waitcnt lgkmcnt(0)
; #define MFMA32(a, b, c) __builtin_amdgcn_mfma_f32_32x32x16_bf16((a), (b), (c), 0, 0, 0)
; DI unsigned pack2(float a, float b) { unsigned r; asm volatile("v_cvt_pk_bf16_f32 %0, %1, %2" : "=v"(r) : "v"(a), "v"(b)); return r; }
; template <int D>
; DI void attn_pass(const bfr* __restrict__ P, int b, int tq_wave, int qcol, int kcol, int vcol, int key0, int nkt, char* smem, f32x16 (&o)[2]) {
;     ...
; #pragma unroll
;     for (int t2 = 0; t2 < 2; ++t2)
; #pragma unroll
;       for (int j = 0; j < 2; ++j) {
;         unsigned pk[4];
; #pragma unroll
;         for (int e = 0; e < 4; ++e) pk[e] = pack2(s[t2][8 * j + 2 * e], s[t2][8 * j + 2 * e + 1]);
;         u32x4 pku = {pk[0], pk[1], pk[2], pk[3]};
;         bf16x8 pf = __builtin_bit_cast(bf16x8, pku);
; #pragma unroll
;         for (int dt = 0; dt < 2; ++dt) {
;           const int vsw = (((dt * 32 + r) >> 3) & 7) << 3;
;           const bfr* vrow = sV + (dt * 32 + r) * 72;
;           s16x4 lo = *(const s16x4*)(vrow + ((t2 * 32 + 16 * j + 4 * h) ^ vsw));
;           s16x4 hi = *(const s16x4*)(vrow + ((t2 * 32 + 16 * j + 4 * h + 8) ^ vsw));
;           bf16x8 vf = __builtin_shufflevector(lo, hi, 0, 1, 2, 3, 4, 5, 6, 7);
;           accO[dt] = MFMA32(vf, pf, accO[dt]);
;         }
;       }
;   }
;   lsum += __shfl_xor(lsum, 32);
;   float inv = 1.f / lsum;
; #pragma unroll
;   for (int i = 0; i < 16; ++i) { o[0][i] = accO[0][i] * inv; o[1][i] = accO[1][i] * inv; }
; DI void store_o(bfr* O, int m, int colbase, int h, const f32x16 (&o)[2]) {
; #pragma unroll
;   for (int dt = 0; dt < 2; ++dt)
; #pragma unroll
;     for (int g4 = 0; g4 < 4; ++g4) {
;       int dv = dt * 32 + 8 * g4 + 4 * h;
;       uint2 pk; pk.x = pack2(o[dt][4 * g4], o[dt][4 * g4 + 1]); pk.y = pack2(o[dt][4 * g4 + 2], o[dt][4 * g4 + 3]);
;       *(uint2*)(O + (size_t)m * DM + colbase + dv) = pk;
;     }
; }
	v_mfma_f32_32x32x16_bf16 v[16:31], v[36:39], v[32:35], v[16:31]
	v_lshl_add_u32 v36, v103, 1, v67
	v_lshl_add_u32 v38, v102, 1, v67
	ds_read_b64 v[36:37], v36 offset:27648
	ds_read_b64 v[38:39], v38 offset:27648
	v_exp_f32_e32 v58, v58
	v_exp_f32_e32 v59, v59
	v_exp_f32_e32 v60, v60
	s_waitcnt lgkmcnt(0)
	v_mfma_f32_32x32x16_bf16 v[0:15], v[36:39], v[32:35], v[0:15]
	v_lshl_add_u32 v36, v100, 1, v80
	v_lshl_add_u32 v38, v101, 1, v80
	v_exp_f32_e32 v61, v61
	v_exp_f32_e32 v62, v62
	v_exp_f32_e32 v63, v63
	v_cvt_pk_bf16_f32 v32, v56, v57
	v_cvt_pk_bf16_f32 v33, v58, v59
	v_cvt_pk_bf16_f32 v34, v60, v61
	v_cvt_pk_bf16_f32 v35, v62, v63
	ds_read_b64 v[36:37], v36 offset:27648
	ds_read_b64 v[38:39], v38 offset:27648
	v_add_f32_e32 v65, v55, v65
	v_add_f32_e32 v65, v40, v65
	v_add_f32_e32 v65, v56, v65
	v_add_f32_e32 v65, v41, v65
	v_add_f32_e32 v65, v57, v65
	v_add_f32_e32 v65, v42, v65
	v_add_f32_e32 v65, v58, v65
	v_add_f32_e32 v65, v43, v65
	v_add_f32_e32 v65, v59, v65
	s_waitcnt lgkmcnt(0)
	v_mfma_f32_32x32x16_bf16 v[16:31], v[36:39], v[32:35], v[16:31]
	v_lshl_add_u32 v36, v99, 1, v67
	v_lshl_add_u32 v38, v98, 1, v67
	v_add_f32_e32 v65, v44, v65
	ds_read_b64 v[36:37], v36 offset:27648
	ds_read_b64 v[38:39], v38 offset:27648
	v_add_f32_e32 v65, v60, v65
	v_add_f32_e32 v65, v45, v65
	v_add_f32_e32 v65, v61, v65
	v_add_f32_e32 v65, v46, v65
	v_add_f32_e32 v65, v62, v65
	v_add_f32_e32 v65, v47, v65
	v_add_f32_e32 v65, v63, v65
	v_fmac_f32_e32 v65, v113, v64
	s_waitcnt lgkmcnt(0)
	v_mfma_f32_32x32x16_bf16 v[0:15], v[36:39], v[32:35], v[0:15]
	ds_bpermute_b32 v32, v91, v65
	s_load_dwordx4 s[12:15], s[0:1], 0x100
	s_waitcnt lgkmcnt(0)
	v_add_f32_e32 v32, v65, v32
	v_div_scale_f32 v33, s[10:11], v32, v32, 1.0
	v_rcp_f32_e32 v34, v33
	s_mov_b64 s[10:11], 0x2b7c700
	v_fma_f32 v35, -v33, v34, 1.0
	v_fmac_f32_e32 v34, v35, v34
	v_div_scale_f32 v35, vcc, 1.0, v32, 1.0
	v_mul_f32_e32 v36, v35, v34
	v_fma_f32 v37, -v33, v36, v35
	v_fmac_f32_e32 v36, v37, v34
	v_fma_f32 v33, -v33, v36, v35
	v_div_fmas_f32 v33, v33, v34, v36
	v_div_fixup_f32 v32, v33, v32, 1.0
	v_mul_f32_e32 v33, v0, v32
	v_and_or_b32 v0, v89, 31, v97
	v_mul_f32_e32 v34, v1, v32
	v_ashrrev_i32_e32 v1, 31, v0
	v_lshlrev_b64 v[0:1], 11, v[0:1]
	v_mul_f32_e32 v37, v4, v32
	v_lshl_add_u64 v[0:1], s[14:15], 0, v[0:1]
	v_lshrrev_b32_e32 v4, 2, v89
	v_lshl_add_u64 v[0:1], v[0:1], 0, v[152:153]
	v_and_b32_e32 v152, 8, v4
	v_lshl_add_u64 v[0:1], v[0:1], 0, v[152:153]
	v_mul_f32_e32 v38, v5, v32
	v_lshl_add_u64 v[4:5], v[0:1], 0, s[10:11]
	s_mov_b32 s10, 0x2b7c000
	v_add_co_u32_e32 v0, vcc, s10, v0
	v_mul_f32_e32 v16, v16, v32
	s_nop 0
	v_addc_co_u32_e32 v1, vcc, 0, v1, vcc
	v_mul_f32_e32 v17, v17, v32
	v_mul_f32_e32 v18, v18, v32
	v_mul_f32_e32 v35, v2, v32
	v_mul_f32_e32 v19, v19, v32
	v_mul_f32_e32 v36, v3, v32
	v_mul_f32_e32 v20, v20, v32
	v_mul_f32_e32 v21, v21, v32
	v_mul_f32_e32 v22, v22, v32
	v_mul_f32_e32 v23, v23, v32
	v_cvt_pk_bf16_f32 v2, v16, v17
	v_cvt_pk_bf16_f32 v3, v18, v19
	global_store_dwordx2 v[0:1], v[2:3], off offset:1792
	v_cvt_pk_bf16_f32 v0, v20, v21
	v_cvt_pk_bf16_f32 v1, v22, v23
	v_mul_f32_e32 v24, v24, v32
	v_mul_f32_e32 v25, v25, v32
	v_mul_f32_e32 v26, v26, v32
	v_mul_f32_e32 v27, v27, v32
	global_store_dwordx2 v[4:5], v[0:1], off offset:16
	v_cvt_pk_bf16_f32 v0, v24, v25
	v_cvt_pk_bf16_f32 v1, v26, v27
	v_mul_f32_e32 v28, v28, v32
	v_mul_f32_e32 v29, v29, v32
	v_mul_f32_e32 v30, v30, v32
	v_mul_f32_e32 v31, v31, v32
	global_store_dwordx2 v[4:5], v[0:1], off offset:32
	v_cvt_pk_bf16_f32 v0, v28, v29
	v_cvt_pk_bf16_f32 v1, v30, v31
	global_store_dwordx2 v[4:5], v[0:1], off offset:48
	v_cvt_pk_bf16_f32 v0, v33, v34
	v_cvt_pk_bf16_f32 v1, v35, v36
	v_mul_f32_e32 v6, v6, v32
	v_mul_f32_e32 v7, v7, v32
	global_store_dwordx2 v[4:5], v[0:1], off offset:64
	v_cvt_pk_bf16_f32 v0, v37, v38
	v_cvt_pk_bf16_f32 v1, v6, v7
	v_mul_f32_e32 v8, v8, v32
	v_mul_f32_e32 v9, v9, v32
	v_mul_f32_e32 v10, v10, v32
	v_mul_f32_e32 v11, v11, v32
	global_store_dwordx2 v[4:5], v[0:1], off offset:80
	v_cvt_pk_bf16_f32 v0, v8, v9
	v_cvt_pk_bf16_f32 v1, v10, v11
	v_mul_f32_e32 v12, v12, v32
	v_mul_f32_e32 v13, v13, v32
	v_mul_f32_e32 v14, v14, v32
	v_mul_f32_e32 v15, v15, v32
	global_store_dwordx2 v[4:5], v[0:1], off offset:96
	v_cvt_pk_bf16_f32 v0, v12, v13
	v_cvt_pk_bf16_f32 v1, v14, v15
	global_store_dwordx2 v[4:5], v[0:1], off offset:112

; DI void attn_pass_da(const bfr* __restrict__ P, int b, int tq_wave, int qcol, int kcol, int vcol, int key0, int nkt, char* smem, f32x16 (&o0)[2], f32x16 (&o1)[2]) {
;     ...
;   for (int kt = 0; kt < nkt; ++kt) {
;     bfr* sK = sbase + (kt & 1) * 9216;
;     bfr* sV = sK + 64 * 72;
;     { int c = gt, row = c >> 3, kc = c & 7; *(u32x4*)(sK + row * KP + kc * 8) = kreg[0]; }
;     for (int i = 0; i < 1; ++i) {
;       int c = gt, row = c >> 3, kc = c & 7;
;       unsigned wds[4] = {vreg[i].x, vreg[i].y, vreg[i].z, vreg[i].w};
; #pragma unroll
;       for (int e = 0; e < 4; ++e) {
;         sV[(kc * 8 + 2 * e) * 72 + (row ^ (kc << 3))] = (bfr)(wds[e] & 0xffffu);
;         sV[(kc * 8 + 2 * e + 1) * 72 + (row ^ (kc << 3))] = (bfr)(wds[e] >> 16);
;       }
;     }
;     __syncthreads();
;     if (kt + 1 < nkt) {
;       const bfr* Pn = Pb + (size_t)(kt + 1) * 64 * PW;
;       { int c = gt, row = c >> 3, kc = c & 7; kreg[0] = *(const u32x4*)(Pn + (size_t)row * PW + kcol + kc * 8); vreg[0] = *(const u32x4*)(Pn + (size_t)row * PW + vcol + kc * 8); }
;     }
;     f32x16 s0[2], s1[2];
; #pragma unroll
;     for (int t2 = 0; t2 < 2; ++t2) {
; #pragma unroll
;       for (int i = 0; i < 16; ++i) { s0[t2][i] = 0.f; s1[t2][i] = 0.f; }
; #pragma unroll
;       for (int ks = 0; ks < 2; ++ks) {
;         bf16x8 a0 = *(const bf16x8*)(sK + (t2 * 32 + r) * KP + ks * 16 + h * 8);
;         bf16x8 a1 = *(const bf16x8*)(sK + (t2 * 32 + r) * KP + 32 + ks * 16 + h * 8);
;         s0[t2] = MFMA32(a0, qf[ks], s0[t2]);
;         s1[t2] = MFMA32(a1, qf[2 + ks], s1[t2]);
;       }
;     }
;     float mx0 = s0[0][0], mx1 = s1[0][0];
; #pragma unroll
;     for (int i = 0; i < 16; ++i) { mx0 = fmaxf(mx0, fmaxf(s0[0][i], s0[1][i])); mx1 = fmaxf(mx1, fmaxf(s1[0][i], s1[1][i])); }
;     mx0 = fmaxf(mx0, __shfl_xor(mx0, 32)); mx1 = fmaxf(mx1, __shfl_xor(mx1, 32));
;     const float mn0 = fmaxf(m0, mx0), mn1 = fmaxf(m1, mx1);
;     const float al0 = __builtin_amdgcn_exp2f(m0 - mn0), al1 = __builtin_amdgcn_exp2f(m1 - mn1);
;     m0 = mn0; m1 = mn1;
;     float ps0 = 0.f, ps1 = 0.f;
; #pragma unroll
;     for (int i = 0; i < 16; ++i) {
;       s0[0][i] = __builtin_amdgcn_exp2f(s0[0][i] - mn0); ps0 += s0[0][i];
;       s0[1][i] = __builtin_amdgcn_exp2f(s0[1][i] - mn0); ps0 += s0[1][i];
;       s1[0][i] = __builtin_amdgcn_exp2f(s1[0][i] - mn1); ps1 += s1[0][i];
.LBB0_408:
	s_bitcmp1_b32 s14, 0
	s_cselect_b32 s15, 0x4800, 0
	s_add_i32 s15, s15, 0
	v_add3_u32 v64, s15, v206, v152
	v_add_u32_e32 v194, s15, v205
	s_waitcnt vmcnt(1)
	ds_write_b128 v64, v[148:151]
	v_add3_u32 v64, s15, v207, v208
	v_add3_u32 v65, s15, v208, v207
	v_add_u32_e32 v100, v194, v204
	s_waitcnt vmcnt(0)
	ds_write_b16 v64, v144 offset:9216
	ds_write_b16_d16_hi v65, v144 offset:9360
	ds_write_b16 v64, v145 offset:9504
	ds_write_b16_d16_hi v65, v145 offset:9648
	ds_write_b16 v64, v146 offset:9792
	ds_write_b16_d16_hi v65, v146 offset:9936
	ds_write_b16 v64, v147 offset:10080
	ds_write_b16_d16_hi v65, v147 offset:10224
	s_waitcnt lgkmcnt(0)
	s_barrier
	global_load_dwordx4 v[148:151], v[158:159], off
	global_load_dwordx4 v[144:147], v[158:159], off offset:512
	ds_read_b128 v[64:67], v100 offset:64
	ds_read_b128 v[68:71], v100
	ds_read_b128 v[96:99], v100 offset:32
	ds_read_b128 v[100:103], v100 offset:96
	s_waitcnt lgkmcnt(2)
	v_mfma_f32_32x32x16_bf16 v[80:95], v[68:71], v[140:143], 0
	v_add_u32_e32 v195, s15, v211
	v_add_u32_e32 v192, v195, v204
	v_mov_b32_e32 v160, v209
	v_mov_b32_e32 v161, v210
	s_add_i32 s14, s14, 1
	v_lshl_add_u64 v[158:159], v[158:159], 0, s[16:17]
	s_cmp_lg_u32 s14, 3
	v_mfma_f32_32x32x16_bf16 v[64:79], v[64:67], v[136:139], 0
	s_waitcnt lgkmcnt(1)
	v_mfma_f32_32x32x16_bf16 v[80:95], v[96:99], v[132:135], v[80:95]
	s_waitcnt lgkmcnt(0)
	v_mfma_f32_32x32x16_bf16 v[64:79], v[100:103], v[128:131], v[64:79]
	ds_read_b128 v[96:99], v192 offset:64
	ds_read_b128 v[100:103], v192
	ds_read_b128 v[212:215], v192 offset:32
	ds_read_b128 v[216:219], v192 offset:96
	s_nop 5
	v_max3_f32 v209, v80, v81, v82
	v_max3_f32 v209, v209, v83, v84
	v_max3_f32 v193, v64, v65, v66
	s_waitcnt lgkmcnt(2)
	v_mfma_f32_32x32x16_bf16 v[112:127], v[100:103], v[140:143], 0
	v_mfma_f32_32x32x16_bf16 v[96:111], v[96:99], v[136:139], 0
	s_waitcnt lgkmcnt(1)
	v_mfma_f32_32x32x16_bf16 v[112:127], v[212:215], v[132:135], v[112:127]
	v_max3_f32 v193, v193, v67, v68
	v_max3_f32 v209, v209, v85, v86
	s_waitcnt lgkmcnt(0)
	v_mfma_f32_32x32x16_bf16 v[96:111], v[216:219], v[128:131], v[96:111]
	v_max3_f32 v193, v193, v69, v70
	v_max3_f32 v209, v209, v87, v88
	v_max3_f32 v193, v193, v71, v72
	v_max3_f32 v209, v209, v89, v90
	v_max3_f32 v193, v193, v73, v74
	v_max3_f32 v209, v209, v91, v92
	v_max3_f32 v193, v193, v75, v76
	v_max3_f32 v209, v209, v93, v94
	v_max3_f32 v193, v193, v77, v78
	v_max3_f32 v209, v209, v95, v112
	v_max3_f32 v209, v209, v113, v114
	v_max3_f32 v209, v209, v115, v116
	v_max3_f32 v209, v209, v117, v118
	v_max3_f32 v209, v209, v119, v120
	v_max3_f32 v209, v209, v121, v122
	v_max3_f32 v209, v209, v123, v124
	v_max3_f32 v209, v209, v125, v126
	v_max_f32_e32 v192, v209, v127
	v_max3_f32 v193, v193, v79, v96
	v_max3_f32 v193, v193, v97, v98
	v_max3_f32 v193, v193, v99, v100
	v_max3_f32 v193, v193, v101, v102
	v_max3_f32 v193, v193, v103, v104
	v_max3_f32 v193, v193, v105, v106
	v_max3_f32 v193, v193, v107, v108
	v_max3_f32 v193, v193, v109, v110
	v_max_f32_e32 v193, v193, v111
	v_mov_b32_e32 v210, v193
	v_mov_b32_e32 v209, v192
	s_nop 1
	v_permlane32_swap_b32_e32 v193, v210
	v_permlane32_swap_b32_e32 v192, v209
	s_waitcnt lgkmcnt(1)
	v_max3_f32 v210, v161, v193, v210
	s_waitcnt lgkmcnt(0)
	v_max3_f32 v209, v160, v192, v209
	v_sub_f32_e32 v64, v64, v210
	v_sub_f32_e32 v80, v80, v209
	v_exp_f32_e32 v193, v64
	v_sub_f32_e32 v64, v96, v210
	v_exp_f32_e32 v192, v80
	v_sub_f32_e32 v80, v112, v209
	v_exp_f32_e32 v213, v64
	v_sub_f32_e32 v64, v81, v209
	v_exp_f32_e32 v212, v80
	v_exp_f32_e32 v80, v64
	v_sub_f32_e32 v64, v113, v209
	v_exp_f32_e32 v96, v64
	v_sub_f32_e32 v64, v65, v210
	v_exp_f32_e32 v81, v64
	v_sub_f32_e32 v64, v97, v210
	v_exp_f32_e32 v97, v64
	v_sub_f32_e32 v64, v82, v209
	v_exp_f32_e32 v112, v64
	v_sub_f32_e32 v64, v114, v209
	v_exp_f32_e32 v214, v64
	v_sub_f32_e32 v64, v66, v210
	v_exp_f32_e32 v113, v64
	v_sub_f32_e32 v64, v98, v210
	v_exp_f32_e32 v215, v64
	v_sub_f32_e32 v64, v83, v209
	v_exp_f32_e32 v82, v64
	v_sub_f32_e32 v64, v115, v209
	v_exp_f32_e32 v98, v64
	v_sub_f32_e32 v64, v67, v210
	v_exp_f32_e32 v83, v64
	v_sub_f32_e32 v64, v99, v210
	v_exp_f32_e32 v99, v64
	v_sub_f32_e32 v64, v84, v209
	v_exp_f32_e32 v114, v64
	v_sub_f32_e32 v64, v116, v209
	v_exp_f32_e32 v216, v64
	v_sub_f32_e32 v64, v68, v210
	v_exp_f32_e32 v115, v64
	v_sub_f32_e32 v64, v100, v210
	v_exp_f32_e32 v217, v64
	v_sub_f32_e32 v64, v85, v209
	v_exp_f32_e32 v84, v64
	v_sub_f32_e32 v64, v117, v209
	v_exp_f32_e32 v100, v64
	v_sub_f32_e32 v64, v69, v210
	v_exp_f32_e32 v85, v64
	v_sub_f32_e32 v64, v101, v210
	v_exp_f32_e32 v101, v64
	v_sub_f32_e32 v64, v86, v209
	v_exp_f32_e32 v116, v64
	v_sub_f32_e32 v64, v118, v209
	v_exp_f32_e32 v218, v64
	v_sub_f32_e32 v64, v70, v210
	v_exp_f32_e32 v117, v64
	v_sub_f32_e32 v64, v102, v210
	v_exp_f32_e32 v219, v64
	v_sub_f32_e32 v64, v87, v209
	v_exp_f32_e32 v70, v64
	v_sub_f32_e32 v64, v119, v209
	v_exp_f32_e32 v86, v64
	v_sub_f32_e32 v64, v71, v210
	v_exp_f32_e32 v71, v64
	v_sub_f32_e32 v64, v103, v210
	v_exp_f32_e32 v87, v64
	v_sub_f32_e32 v64, v88, v209
	v_exp_f32_e32 v102, v64
	v_sub_f32_e32 v64, v120, v209
	v_exp_f32_e32 v118, v64
	v_sub_f32_e32 v64, v72, v210
	v_exp_f32_e32 v103, v64
	v_sub_f32_e32 v64, v104, v210
	v_exp_f32_e32 v119, v64
	v_sub_f32_e32 v64, v89, v209
	v_exp_f32_e32 v88, v64
	v_sub_f32_e32 v64, v121, v209
	v_exp_f32_e32 v104, v64
	v_sub_f32_e32 v64, v73, v210
	v_exp_f32_e32 v89, v64
	v_sub_f32_e32 v64, v105, v210
	v_exp_f32_e32 v105, v64
	v_sub_f32_e32 v64, v90, v209
	v_exp_f32_e32 v120, v64
	v_sub_f32_e32 v64, v122, v209
	v_exp_f32_e32 v220, v64
	v_sub_f32_e32 v64, v74, v210
	v_exp_f32_e32 v121, v64
; #define MFMA32(a, b, c) __builtin_amdgcn_mfma_f32_32x32x16_bf16((a), (b), (c), 0, 0, 0)
; DI unsigned pack2(float a, float b) { unsigned r; asm volatile("v_cvt_pk_bf16_f32 %0, %1, %2" : "=v"(r) : "v"(a), "v"(b)); return r; }
; DI void attn_pass_da(const bfr* __restrict__ P, int b, int tq_wave, int qcol, int kcol, int vcol, int key0, int nkt, char* smem, f32x16 (&o0)[2], f32x16 (&o1)[2]) {
;     ...
;     const float mn0 = fmaxf(m0, mx0), mn1 = fmaxf(m1, mx1);
;     const float al0 = __builtin_amdgcn_exp2f(m0 - mn0), al1 = __builtin_amdgcn_exp2f(m1 - mn1);
;     m0 = mn0; m1 = mn1;
;     float ps0 = 0.f, ps1 = 0.f;
; #pragma unroll
;     for (int i = 0; i < 16; ++i) {
;       s0[0][i] = __builtin_amdgcn_exp2f(s0[0][i] - mn0); ps0 += s0[0][i];
;       s0[1][i] = __builtin_amdgcn_exp2f(s0[1][i] - mn0); ps0 += s0[1][i];
;       s1[0][i] = __builtin_amdgcn_exp2f(s1[0][i] - mn1); ps1 += s1[0][i];
;       s1[1][i] = __builtin_amdgcn_exp2f(s1[1][i] - mn1); ps1 += s1[1][i];
;     }
;     l0 = l0 * al0 + ps0; l1 = l1 * al1 + ps1;
; #pragma unroll
;     for (int i = 0; i < 16; ++i) { acc0[0][i] *= al0; acc0[1][i] *= al0; acc1[0][i] *= al1; acc1[1][i] *= al1; }
; #pragma unroll
;     for (int t2 = 0; t2 < 2; ++t2)
; #pragma unroll
;       for (int j = 0; j < 2; ++j) {
;         u32x4 pk0, pk1;
;         pk0.x = pack2(s0[t2][8 * j + 0], s0[t2][8 * j + 1]); pk0.y = pack2(s0[t2][8 * j + 2], s0[t2][8 * j + 3]);
;         pk0.z = pack2(s0[t2][8 * j + 4], s0[t2][8 * j + 5]); pk0.w = pack2(s0[t2][8 * j + 6], s0[t2][8 * j + 7]);
;         pk1.x = pack2(s1[t2][8 * j + 0], s1[t2][8 * j + 1]); pk1.y = pack2(s1[t2][8 * j + 2], s1[t2][8 * j + 3]);
;         pk1.z = pack2(s1[t2][8 * j + 4], s1[t2][8 * j + 5]); pk1.w = pack2(s1[t2][8 * j + 6], s1[t2][8 * j + 7]);
;         const bf16x8 pf0 = __builtin_bit_cast(bf16x8, pk0), pf1 = __builtin_bit_cast(bf16x8, pk1);
; #pragma unroll
;         for (int dt = 0; dt < 2; ++dt) {
;           const int vsw = (((dt * 32 + r) >> 3) & 7) << 3;
;           const bfr* vrow = sV + (dt * 32 + r) * 72;
;           s16x4 lo = *(const s16x4*)(vrow + ((t2 * 32 + 16 * j + 4 * h) ^ vsw));
;           s16x4 hi = *(const s16x4*)(vrow + ((t2 * 32 + 16 * j + 4 * h + 8) ^ vsw));
;           bf16x8 vf = __builtin_shufflevector(lo, hi, 0, 1, 2, 3, 4, 5, 6, 7);
;           acc0[dt] = MFMA32(vf, pf0, acc0[dt]);
;           acc1[dt] = MFMA32(vf, pf1, acc1[dt]);
;         }
	v_sub_f32_e32 v64, v106, v210
	v_exp_f32_e32 v221, v64
	v_sub_f32_e32 v64, v91, v209
	v_exp_f32_e32 v90, v64
	v_sub_f32_e32 v64, v123, v209
	v_exp_f32_e32 v106, v64
	v_sub_f32_e32 v64, v75, v210
	v_exp_f32_e32 v91, v64
	v_sub_f32_e32 v64, v107, v210
	v_exp_f32_e32 v107, v64
	v_sub_f32_e32 v64, v92, v209
	v_exp_f32_e32 v122, v64
	v_sub_f32_e32 v64, v124, v209
	v_exp_f32_e32 v222, v64
	v_sub_f32_e32 v64, v76, v210
	v_exp_f32_e32 v123, v64
	v_sub_f32_e32 v64, v108, v210
	v_exp_f32_e32 v223, v64
	v_sub_f32_e32 v64, v93, v209
	v_exp_f32_e32 v92, v64
	v_sub_f32_e32 v64, v125, v209
	v_exp_f32_e32 v108, v64
	v_sub_f32_e32 v64, v77, v210
	v_exp_f32_e32 v93, v64
	v_sub_f32_e32 v64, v109, v210
	v_exp_f32_e32 v109, v64
	v_sub_f32_e32 v64, v94, v209
	v_exp_f32_e32 v124, v64
	v_sub_f32_e32 v64, v126, v209
	v_exp_f32_e32 v224, v64
	v_sub_f32_e32 v64, v78, v210
	v_exp_f32_e32 v125, v64
	v_sub_f32_e32 v64, v110, v210
	v_exp_f32_e32 v225, v64
	v_sub_f32_e32 v64, v95, v209
	v_exp_f32_e32 v94, v64
	v_sub_f32_e32 v64, v127, v209
	v_exp_f32_e32 v110, v64
	v_sub_f32_e32 v64, v79, v210
	v_exp_f32_e32 v95, v64
	v_sub_f32_e32 v64, v111, v210
	v_exp_f32_e32 v111, v64
	v_pk_add_f32 v[64:65], v[192:193], 0 op_sel_hi:[1,0]
	v_sub_f32_e32 v161, v161, v210
	v_pk_add_f32 v[64:65], v[212:213], v[64:65]
	v_exp_f32_e32 v161, v161
	v_pk_add_f32 v[64:65], v[80:81], v[64:65]
	v_lshl_add_u32 v74, v180, 1, v194
	v_pk_add_f32 v[64:65], v[96:97], v[64:65]
	v_lshl_add_u32 v76, v179, 1, v195
	v_pk_add_f32 v[64:65], v[112:113], v[64:65]
	v_lshl_add_u32 v78, v178, 1, v195
	v_pk_add_f32 v[64:65], v[214:215], v[64:65]
	v_sub_f32_e32 v160, v160, v209
	v_pk_add_f32 v[64:65], v[82:83], v[64:65]
	v_exp_f32_e32 v160, v160
	v_pk_add_f32 v[64:65], v[98:99], v[64:65]
	v_pk_mul_f32 v[62:63], v[62:63], v[160:161] op_sel_hi:[1,0]
	v_pk_add_f32 v[64:65], v[114:115], v[64:65]
	v_pk_mul_f32 v[60:61], v[60:61], v[160:161] op_sel_hi:[1,0]
	v_pk_add_f32 v[64:65], v[216:217], v[64:65]
	v_pk_mul_f32 v[58:59], v[58:59], v[160:161] op_sel_hi:[1,0]
	v_pk_add_f32 v[64:65], v[84:85], v[64:65]
	v_pk_mul_f32 v[56:57], v[56:57], v[160:161] op_sel_hi:[1,0]
	v_pk_add_f32 v[64:65], v[100:101], v[64:65]
	v_pk_mul_f32 v[54:55], v[54:55], v[160:161] op_sel_hi:[1,0]
	v_pk_add_f32 v[64:65], v[116:117], v[64:65]
	v_pk_mul_f32 v[52:53], v[52:53], v[160:161] op_sel_hi:[1,0]
	v_pk_add_f32 v[64:65], v[218:219], v[64:65]
	v_pk_mul_f32 v[50:51], v[50:51], v[160:161] op_sel_hi:[1,0]
	v_pk_add_f32 v[64:65], v[70:71], v[64:65]
	v_pk_mul_f32 v[48:49], v[48:49], v[160:161] op_sel_hi:[1,0]
	v_pk_add_f32 v[64:65], v[86:87], v[64:65]
	v_pk_mul_f32 v[30:31], v[30:31], v[160:161] op_sel_hi:[1,0]
	v_pk_add_f32 v[64:65], v[102:103], v[64:65]
	v_pk_mul_f32 v[28:29], v[28:29], v[160:161] op_sel_hi:[1,0]
	v_pk_add_f32 v[64:65], v[118:119], v[64:65]
	v_pk_mul_f32 v[26:27], v[26:27], v[160:161] op_sel_hi:[1,0]
	v_pk_add_f32 v[64:65], v[88:89], v[64:65]
	v_pk_mul_f32 v[24:25], v[24:25], v[160:161] op_sel_hi:[1,0]
	v_pk_add_f32 v[64:65], v[104:105], v[64:65]
	v_pk_mul_f32 v[22:23], v[22:23], v[160:161] op_sel_hi:[1,0]
	v_pk_add_f32 v[64:65], v[120:121], v[64:65]
	v_pk_mul_f32 v[20:21], v[20:21], v[160:161] op_sel_hi:[1,0]
	v_pk_add_f32 v[126:127], v[220:221], v[64:65]
	v_cvt_pk_bf16_f32 v64, v192, v80
	v_cvt_pk_bf16_f32 v65, v112, v82
	v_lshl_add_u32 v112, v181, 1, v194
	v_cvt_pk_bf16_f32 v66, v114, v84
	v_cvt_pk_bf16_f32 v67, v116, v70
	v_cvt_pk_bf16_f32 v68, v193, v81
	v_cvt_pk_bf16_f32 v69, v113, v83
	v_cvt_pk_bf16_f32 v70, v115, v85
	v_cvt_pk_bf16_f32 v71, v117, v71
	ds_read_b64 v[72:73], v112 offset:9216
	ds_read_b64 v[74:75], v74 offset:9216
	ds_read_b64 v[76:77], v76 offset:9216
	ds_read_b64 v[78:79], v78 offset:9216
	v_mov_b32_e32 v82, v161
	v_pk_mul_f32 v[46:47], v[46:47], v[82:83] op_sel_hi:[1,0]
	v_pk_mul_f32 v[44:45], v[44:45], v[82:83] op_sel_hi:[1,0]
	v_pk_mul_f32 v[42:43], v[42:43], v[82:83] op_sel_hi:[1,0]
	v_pk_mul_f32 v[40:41], v[40:41], v[82:83] op_sel_hi:[1,0]
	v_pk_mul_f32 v[38:39], v[38:39], v[82:83] op_sel_hi:[1,0]
	v_pk_mul_f32 v[36:37], v[36:37], v[82:83] op_sel_hi:[1,0]
	v_pk_mul_f32 v[34:35], v[34:35], v[82:83] op_sel_hi:[1,0]
	v_pk_mul_f32 v[32:33], v[32:33], v[82:83] op_sel_hi:[1,0]
	v_pk_mul_f32 v[14:15], v[14:15], v[82:83] op_sel_hi:[1,0]
	v_pk_mul_f32 v[12:13], v[12:13], v[82:83] op_sel_hi:[1,0]
	v_pk_mul_f32 v[10:11], v[10:11], v[82:83] op_sel_hi:[1,0]
	v_pk_mul_f32 v[8:9], v[8:9], v[82:83] op_sel_hi:[1,0]
	v_pk_mul_f32 v[6:7], v[6:7], v[82:83] op_sel_hi:[1,0]
	v_pk_mul_f32 v[4:5], v[4:5], v[82:83] op_sel_hi:[1,0]
	v_pk_mul_f32 v[2:3], v[2:3], v[82:83] op_sel_hi:[1,0]
	v_pk_mul_f32 v[0:1], v[0:1], v[82:83] op_sel_hi:[1,0]
	v_pk_add_f32 v[82:83], v[90:91], v[126:127]
	s_waitcnt lgkmcnt(2)
	v_mfma_f32_32x32x16_bf16 v[48:63], v[72:75], v[64:67], v[48:63]
	v_add_f32_e64 v82, v106, v82
	v_add_f32_e64 v83, v107, v83
	v_cvt_pk_bf16_f32 v80, v102, v88
	v_lshl_add_u32 v88, v177, 1, v194
	v_add_f32_e64 v82, v122, v82
	v_add_f32_e64 v83, v123, v83
	v_pk_mul_f32 v[18:19], v[18:19], v[160:161] op_sel_hi:[1,0]
	v_pk_add_f32 v[82:83], v[222:223], v[82:83]
	v_pk_mul_f32 v[16:17], v[16:17], v[160:161] op_sel_hi:[1,0]
	v_pk_add_f32 v[82:83], v[92:93], v[82:83]
	v_mfma_f32_32x32x16_bf16 v[32:47], v[72:75], v[68:71], v[32:47]
	v_add_f32_e64 v82, v108, v82
	v_add_f32_e64 v83, v109, v83
	v_cvt_pk_bf16_f32 v81, v120, v90
	v_lshl_add_u32 v102, v176, 1, v194
	v_add_f32_e64 v82, v124, v82
	v_add_f32_e64 v83, v125, v83
	v_lshl_add_u32 v113, v175, 1, v195
	v_pk_add_f32 v[82:83], v[224:225], v[82:83]
	v_lshl_add_u32 v114, v174, 1, v195
	v_pk_add_f32 v[82:83], v[94:95], v[82:83]
	s_waitcnt lgkmcnt(0)
; DI void attn_pass_da(const bfr* __restrict__ P, int b, int tq_wave, int qcol, int kcol, int vcol, int key0, int nkt, char* smem, f32x16 (&o0)[2], f32x16 (&o1)[2]) {
;     ...
;   for (int kt = 0; kt < nkt; ++kt) {
;     bfr* sK = sbase + (kt & 1) * 9216;
;     bfr* sV = sK + 64 * 72;
;     { int c = gt, row = c >> 3, kc = c & 7; *(u32x4*)(sK + row * KP + kc * 8) = kreg[0]; }
;     for (int i = 0; i < 1; ++i) {
;       int c = gt, row = c >> 3, kc = c & 7;
;       unsigned wds[4] = {vreg[i].x, vreg[i].y, vreg[i].z, vreg[i].w};
; #pragma unroll
;       for (int e = 0; e < 4; ++e) {
;         sV[(kc * 8 + 2 * e) * 72 + (row ^ (kc << 3))] = (bfr)(wds[e] & 0xffffu);
;         sV[(kc * 8 + 2 * e + 1) * 72 + (row ^ (kc << 3))] = (bfr)(wds[e] >> 16);
;       }
;     }
;     __syncthreads();
;     if (kt + 1 < nkt) {
;       const bfr* Pn = Pb + (size_t)(kt + 1) * 64 * PW;
;       { int c = gt, row = c >> 3, kc = c & 7; kreg[0] = *(const u32x4*)(Pn + (size_t)row * PW + kcol + kc * 8); vreg[0] = *(const u32x4*)(Pn + (size_t)row * PW + vcol + kc * 8); }
;     }
;     f32x16 s0[2], s1[2];
; #pragma unroll
;     for (int t2 = 0; t2 < 2; ++t2) {
; #pragma unroll
;     ...
;     for (int t2 = 0; t2 < 2; ++t2)
; #pragma unroll
;       for (int j = 0; j < 2; ++j) {
;         u32x4 pk0, pk1;
;         pk0.x = pack2(s0[t2][8 * j + 0], s0[t2][8 * j + 1]); pk0.y = pack2(s0[t2][8 * j + 2], s0[t2][8 * j + 3]);
;         pk0.z = pack2(s0[t2][8 * j + 4], s0[t2][8 * j + 5]); pk0.w = pack2(s0[t2][8 * j + 6], s0[t2][8 * j + 7]);
;         pk1.x = pack2(s1[t2][8 * j + 0], s1[t2][8 * j + 1]); pk1.y = pack2(s1[t2][8 * j + 2], s1[t2][8 * j + 3]);
;         pk1.z = pack2(s1[t2][8 * j + 4], s1[t2][8 * j + 5]); pk1.w = pack2(s1[t2][8 * j + 6], s1[t2][8 * j + 7]);
;         const bf16x8 pf0 = __builtin_bit_cast(bf16x8, pk0), pf1 = __builtin_bit_cast(bf16x8, pk1);
; #pragma unroll
;         for (int dt = 0; dt < 2; ++dt) {
;           const int vsw = (((dt * 32 + r) >> 3) & 7) << 3;
;           const bfr* vrow = sV + (dt * 32 + r) * 72;
;           s16x4 lo = *(const s16x4*)(vrow + ((t2 * 32 + 16 * j + 4 * h) ^ vsw));
;           s16x4 hi = *(const s16x4*)(vrow + ((t2 * 32 + 16 * j + 4 * h + 8) ^ vsw));
;           bf16x8 vf = __builtin_shufflevector(lo, hi, 0, 1, 2, 3, 4, 5, 6, 7);
;           acc0[dt] = MFMA32(vf, pf0, acc0[dt]);
;           acc1[dt] = MFMA32(vf, pf1, acc1[dt]);
;         }
	v_mfma_f32_32x32x16_bf16 v[16:31], v[76:79], v[64:67], v[16:31]
	v_add_f32_e64 v84, v110, v82
	v_add_f32_e64 v85, v111, v83
	v_cvt_pk_bf16_f32 v82, v122, v92
	v_cvt_pk_bf16_f32 v83, v124, v94
	v_cvt_pk_bf16_f32 v64, v103, v89
	v_cvt_pk_bf16_f32 v65, v121, v91
	v_cvt_pk_bf16_f32 v66, v123, v93
	v_cvt_pk_bf16_f32 v67, v125, v95
	v_mfma_f32_32x32x16_bf16 v[0:15], v[76:79], v[68:71], v[0:15]
	ds_read_b64 v[68:69], v88 offset:9216
	ds_read_b64 v[70:71], v102 offset:9216
	v_lshl_add_u32 v115, v173, 1, v194
	v_lshl_add_u32 v116, v172, 1, v195
	v_lshl_add_u32 v117, v171, 1, v195
	v_lshl_add_u32 v120, v169, 1, v194
	v_lshl_add_u32 v192, v170, 1, v194
	v_lshl_add_u32 v193, v168, 1, v195
	s_waitcnt lgkmcnt(0)
	v_mfma_f32_32x32x16_bf16 v[48:63], v[68:71], v[80:83], v[48:63]
	v_lshl_add_u32 v194, v167, 1, v195
	v_fma_f32 v156, v156, v160, v84
	v_fma_f32 v157, v157, v161, v85
	v_mfma_f32_32x32x16_bf16 v[32:47], v[68:71], v[64:67], v[32:47]
	ds_read_b64 v[68:69], v113 offset:9216
	ds_read_b64 v[70:71], v114 offset:9216
	s_waitcnt lgkmcnt(0)
	v_mfma_f32_32x32x16_bf16 v[16:31], v[68:71], v[80:83], v[16:31]
	v_mfma_f32_32x32x16_bf16 v[0:15], v[68:71], v[64:67], v[0:15]
	v_cvt_pk_bf16_f32 v64, v212, v96
	v_cvt_pk_bf16_f32 v65, v214, v98
	v_cvt_pk_bf16_f32 v66, v216, v100
	v_cvt_pk_bf16_f32 v67, v218, v86
	v_cvt_pk_bf16_f32 v68, v213, v97
	v_cvt_pk_bf16_f32 v69, v215, v99
	v_cvt_pk_bf16_f32 v70, v217, v101
	v_cvt_pk_bf16_f32 v71, v219, v87
	ds_read_b64 v[72:73], v112 offset:9280
	ds_read_b64 v[74:75], v115 offset:9216
	s_waitcnt lgkmcnt(0)
	v_mfma_f32_32x32x16_bf16 v[48:63], v[72:75], v[64:67], v[48:63]
	v_mfma_f32_32x32x16_bf16 v[32:47], v[72:75], v[68:71], v[32:47]
	ds_read_b64 v[72:73], v116 offset:9216
	ds_read_b64 v[74:75], v117 offset:9216
	s_waitcnt lgkmcnt(0)
	v_mfma_f32_32x32x16_bf16 v[16:31], v[72:75], v[64:67], v[16:31]
	v_cvt_pk_bf16_f32 v64, v118, v104
	v_cvt_pk_bf16_f32 v65, v220, v106
	v_cvt_pk_bf16_f32 v66, v222, v108
	v_cvt_pk_bf16_f32 v67, v224, v110
	v_mfma_f32_32x32x16_bf16 v[0:15], v[72:75], v[68:71], v[0:15]
	v_cvt_pk_bf16_f32 v68, v119, v105
	v_cvt_pk_bf16_f32 v69, v221, v107
	v_cvt_pk_bf16_f32 v70, v223, v109
	v_cvt_pk_bf16_f32 v71, v225, v111
	ds_read_b64 v[72:73], v120 offset:9216
	ds_read_b64 v[74:75], v192 offset:9216
	s_waitcnt lgkmcnt(0)
	v_mfma_f32_32x32x16_bf16 v[48:63], v[72:75], v[64:67], v[48:63]
	v_mfma_f32_32x32x16_bf16 v[32:47], v[72:75], v[68:71], v[32:47]
	ds_read_b64 v[72:73], v193 offset:9216
	ds_read_b64 v[74:75], v194 offset:9216
	s_waitcnt lgkmcnt(0)
	v_mfma_f32_32x32x16_bf16 v[16:31], v[72:75], v[64:67], v[16:31]
	v_mfma_f32_32x32x16_bf16 v[0:15], v[72:75], v[68:71], v[0:15]
	s_cbranch_scc1 .LBB0_408
	v_add3_u32 v64, 0, v206, v152
	s_waitcnt vmcnt(1)
	ds_write_b128 v64, v[148:151] offset:18432
	v_add3_u32 v64, 0, v207, v208
	v_add3_u32 v65, 0, v208, v207
	s_waitcnt vmcnt(0)
	ds_write_b16 v64, v144 offset:27648
	ds_write_b16_d16_hi v65, v144 offset:27792
	ds_write_b16 v64, v145 offset:27936
	ds_write_b16_d16_hi v65, v145 offset:28080
	ds_write_b16 v64, v146 offset:28224
	ds_write_b16_d16_hi v65, v146 offset:28368
	ds_write_b16 v64, v147 offset:28512
	ds_write_b16_d16_hi v65, v147 offset:28656
	v_add_u32_e32 v144, 0, v205
	v_add_u32_e32 v102, v144, v204
	s_waitcnt lgkmcnt(0)
	s_barrier
	ds_read_b128 v[64:67], v102 offset:18432
	ds_read_b128 v[96:99], v102 offset:18464
	s_waitcnt lgkmcnt(1)
	v_mfma_f32_32x32x16_bf16 v[64:79], v[64:67], v[140:143], 0
	ds_read_b128 v[80:83], v102 offset:18496
	v_readlane_b32 s14, v203, 16
	v_readlane_b32 s15, v203, 48
	v_add_u32_e32 v145, 0x1200, v144
	v_mov_b32_e32 v100, s14
	v_mov_b32_e32 v101, s15
	v_pk_add_f32 v[100:101], s[12:13], v[100:101]
	s_mov_b32 s14, 0x3fb8aa3b
	v_add_f32_e32 v146, v100, v101
	v_mul_f32_e32 v104, 0x3fb8aa3b, v146
	v_fma_f32 v105, v146, s14, -v104
	v_rndne_f32_e32 v106, v104
	s_waitcnt lgkmcnt(1)
	v_mfma_f32_32x32x16_bf16 v[64:79], v[96:99], v[132:135], v[64:79]
	v_fmac_f32_e32 v105, 0x32a5705f, v146
	v_sub_f32_e32 v96, v104, v106
	v_add_u32_e32 v147, v145, v204
	v_add_f32_e32 v104, v96, v105
	ds_read_b128 v[96:99], v147 offset:18432
	ds_read_b128 v[100:103], v102 offset:18528
	ds_read_b128 v[112:115], v147 offset:18496
	s_waitcnt lgkmcnt(3)
	v_mfma_f32_32x32x16_bf16 v[80:95], v[80:83], v[136:139], 0
	v_readlane_b32 s12, v202, 16
	v_readlane_b32 s13, v202, 48
	s_mov_b32 s15, 0xc2ce8ed0
	v_mov_b32_e32 v116, s12
	v_mov_b32_e32 v117, s13
	v_pk_add_f32 v[116:117], s[10:11], v[116:117]
	v_cmp_ngt_f32_e32 vcc, s15, v146
	s_waitcnt lgkmcnt(1)
	v_mfma_f32_32x32x16_bf16 v[80:95], v[100:103], v[128:131], v[80:95]
	v_exp_f32_e32 v100, v104
	v_cvt_i32_f32_e32 v101, v106
	v_add_f32_e32 v149, v116, v117
	v_mul_f32_e32 v150, 0x3fb8aa3b, v149
	v_rndne_f32_e32 v151, v150
	v_ldexp_f32 v148, v100, v101
	s_mov_b32 s10, 0x42b17218
	s_waitcnt lgkmcnt(0)
	v_mfma_f32_32x32x16_bf16 v[112:127], v[112:115], v[136:139], 0
	v_fma_f32 v136, v149, s14, -v150
	v_fmac_f32_e32 v136, 0x32a5705f, v149
	v_sub_f32_e32 v137, v150, v151
	v_add_f32_e32 v136, v137, v136
	v_exp_f32_e32 v150, v136
	ds_read_b128 v[136:139], v147 offset:18528
	v_readlane_b32 s12, v253, 28
	v_mfma_f32_32x32x16_bf16 v[96:111], v[96:99], v[140:143], 0
	ds_read_b128 v[140:143], v147 offset:18464
	v_readlane_b32 s13, v253, 29
	s_waitcnt lgkmcnt(0)
; DI void attn_pass_da(const bfr* __restrict__ P, int b, int tq_wave, int qcol, int kcol, int vcol, int key0, int nkt, char* smem, f32x16 (&o0)[2], f32x16 (&o1)[2]) {
;     ...
;     float mx0 = s0[0][0], mx1 = s1[0][0];
; #pragma unroll
;     for (int i = 0; i < 16; ++i) { mx0 = fmaxf(mx0, fmaxf(s0[0][i], s0[1][i])); mx1 = fmaxf(mx1, fmaxf(s1[0][i], s1[1][i])); }
;     mx0 = fmaxf(mx0, __shfl_xor(mx0, 32)); mx1 = fmaxf(mx1, __shfl_xor(mx1, 32));
;     const float mn0 = fmaxf(m0, mx0), mn1 = fmaxf(m1, mx1);
;     const float al0 = __builtin_amdgcn_exp2f(m0 - mn0), al1 = __builtin_amdgcn_exp2f(m1 - mn1);
;     m0 = mn0; m1 = mn1;
;     float ps0 = 0.f, ps1 = 0.f;
; #pragma unroll
;     for (int i = 0; i < 16; ++i) {
;       s0[0][i] = __builtin_amdgcn_exp2f(s0[0][i] - mn0); ps0 += s0[0][i];
;       s0[1][i] = __builtin_amdgcn_exp2f(s0[1][i] - mn0); ps0 += s0[1][i];
;       s1[0][i] = __builtin_amdgcn_exp2f(s1[0][i] - mn1); ps1 += s1[0][i];
;       s1[1][i] = __builtin_amdgcn_exp2f(s1[1][i] - mn1); ps1 += s1[1][i];
;     }
; DN void da_item(const Params& p, int l, int b, int hd, int tq0, int key0, int nkt, char* smem) {
;     ...
;   float lam_init = 0.8f - 0.6f * expf(-0.3f * (float)l);
;   float lam = expf(d01) - expf(d23) + lam_init;
	v_mfma_f32_32x32x16_bf16 v[96:111], v[140:143], v[132:135], v[96:111]
	v_max_f32_e32 v134, v82, v82
	v_max_f32_e32 v135, v67, v67
	v_cvt_i32_f32_e32 v132, v151
	v_cndmask_b32_e32 v133, 0, v148, vcc
	v_cmp_nlt_f32_e32 vcc, s10, v146
	v_ldexp_f32 v132, v150, v132
	v_mfma_f32_32x32x16_bf16 v[112:127], v[136:139], v[128:131], v[112:127]
	s_nop 4
	v_max_f32_e32 v128, v97, v97
	v_max_f32_e32 v129, v65, v65
	v_max_f32_e32 v128, v129, v128
	v_max_f32_e32 v130, v81, v81
	v_max_f32_e32 v131, v66, v66
	v_max3_f32 v128, v64, v96, v128
	v_cndmask_b32_e32 v133, v201, v133, vcc
	v_max_f32_e32 v129, v113, v113
	v_max_f32_e32 v129, v130, v129
	v_max_f32_e32 v130, v98, v98
	v_max_f32_e32 v130, v131, v130
	v_max_f32_e32 v131, v114, v114
	v_max_f32_e32 v131, v134, v131
	v_max_f32_e32 v134, v99, v99
	v_max_f32_e32 v134, v135, v134
	v_max3_f32 v128, v128, v130, v134
	v_max_f32_e32 v130, v115, v115
	v_max_f32_e32 v134, v83, v83
	v_max3_f32 v129, v80, v112, v129
	v_max_f32_e32 v130, v134, v130
	v_max3_f32 v129, v129, v131, v130
	v_max_f32_e32 v130, v100, v100
	v_max_f32_e32 v131, v68, v68
	v_max_f32_e32 v130, v131, v130
	v_max_f32_e32 v131, v116, v116
	v_max_f32_e32 v134, v84, v84
	v_max_f32_e32 v131, v134, v131
	v_max_f32_e32 v134, v101, v101
	v_max_f32_e32 v135, v69, v69
	v_max_f32_e32 v134, v135, v134
	v_max3_f32 v128, v128, v130, v134
	v_max_f32_e32 v130, v117, v117
	v_max_f32_e32 v134, v85, v85
	v_max_f32_e32 v130, v134, v130
	v_max3_f32 v129, v129, v131, v130
	v_max_f32_e32 v130, v102, v102
	v_max_f32_e32 v131, v70, v70
	v_max_f32_e32 v130, v131, v130
	v_max_f32_e32 v131, v118, v118
	v_max_f32_e32 v134, v86, v86
	v_max_f32_e32 v131, v134, v131
	v_max_f32_e32 v134, v103, v103
	v_max_f32_e32 v135, v71, v71
	v_max_f32_e32 v134, v135, v134
	v_max3_f32 v128, v128, v130, v134
	v_max_f32_e32 v130, v119, v119
	v_max_f32_e32 v134, v87, v87
	v_max_f32_e32 v130, v134, v130
	v_max3_f32 v129, v129, v131, v130
	v_max_f32_e32 v130, v104, v104
	v_max_f32_e32 v131, v72, v72
	v_max_f32_e32 v130, v131, v130
	v_max_f32_e32 v131, v120, v120
	v_max_f32_e32 v134, v88, v88
	v_max_f32_e32 v131, v134, v131
	v_max_f32_e32 v134, v105, v105
	v_max_f32_e32 v135, v73, v73
	v_max_f32_e32 v134, v135, v134
	v_max3_f32 v128, v128, v130, v134
	v_max_f32_e32 v130, v121, v121
	v_max_f32_e32 v134, v89, v89
	v_max_f32_e32 v130, v134, v130
	v_max3_f32 v129, v129, v131, v130
	v_max_f32_e32 v130, v106, v106
	v_max_f32_e32 v131, v74, v74
	v_max_f32_e32 v130, v131, v130
	v_max_f32_e32 v131, v122, v122
	v_max_f32_e32 v134, v90, v90
	v_max_f32_e32 v131, v134, v131
	v_max_f32_e32 v134, v107, v107
	v_max_f32_e32 v135, v75, v75
	v_max_f32_e32 v134, v135, v134
	v_max3_f32 v128, v128, v130, v134
	v_max_f32_e32 v130, v123, v123
	v_max_f32_e32 v134, v91, v91
	v_max_f32_e32 v130, v134, v130
	v_max3_f32 v129, v129, v131, v130
	v_max_f32_e32 v130, v108, v108
	v_max_f32_e32 v131, v76, v76
	v_max_f32_e32 v130, v131, v130
	v_max_f32_e32 v131, v124, v124
	v_max_f32_e32 v134, v92, v92
	v_max_f32_e32 v131, v134, v131
	v_max_f32_e32 v134, v109, v109
	v_max_f32_e32 v135, v77, v77
	v_max_f32_e32 v134, v135, v134
	v_max3_f32 v128, v128, v130, v134
	v_max_f32_e32 v130, v125, v125
	v_max_f32_e32 v134, v93, v93
	v_max_f32_e32 v130, v134, v130
	v_max3_f32 v129, v129, v131, v130
	v_max_f32_e32 v130, v110, v110
	v_max_f32_e32 v131, v78, v78
	v_max_f32_e32 v130, v131, v130
	v_max_f32_e32 v131, v126, v126
	v_max_f32_e32 v134, v94, v94
	v_max_f32_e32 v131, v134, v131
	v_max_f32_e32 v134, v111, v111
	v_max_f32_e32 v135, v79, v79
	v_max_f32_e32 v134, v135, v134
	v_max3_f32 v128, v128, v130, v134
	v_max_f32_e32 v130, v127, v127
	v_max_f32_e32 v134, v95, v95
	v_max_f32_e32 v130, v134, v130
	v_max3_f32 v130, v129, v131, v130
	ds_bpermute_b32 v131, v166, v128
	ds_bpermute_b32 v134, v166, v130
	v_cmp_ngt_f32_e32 vcc, s15, v149
	s_waitcnt lgkmcnt(0)
	v_max3_f32 v150, v210, v130, v134
	v_cndmask_b32_e32 v132, 0, v132, vcc
	v_cmp_nlt_f32_e32 vcc, s10, v149
	v_max3_f32 v149, v209, v128, v131
	v_sub_f32_e32 v64, v64, v149
	v_exp_f32_e32 v148, v64
	v_sub_f32_e32 v64, v96, v149
	v_exp_f32_e32 v131, v64
	v_sub_f32_e32 v64, v80, v150
	v_exp_f32_e32 v151, v64
	v_sub_f32_e32 v64, v112, v150
	v_exp_f32_e32 v96, v64
	v_sub_f32_e32 v64, v65, v149
	v_exp_f32_e32 v152, v64
	v_sub_f32_e32 v64, v97, v149
	v_exp_f32_e32 v112, v64
	v_sub_f32_e32 v64, v81, v150
	v_exp_f32_e32 v158, v64
	v_sub_f32_e32 v64, v113, v150
	v_exp_f32_e32 v97, v64
	v_sub_f32_e32 v64, v66, v149
	v_exp_f32_e32 v143, v64
	v_sub_f32_e32 v64, v98, v149
	v_exp_f32_e32 v113, v64
	v_sub_f32_e32 v64, v82, v150
	v_exp_f32_e32 v146, v64
	v_sub_f32_e32 v64, v114, v150
	v_exp_f32_e32 v98, v64
	v_sub_f32_e32 v64, v67, v149
	v_exp_f32_e32 v147, v64
	v_sub_f32_e32 v64, v99, v149
	v_exp_f32_e32 v114, v64
	v_sub_f32_e32 v64, v83, v150
	v_exp_f32_e32 v138, v64
	v_sub_f32_e32 v64, v115, v150
	v_exp_f32_e32 v99, v64
	v_sub_f32_e32 v64, v68, v149
	v_exp_f32_e32 v139, v64
	v_sub_f32_e32 v64, v100, v149
	v_exp_f32_e32 v115, v64
	v_sub_f32_e32 v64, v84, v150
	v_exp_f32_e32 v140, v64
	v_sub_f32_e32 v64, v116, v150
	v_exp_f32_e32 v100, v64
	v_sub_f32_e32 v64, v69, v149
	v_exp_f32_e32 v141, v64
	v_sub_f32_e32 v64, v101, v149
	v_exp_f32_e32 v116, v64
	v_sub_f32_e32 v64, v85, v150
	v_exp_f32_e32 v142, v64
	v_sub_f32_e32 v64, v117, v150
	v_exp_f32_e32 v101, v64
	v_sub_f32_e32 v64, v70, v149
	v_exp_f32_e32 v134, v64
	v_sub_f32_e32 v64, v102, v149
	v_cndmask_b32_e32 v129, v201, v132, vcc
	v_exp_f32_e32 v132, v64
	v_sub_f32_e32 v64, v86, v150
	v_exp_f32_e32 v135, v64
	v_sub_f32_e32 v64, v118, v150
	v_exp_f32_e32 v117, v64
	v_sub_f32_e32 v64, v71, v149
	v_exp_f32_e32 v136, v64
	v_sub_f32_e32 v64, v103, v149
; #define MFMA32(a, b, c) __builtin_amdgcn_mfma_f32_32x32x16_bf16((a), (b), (c), 0, 0, 0)
; DI unsigned pack2(float a, float b) { unsigned r; asm volatile("v_cvt_pk_bf16_f32 %0, %1, %2" : "=v"(r) : "v"(a), "v"(b)); return r; }
; DI void attn_pass_da(const bfr* __restrict__ P, int b, int tq_wave, int qcol, int kcol, int vcol, int key0, int nkt, char* smem, f32x16 (&o0)[2], f32x16 (&o1)[2]) {
;     ...
;     const float mn0 = fmaxf(m0, mx0), mn1 = fmaxf(m1, mx1);
;     const float al0 = __builtin_amdgcn_exp2f(m0 - mn0), al1 = __builtin_amdgcn_exp2f(m1 - mn1);
;     m0 = mn0; m1 = mn1;
;     float ps0 = 0.f, ps1 = 0.f;
; #pragma unroll
;     for (int i = 0; i < 16; ++i) {
;       s0[0][i] = __builtin_amdgcn_exp2f(s0[0][i] - mn0); ps0 += s0[0][i];
;       s0[1][i] = __builtin_amdgcn_exp2f(s0[1][i] - mn0); ps0 += s0[1][i];
;       s1[0][i] = __builtin_amdgcn_exp2f(s1[0][i] - mn1); ps1 += s1[0][i];
;       s1[1][i] = __builtin_amdgcn_exp2f(s1[1][i] - mn1); ps1 += s1[1][i];
;     }
;     l0 = l0 * al0 + ps0; l1 = l1 * al1 + ps1;
; #pragma unroll
;     for (int i = 0; i < 16; ++i) { acc0[0][i] *= al0; acc0[1][i] *= al0; acc1[0][i] *= al1; acc1[1][i] *= al1; }
; #pragma unroll
;     for (int t2 = 0; t2 < 2; ++t2)
; #pragma unroll
;       for (int j = 0; j < 2; ++j) {
;         u32x4 pk0, pk1;
;         pk0.x = pack2(s0[t2][8 * j + 0], s0[t2][8 * j + 1]); pk0.y = pack2(s0[t2][8 * j + 2], s0[t2][8 * j + 3]);
;         pk0.z = pack2(s0[t2][8 * j + 4], s0[t2][8 * j + 5]); pk0.w = pack2(s0[t2][8 * j + 6], s0[t2][8 * j + 7]);
;         pk1.x = pack2(s1[t2][8 * j + 0], s1[t2][8 * j + 1]); pk1.y = pack2(s1[t2][8 * j + 2], s1[t2][8 * j + 3]);
;         pk1.z = pack2(s1[t2][8 * j + 4], s1[t2][8 * j + 5]); pk1.w = pack2(s1[t2][8 * j + 6], s1[t2][8 * j + 7]);
;         const bf16x8 pf0 = __builtin_bit_cast(bf16x8, pk0), pf1 = __builtin_bit_cast(bf16x8, pk1);
; #pragma unroll
;         for (int dt = 0; dt < 2; ++dt) {
;           const int vsw = (((dt * 32 + r) >> 3) & 7) << 3;
;           const bfr* vrow = sV + (dt * 32 + r) * 72;
;           s16x4 lo = *(const s16x4*)(vrow + ((t2 * 32 + 16 * j + 4 * h) ^ vsw));
;           s16x4 hi = *(const s16x4*)(vrow + ((t2 * 32 + 16 * j + 4 * h + 8) ^ vsw));
;           bf16x8 vf = __builtin_shufflevector(lo, hi, 0, 1, 2, 3, 4, 5, 6, 7);
;           acc0[dt] = MFMA32(vf, pf0, acc0[dt]);
;           acc1[dt] = MFMA32(vf, pf1, acc1[dt]);
;         }
	v_sub_f32_e32 v129, v133, v129
	v_exp_f32_e32 v133, v64
	v_sub_f32_e32 v64, v87, v150
	v_exp_f32_e32 v137, v64
	v_sub_f32_e32 v64, v119, v150
	v_exp_f32_e32 v102, v64
	v_sub_f32_e32 v64, v72, v149
	v_exp_f32_e32 v103, v64
	v_sub_f32_e32 v64, v104, v149
	v_exp_f32_e32 v71, v64
	v_sub_f32_e32 v64, v88, v150
	v_exp_f32_e32 v104, v64
	v_sub_f32_e32 v64, v120, v150
	v_exp_f32_e32 v70, v64
	v_sub_f32_e32 v64, v73, v149
	v_exp_f32_e32 v118, v64
	v_sub_f32_e32 v64, v105, v149
	v_exp_f32_e32 v73, v64
	v_sub_f32_e32 v64, v89, v150
	v_exp_f32_e32 v105, v64
	v_sub_f32_e32 v64, v121, v150
	v_exp_f32_e32 v72, v64
	v_sub_f32_e32 v64, v74, v149
	v_exp_f32_e32 v119, v64
	v_sub_f32_e32 v64, v106, v149
	v_exp_f32_e32 v81, v64
	v_sub_f32_e32 v64, v90, v150
	v_exp_f32_e32 v89, v64
	v_sub_f32_e32 v64, v122, v150
	v_exp_f32_e32 v80, v64
	v_sub_f32_e32 v64, v75, v149
	v_exp_f32_e32 v90, v64
	v_sub_f32_e32 v64, v107, v149
	v_exp_f32_e32 v87, v64
	v_sub_f32_e32 v64, v91, v150
	v_exp_f32_e32 v91, v64
	v_sub_f32_e32 v64, v123, v150
	v_exp_f32_e32 v86, v64
	v_sub_f32_e32 v64, v76, v149
	v_exp_f32_e32 v74, v64
	v_sub_f32_e32 v64, v108, v149
	v_exp_f32_e32 v75, v64
	v_sub_f32_e32 v64, v92, v150
	v_exp_f32_e32 v76, v64
	v_sub_f32_e32 v64, v124, v150
	v_exp_f32_e32 v82, v64
	v_sub_f32_e32 v64, v77, v149
	v_exp_f32_e32 v77, v64
	v_sub_f32_e32 v64, v109, v149
	v_exp_f32_e32 v83, v64
	v_sub_f32_e32 v64, v93, v150
	v_exp_f32_e32 v84, v64
	v_sub_f32_e32 v64, v125, v150
	v_exp_f32_e32 v85, v64
	v_sub_f32_e32 v64, v78, v149
	v_exp_f32_e32 v78, v64
	v_sub_f32_e32 v64, v110, v149
	v_exp_f32_e32 v88, v64
	v_sub_f32_e32 v64, v94, v150
	v_exp_f32_e32 v66, v64
	v_sub_f32_e32 v64, v126, v150
	v_exp_f32_e32 v67, v64
	v_sub_f32_e32 v64, v79, v149
	v_exp_f32_e32 v68, v64
	v_sub_f32_e32 v64, v111, v149
	v_lshl_add_u32 v79, v181, 1, v144
	v_lshl_add_u32 v110, v180, 1, v144
	v_lshl_add_u32 v124, v179, 1, v145
	v_lshl_add_u32 v126, v178, 1, v145
	v_exp_f32_e32 v69, v64
	v_sub_f32_e32 v64, v95, v150
	v_sub_f32_e32 v65, v127, v150
	v_cvt_pk_bf16_f32 v92, v148, v152
	v_cvt_pk_bf16_f32 v93, v143, v147
	v_cvt_pk_bf16_f32 v94, v139, v141
	v_cvt_pk_bf16_f32 v95, v134, v136
	v_cvt_pk_bf16_f32 v106, v151, v158
	v_cvt_pk_bf16_f32 v107, v146, v138
	v_cvt_pk_bf16_f32 v108, v140, v142
	v_cvt_pk_bf16_f32 v109, v135, v137
	ds_read_b64 v[120:121], v79 offset:27648
	ds_read_b64 v[122:123], v110 offset:27648
	ds_read_b64 v[124:125], v124 offset:27648
	ds_read_b64 v[126:127], v126 offset:27648
	v_sub_f32_e32 v128, v209, v149
	v_exp_f32_e32 v130, v128
	v_sub_f32_e32 v128, v210, v150
	v_add_f32_e32 v111, 0, v151
	v_exp_f32_e32 v128, v128
	v_add_f32_e32 v110, 0, v148
	v_add_f32_e32 v111, v96, v111
	v_add_f32_e32 v110, v131, v110
	v_add_f32_e32 v111, v158, v111
	v_add_f32_e32 v110, v152, v110
	v_add_f32_e32 v111, v97, v111
	v_add_f32_e32 v110, v112, v110
	v_add_f32_e32 v111, v146, v111
	v_pk_mul_f32 v[46:47], v[46:47], v[128:129] op_sel_hi:[1,0]
	v_pk_mul_f32 v[44:45], v[44:45], v[128:129] op_sel_hi:[1,0]
	v_pk_mul_f32 v[42:43], v[42:43], v[128:129] op_sel_hi:[1,0]
	v_pk_mul_f32 v[40:41], v[40:41], v[128:129] op_sel_hi:[1,0]
	v_pk_mul_f32 v[38:39], v[38:39], v[128:129] op_sel_hi:[1,0]
	v_pk_mul_f32 v[36:37], v[36:37], v[128:129] op_sel_hi:[1,0]
	v_pk_mul_f32 v[34:35], v[34:35], v[128:129] op_sel_hi:[1,0]
	v_pk_mul_f32 v[32:33], v[32:33], v[128:129] op_sel_hi:[1,0]
	v_pk_mul_f32 v[14:15], v[14:15], v[128:129] op_sel_hi:[1,0]
	v_pk_mul_f32 v[12:13], v[12:13], v[128:129] op_sel_hi:[1,0]
	v_pk_mul_f32 v[10:11], v[10:11], v[128:129] op_sel_hi:[1,0]
	v_pk_mul_f32 v[8:9], v[8:9], v[128:129] op_sel_hi:[1,0]
	v_pk_mul_f32 v[6:7], v[6:7], v[128:129] op_sel_hi:[1,0]
	v_pk_mul_f32 v[4:5], v[4:5], v[128:129] op_sel_hi:[1,0]
	v_pk_mul_f32 v[2:3], v[2:3], v[128:129] op_sel_hi:[1,0]
	v_pk_mul_f32 v[0:1], v[0:1], v[128:129] op_sel_hi:[1,0]
	v_add_f32_e32 v110, v143, v110
	v_add_f32_e32 v111, v98, v111
	s_waitcnt lgkmcnt(2)
	v_mfma_f32_32x32x16_bf16 v[32:47], v[120:123], v[106:109], v[32:47]
	v_add_f32_e32 v110, v113, v110
	v_add_f32_e32 v110, v147, v110
	v_add_f32_e32 v110, v114, v110
	v_mul_f32_e64 v62, v62, v130
	v_mul_f32_e64 v63, v63, v130
	v_pk_mul_f32 v[60:61], v[60:61], v[130:131] op_sel_hi:[1,0]
	v_pk_mul_f32 v[58:59], v[58:59], v[130:131] op_sel_hi:[1,0]
	v_pk_mul_f32 v[56:57], v[56:57], v[130:131] op_sel_hi:[1,0]
	s_waitcnt lgkmcnt(0)
	v_mfma_f32_32x32x16_bf16 v[0:15], v[124:127], v[106:109], v[0:15]
	v_add_f32_e32 v106, v138, v111
	v_add_f32_e32 v106, v99, v106
	v_add_f32_e32 v106, v140, v106
	v_add_f32_e32 v107, v139, v110
	v_add_f32_e32 v106, v100, v106
	v_add_f32_e32 v107, v115, v107
	v_add_f32_e32 v106, v142, v106
	v_pk_mul_f32 v[54:55], v[54:55], v[130:131] op_sel_hi:[1,0]
	v_pk_mul_f32 v[52:53], v[52:53], v[130:131] op_sel_hi:[1,0]
	v_pk_mul_f32 v[50:51], v[50:51], v[130:131] op_sel_hi:[1,0]
	v_pk_mul_f32 v[48:49], v[48:49], v[130:131] op_sel_hi:[1,0]
	v_pk_mul_f32 v[30:31], v[30:31], v[130:131] op_sel_hi:[1,0]
	v_pk_mul_f32 v[28:29], v[28:29], v[130:131] op_sel_hi:[1,0]
	v_pk_mul_f32 v[26:27], v[26:27], v[130:131] op_sel_hi:[1,0]
	v_pk_mul_f32 v[24:25], v[24:25], v[130:131] op_sel_hi:[1,0]
	v_pk_mul_f32 v[22:23], v[22:23], v[130:131] op_sel_hi:[1,0]
	v_pk_mul_f32 v[20:21], v[20:21], v[130:131] op_sel_hi:[1,0]
	v_pk_mul_f32 v[18:19], v[18:19], v[130:131] op_sel_hi:[1,0]
	v_pk_mul_f32 v[16:17], v[16:17], v[130:131] op_sel_hi:[1,0]
	v_lshl_add_u32 v143, v177, 1, v144
	v_add_f32_e32 v107, v141, v107
	v_add_f32_e32 v111, v101, v106
	v_lshl_add_u32 v106, v175, 1, v145
	v_lshl_add_u32 v108, v174, 1, v145
	v_exp_f32_e32 v64, v64
	v_mfma_f32_32x32x16_bf16 v[48:63], v[120:123], v[92:95], v[48:63]
	v_add_f32_e32 v110, v116, v107
	v_add_f32_e32 v110, v134, v110
	v_add_f32_e32 v110, v132, v110
	v_add_f32_e32 v110, v136, v110
	v_add_f32_e32 v111, v135, v111
	v_add_f32_e32 v111, v117, v111
	v_exp_f32_e32 v65, v65
	v_mfma_f32_32x32x16_bf16 v[16:31], v[124:127], v[92:95], v[16:31]
	v_cvt_pk_bf16_f32 v92, v103, v118
	v_cvt_pk_bf16_f32 v93, v119, v90
	v_cvt_pk_bf16_f32 v94, v74, v77
	v_cvt_pk_bf16_f32 v95, v78, v68
	v_cvt_pk_bf16_f32 v120, v104, v105
	v_cvt_pk_bf16_f32 v121, v89, v91
	v_cvt_pk_bf16_f32 v122, v76, v84
	v_cvt_pk_bf16_f32 v123, v66, v64
	ds_read_b64 v[146:147], v143 offset:27648
	ds_read_b64 v[106:107], v106 offset:27648
	ds_read_b64 v[108:109], v108 offset:27648
	v_lshl_add_u32 v143, v176, 1, v144
	ds_read_b64 v[148:149], v143 offset:27648
	v_add_f32_e32 v124, v133, v110
	s_waitcnt lgkmcnt(0)
; DI int oidx(int i) { asm volatile("" : "+s"(i)); return i; }
; DI void attn_pass_da(const bfr* __restrict__ P, int b, int tq_wave, int qcol, int kcol, int vcol, int key0, int nkt, char* smem, f32x16 (&o0)[2], f32x16 (&o1)[2]) {
;     ...
;   l0 += __shfl_xor(l0, 32); l1 += __shfl_xor(l1, 32);
;   const float i0 = 1.f / l0, i1 = 1.f / l1;
; #pragma unroll
;   for (int i = 0; i < 16; ++i) { o0[0][i] = acc0[0][i] * i0; o0[1][i] = acc0[1][i] * i0; o1[0][i] = acc1[0][i] * i1; o1[1][i] = acc1[1][i] * i1; }
; DN void da_item(const Params& p, int l, int b, int hd, int tq0, int key0, int nkt, char* smem) {
;     ...
;   float ss = 0.f;
; #pragma unroll
;   for (int dt = 0; dt < 2; ++dt)
; #pragma unroll
;     for (int i = 0; i < 16; ++i) { float v = o0[dt][i] - lam * o1[dt][i]; o0[dt][i] = v; ss += v * v; }
;   ss += __shfl_xor(ss, 32);
;   float rstd = rsqrtf(ss * (1.f / 64.f) + 1e-6f) * (1.f - lam_init);
;   const float* sg = p.in[oidx(23)] + l * 64;
	v_mfma_f32_32x32x16_bf16 v[48:63], v[146:149], v[92:95], v[48:63]
	v_add_f32_e32 v125, v137, v111
	v_lshlrev_b32_e32 v152, 1, v154
	v_mfma_f32_32x32x16_bf16 v[16:31], v[106:109], v[92:95], v[16:31]
	v_cvt_pk_bf16_f32 v92, v131, v112
	v_cvt_pk_bf16_f32 v93, v113, v114
	v_cvt_pk_bf16_f32 v94, v115, v116
	v_cvt_pk_bf16_f32 v95, v132, v133
	v_cvt_pk_bf16_f32 v96, v96, v97
	v_cvt_pk_bf16_f32 v97, v98, v99
	v_cvt_pk_bf16_f32 v98, v100, v101
	v_add_f32_e32 v100, v103, v124
	v_add_f32_e32 v100, v71, v100
	v_cvt_pk_bf16_f32 v99, v117, v102
	ds_read_b64 v[110:111], v79 offset:27712
	v_lshl_add_u32 v79, v173, 1, v144
	v_add_f32_e32 v100, v118, v100
	ds_read_b64 v[112:113], v79 offset:27648
	v_add_f32_e32 v79, v102, v125
	v_add_f32_e32 v100, v73, v100
	v_add_f32_e32 v79, v104, v79
	v_add_f32_e32 v104, v119, v100
	v_lshl_add_u32 v100, v172, 1, v145
	v_lshl_add_u32 v102, v171, 1, v145
	ds_read_b64 v[100:101], v100 offset:27648
	ds_read_b64 v[102:103], v102 offset:27648
	v_add_f32_e32 v79, v70, v79
	v_add_f32_e32 v79, v105, v79
	v_add_f32_e32 v79, v72, v79
	v_add_f32_e32 v104, v81, v104
	v_add_f32_e32 v79, v89, v79
	v_add_f32_e32 v79, v80, v79
	v_add_f32_e32 v89, v90, v104
	v_add_f32_e32 v89, v87, v89
	v_add_f32_e32 v79, v91, v79
	v_add_f32_e32 v79, v86, v79
	v_add_f32_e32 v74, v74, v89
	s_waitcnt lgkmcnt(2)
	v_mfma_f32_32x32x16_bf16 v[48:63], v[110:113], v[92:95], v[48:63]
	v_cvt_pk_bf16_f32 v90, v71, v73
	v_cvt_pk_bf16_f32 v91, v81, v87
	v_add_f32_e32 v74, v75, v74
	v_add_f32_e32 v74, v77, v74
	v_add_f32_e32 v74, v83, v74
	v_add_f32_e32 v74, v78, v74
	v_add_f32_e32 v78, v88, v74
	s_waitcnt lgkmcnt(0)
	v_mfma_f32_32x32x16_bf16 v[16:31], v[100:103], v[92:95], v[16:31]
	v_cvt_pk_bf16_f32 v92, v75, v83
	v_add_f32_e32 v75, v76, v79
	v_add_f32_e32 v75, v82, v75
	v_add_f32_e32 v75, v84, v75
	v_add_f32_e32 v79, v85, v75
	v_add_f32_e32 v66, v66, v79
	v_cvt_pk_bf16_f32 v93, v88, v69
	v_mfma_f32_32x32x16_bf16 v[32:47], v[146:149], v[120:123], v[32:47]
	v_cvt_pk_bf16_f32 v70, v70, v72
	v_cvt_pk_bf16_f32 v71, v80, v86
	v_cvt_pk_bf16_f32 v72, v82, v85
	v_cvt_pk_bf16_f32 v73, v67, v65
	v_add_f32_e32 v66, v67, v66
	v_add_f32_e32 v67, v68, v78
	v_add_f32_e32 v67, v69, v67
	v_mfma_f32_32x32x16_bf16 v[0:15], v[106:109], v[120:123], v[0:15]
	v_fmac_f32_e32 v67, v156, v130
	ds_bpermute_b32 v68, v166, v67
	v_lshl_add_u32 v80, v169, 1, v144
	v_lshl_add_u32 v74, v168, 1, v145
	v_lshl_add_u32 v76, v167, 1, v145
	ds_read_b64 v[104:105], v80 offset:27648
	ds_read_b64 v[74:75], v74 offset:27648
	ds_read_b64 v[76:77], v76 offset:27648
	v_lshl_add_u32 v80, v170, 1, v144
	v_add_f32_e32 v64, v64, v66
	ds_read_b64 v[106:107], v80 offset:27648
	v_add_f32_e32 v65, v65, v64
	v_mfma_f32_32x32x16_bf16 v[32:47], v[110:113], v[96:99], v[32:47]
	v_fmac_f32_e32 v65, v157, v128
	s_waitcnt lgkmcnt(4)
	v_add_f32_e32 v66, v67, v68
	ds_bpermute_b32 v67, v166, v65
	v_div_scale_f32 v68, s[10:11], v66, v66, 1.0
	v_rcp_f32_e32 v69, v68
	v_add_f32_e32 v64, v155, v129
	v_mfma_f32_32x32x16_bf16 v[0:15], v[100:103], v[96:99], v[0:15]
	s_waitcnt lgkmcnt(0)
	v_add_f32_e32 v65, v65, v67
	v_fma_f32 v67, -v68, v69, 1.0
	v_fmac_f32_e32 v69, v67, v69
	v_div_scale_f32 v67, vcc, 1.0, v66, 1.0
	v_mfma_f32_32x32x16_bf16 v[32:47], v[104:107], v[70:73], v[32:47]
	v_mfma_f32_32x32x16_bf16 v[0:15], v[74:77], v[70:73], v[0:15]
	v_mul_f32_e32 v70, v67, v69
	v_fma_f32 v71, -v68, v70, v67
	v_fmac_f32_e32 v70, v71, v69
	v_fma_f32 v67, -v68, v70, v67
	v_div_scale_f32 v68, s[10:11], v65, v65, 1.0
	v_rcp_f32_e32 v71, v68
	v_div_fmas_f32 v67, v67, v69, v70
	v_div_fixup_f32 v66, v67, v66, 1.0
	v_mfma_f32_32x32x16_bf16 v[48:63], v[104:107], v[90:93], v[48:63]
	v_fma_f32 v67, -v68, v71, 1.0
	v_fmac_f32_e32 v71, v67, v71
	v_div_scale_f32 v67, vcc, 1.0, v65, 1.0
	v_mul_f32_e32 v69, v67, v71
	v_fma_f32 v70, -v68, v69, v67
	v_fmac_f32_e32 v69, v70, v71
	v_fma_f32 v67, -v68, v69, v67
	v_div_fmas_f32 v67, v67, v71, v69
	v_div_fixup_f32 v68, v67, v65, 1.0
	v_mul_f32_e32 v65, v0, v68
	v_mul_f32_e32 v0, v33, v68
	v_mul_f32_e32 v67, v1, v68
	v_mul_f32_e32 v1, v34, v68
	v_mul_f32_e32 v0, v64, v0
	v_mul_f32_e32 v32, v32, v68
	v_mul_f32_e32 v69, v2, v68
	v_mul_f32_e32 v2, v35, v68
	v_mul_f32_e32 v33, v37, v68
	v_mul_f32_e32 v37, v41, v68
	v_mul_f32_e32 v41, v45, v68
	v_fma_f32 v45, v49, v66, -v0
	v_mul_f32_e32 v0, v64, v1
	v_mul_f32_e32 v70, v3, v68
	v_mul_f32_e32 v3, v36, v68
	v_mul_f32_e32 v35, v39, v68
	v_mul_f32_e32 v39, v43, v68
	v_mul_f32_e32 v43, v47, v68
	v_mul_f32_e32 v32, v64, v32
	v_fma_f32 v47, v50, v66, -v0
	v_mul_f32_e32 v0, v64, v2
	v_mul_f32_e32 v36, v40, v68
	v_mul_f32_e32 v40, v44, v68
	v_fma_f32 v44, v48, v66, -v32
	v_fma_f32 v48, v51, v66, -v0
	v_mul_f32_e32 v0, v64, v3
	v_mul_f32_e32 v34, v38, v68
	v_fma_f32 v49, v52, v66, -v0
	v_mul_f32_e32 v0, v64, v33
	s_mov_b32 s10, 23
	v_fma_f32 v50, v53, v66, -v0
	v_mul_f32_e32 v0, v64, v34
	s_ashr_i32 s11, s10, 31
	v_fma_f32 v51, v54, v66, -v0
	v_mul_f32_e32 v0, v64, v35
	s_lshl_b64 s[10:11], s[10:11], 3
	v_fma_f32 v52, v55, v66, -v0
	v_mul_f32_e32 v0, v64, v36
	s_add_u32 s10, s0, s10
	v_mul_f32_e32 v38, v42, v68
	v_fma_f32 v53, v56, v66, -v0
	v_mul_f32_e32 v0, v64, v37
	s_addc_u32 s11, s1, s11
	v_fma_f32 v54, v57, v66, -v0
	v_mul_f32_e32 v0, v64, v38
	s_load_dwordx2 s[10:11], s[10:11], 0x0
	v_mul_f32_e32 v42, v46, v68
	v_mul_f32_e32 v46, v45, v45
	v_fma_f32 v55, v58, v66, -v0
	v_mul_f32_e32 v0, v64, v39
	v_fmac_f32_e32 v46, v44, v44
	v_fma_f32 v56, v59, v66, -v0
	v_mul_f32_e32 v0, v64, v40
	v_fmac_f32_e32 v46, v47, v47
	v_fma_f32 v57, v60, v66, -v0
	v_mul_f32_e32 v0, v64, v41
	v_fmac_f32_e32 v46, v48, v48
	v_fma_f32 v58, v61, v66, -v0
	s_lshl_b64 s[12:13], s[12:13], 2
	v_lshrrev_b32_e32 v0, 3, v164
	v_fmac_f32_e32 v46, v49, v49
	s_waitcnt lgkmcnt(0)
; DI int oidx(int i) { asm volatile("" : "+s"(i)); return i; }
; DI unsigned pack2(float a, float b) { unsigned r; asm volatile("v_cvt_pk_bf16_f32 %0, %1, %2" : "=v"(r) : "v"(a), "v"(b)); return r; }
; DI void store_o(bfr* O, int m, int colbase, int h, const f32x16 (&o)[2]) {
; #pragma unroll
;   for (int dt = 0; dt < 2; ++dt)
; #pragma unroll
;     for (int g4 = 0; g4 < 4; ++g4) {
;       int dv = dt * 32 + 8 * g4 + 4 * h;
;       uint2 pk; pk.x = pack2(o[dt][4 * g4], o[dt][4 * g4 + 1]); pk.y = pack2(o[dt][4 * g4 + 2], o[dt][4 * g4 + 3]);
;       *(uint2*)(O + (size_t)m * DM + colbase + dv) = pk;
;     }
; }
; DN void da_item(const Params& p, int l, int b, int hd, int tq0, int key0, int nkt, char* smem) {
;     ...
;     for (int i = 0; i < 16; ++i) { float v = o0[dt][i] - lam * o1[dt][i]; o0[dt][i] = v; ss += v * v; }
;   ss += __shfl_xor(ss, 32);
;   float rstd = rsqrtf(ss * (1.f / 64.f) + 1e-6f) * (1.f - lam_init);
;   const float* sg = p.in[oidx(23)] + l * 64;
; #pragma unroll
;   for (int dt = 0; dt < 2; ++dt)
; #pragma unroll
;     for (int i = 0; i < 16; ++i) { int dv = dt * 32 + 8 * (i >> 2) + 4 * h + (i & 3); o0[dt][i] = o0[dt][i] * rstd * sg[dv]; }
;   store_o(O, b * TT + tqw + r, 256 + hd * 64, h, o0);
	s_add_u32 s10, s10, s12
	v_and_b32_e32 v59, 4, v0
	v_fmac_f32_e32 v46, v50, v50
	s_addc_u32 s11, s11, s13
	v_lshlrev_b32_e32 v60, 2, v59
	v_mfma_f32_32x32x16_bf16 v[16:31], v[74:77], v[90:93], v[16:31]
	v_fmac_f32_e32 v46, v51, v51
	global_load_dwordx4 v[0:3], v60, s[10:11]
	v_fmac_f32_e32 v46, v52, v52
	v_fmac_f32_e32 v46, v53, v53
	v_mul_f32_e32 v32, v64, v42
	v_fmac_f32_e32 v46, v54, v54
	v_fma_f32 v61, v62, v66, -v32
	v_mul_f32_e32 v32, v64, v43
	v_fmac_f32_e32 v46, v55, v55
	v_fma_f32 v62, v63, v66, -v32
	global_load_dwordx4 v[32:35], v60, s[10:11] offset:32
	v_fmac_f32_e32 v46, v56, v56
	v_fmac_f32_e32 v46, v57, v57
	v_fmac_f32_e32 v46, v58, v58
	v_mul_f32_e32 v36, v64, v65
	v_fmac_f32_e32 v46, v61, v61
	v_fma_f32 v63, v16, v66, -v36
	v_mul_f32_e32 v16, v64, v67
	global_load_dwordx4 v[36:39], v60, s[10:11] offset:64
	v_mul_f32_e32 v4, v4, v68
	v_fmac_f32_e32 v46, v62, v62
	v_fma_f32 v65, v17, v66, -v16
	v_mul_f32_e32 v16, v64, v69
	v_mul_f32_e32 v5, v5, v68
	v_fmac_f32_e32 v46, v63, v63
	v_fma_f32 v67, v18, v66, -v16
	v_mul_f32_e32 v16, v64, v70
	v_mul_f32_e32 v4, v64, v4
	v_fmac_f32_e32 v46, v65, v65
	v_fma_f32 v69, v19, v66, -v16
	v_fma_f32 v70, v20, v66, -v4
	v_mul_f32_e32 v4, v64, v5
	v_fmac_f32_e32 v46, v67, v67
	global_load_dwordx4 v[16:19], v60, s[10:11] offset:96
	v_fma_f32 v71, v21, v66, -v4
	v_pk_mul_f32 v[4:5], v[6:7], v[68:69] op_sel_hi:[1,0]
	v_fmac_f32_e32 v46, v69, v69
	v_pk_mul_f32 v[4:5], v[64:65], v[4:5] op_sel_hi:[0,1]
	v_fmac_f32_e32 v46, v70, v70
	v_pk_fma_f32 v[40:41], v[22:23], v[66:67], v[4:5] op_sel_hi:[1,0,1] neg_lo:[0,0,1] neg_hi:[0,0,1]
	v_pk_mul_f32 v[8:9], v[8:9], v[68:69] op_sel_hi:[1,0]
	v_fmac_f32_e32 v46, v71, v71
	v_pk_mul_f32 v[20:21], v[40:41], v[40:41]
	v_pk_mul_f32 v[8:9], v[64:65], v[8:9] op_sel_hi:[0,1]
	global_load_dwordx4 v[4:7], v60, s[10:11] offset:128
	v_add_f32_e32 v20, v20, v46
	v_pk_fma_f32 v[24:25], v[24:25], v[66:67], v[8:9] op_sel_hi:[1,0,1] neg_lo:[0,0,1] neg_hi:[0,0,1]
	v_add_f32_e32 v20, v21, v20
	v_pk_mul_f32 v[8:9], v[24:25], v[24:25]
	v_pk_mul_f32 v[12:13], v[12:13], v[68:69] op_sel_hi:[1,0]
	v_add_f32_e32 v8, v8, v20
	v_add_f32_e32 v42, v9, v8
	v_pk_mul_f32 v[8:9], v[10:11], v[68:69] op_sel_hi:[1,0]
	global_load_dwordx4 v[20:23], v60, s[10:11] offset:160
	v_pk_mul_f32 v[8:9], v[64:65], v[8:9] op_sel_hi:[0,1]
	v_pk_fma_f32 v[26:27], v[26:27], v[66:67], v[8:9] op_sel_hi:[1,0,1] neg_lo:[0,0,1] neg_hi:[0,0,1]
	v_pk_mul_f32 v[12:13], v[64:65], v[12:13] op_sel_hi:[0,1]
	v_pk_mul_f32 v[8:9], v[26:27], v[26:27]
	v_pk_fma_f32 v[28:29], v[28:29], v[66:67], v[12:13] op_sel_hi:[1,0,1] neg_lo:[0,0,1] neg_hi:[0,0,1]
	v_add_f32_e32 v8, v8, v42
	v_add_f32_e32 v42, v9, v8
	global_load_dwordx4 v[8:11], v60, s[10:11] offset:192
	v_pk_mul_f32 v[12:13], v[28:29], v[28:29]
	s_load_dwordx4 s[12:15], s[0:1], 0x100
	v_add_f32_e32 v12, v12, v42
	v_add_f32_e32 v46, v13, v12
	v_pk_mul_f32 v[42:43], v[14:15], v[68:69] op_sel_hi:[1,0]
	global_load_dwordx4 v[12:15], v60, s[10:11] offset:224
	v_pk_mul_f32 v[42:43], v[64:65], v[42:43] op_sel_hi:[0,1]
	v_pk_fma_f32 v[30:31], v[30:31], v[66:67], v[42:43] op_sel_hi:[1,0,1] neg_lo:[0,0,1] neg_hi:[0,0,1]
	s_mov_b64 s[10:11], 0x2b7c300
	v_pk_mul_f32 v[42:43], v[30:31], v[30:31]
	s_nop 0
	v_add_f32_e32 v42, v42, v46
	v_add_f32_e32 v42, v43, v42
	ds_bpermute_b32 v43, v166, v42
	s_waitcnt lgkmcnt(0)
	v_add_f32_e32 v42, v42, v43
	v_fmamk_f32 v42, v42, 0x3c800000, v186
	v_cmp_gt_f32_e32 vcc, s33, v42
	v_mul_f32_e32 v43, 0x4b800000, v42
	s_nop 0
	v_cndmask_b32_e32 v42, v42, v43, vcc
	v_rsq_f32_e32 v42, v42
	s_nop 0
	v_mul_f32_e32 v43, 0x45800000, v42
	v_cndmask_b32_e32 v42, v42, v43, vcc
	v_mul_f32_e32 v42, v162, v42
	v_mul_f32_e32 v43, v44, v42
	s_waitcnt vmcnt(7)
	v_mul_f32_e32 v43, v0, v43
	v_mul_f32_e32 v0, v45, v42
	v_mul_f32_e32 v44, v1, v0
	v_mul_f32_e32 v0, v47, v42
	v_mul_f32_e32 v45, v2, v0
	v_mul_f32_e32 v0, v48, v42
	v_mul_f32_e32 v3, v3, v0
	v_mul_f32_e32 v0, v49, v42
	s_waitcnt vmcnt(6)
	v_mul_f32_e32 v32, v32, v0
	v_mul_f32_e32 v0, v50, v42
	v_mul_f32_e32 v33, v33, v0
	v_mul_f32_e32 v0, v51, v42
	v_mul_f32_e32 v34, v34, v0
	v_mul_f32_e32 v0, v52, v42
	v_mul_f32_e32 v35, v35, v0
	v_mul_f32_e32 v0, v53, v42
	s_waitcnt vmcnt(5)
	v_mul_f32_e32 v36, v36, v0
	v_mul_f32_e32 v0, v54, v42
	v_mul_f32_e32 v37, v37, v0
	v_mul_f32_e32 v0, v55, v42
	v_mul_f32_e32 v38, v38, v0
	v_mul_f32_e32 v0, v56, v42
	v_mul_f32_e32 v39, v39, v0
	v_mul_f32_e32 v0, v57, v42
	s_waitcnt vmcnt(4)
	v_mul_f32_e32 v16, v16, v0
	v_mul_f32_e32 v0, v58, v42
	v_mul_f32_e32 v17, v17, v0
	v_mul_f32_e32 v0, v61, v42
	v_mul_f32_e32 v18, v18, v0
	v_mul_f32_e32 v0, v62, v42
	v_mul_f32_e32 v19, v19, v0
	v_mul_f32_e32 v0, v63, v42
	s_waitcnt vmcnt(3)
	v_mul_f32_e32 v46, v4, v0
	v_mul_f32_e32 v0, v65, v42
	v_mul_f32_e32 v47, v5, v0
	v_mul_f32_e32 v0, v67, v42
	v_mul_f32_e32 v6, v6, v0
	v_mul_f32_e32 v0, v69, v42
	v_mul_f32_e32 v7, v7, v0
	v_mul_f32_e32 v0, v70, v42
	s_waitcnt vmcnt(2)
	v_mul_f32_e32 v20, v20, v0
	v_mul_f32_e32 v0, v71, v42
	v_mul_f32_e32 v21, v21, v0
	v_mul_f32_e32 v0, v40, v42
	v_mul_f32_e32 v22, v22, v0
	v_mul_f32_e32 v0, v41, v42
	v_mul_f32_e32 v23, v23, v0
	v_mul_f32_e32 v0, v24, v42
	s_waitcnt vmcnt(1)
	v_mul_f32_e32 v8, v8, v0
	v_mul_f32_e32 v0, v25, v42
	v_mul_f32_e32 v9, v9, v0
	v_mul_f32_e32 v0, v26, v42
	v_mul_f32_e32 v10, v10, v0
	v_mul_f32_e32 v0, v27, v42
	v_mul_f32_e32 v11, v11, v0
	v_mul_f32_e32 v0, v28, v42
	s_waitcnt vmcnt(0)
	v_mul_f32_e32 v12, v12, v0
	v_mul_f32_e32 v0, v29, v42
	v_mul_f32_e32 v13, v13, v0
	v_mul_f32_e32 v0, v30, v42
	v_mul_f32_e32 v14, v14, v0
	v_mul_f32_e32 v0, v31, v42
	v_mul_f32_e32 v15, v15, v0
	v_and_or_b32 v0, v164, 31, v165
	v_ashrrev_i32_e32 v1, 31, v0
	v_lshlrev_b64 v[0:1], 11, v[0:1]
	v_lshl_add_u64 v[0:1], s[14:15], 0, v[0:1]
	v_lshl_add_u64 v[0:1], v[0:1], 0, v[152:153]
	v_lshlrev_b32_e32 v152, 1, v59
	v_lshl_add_u64 v[0:1], v[0:1], 0, v[152:153]
	v_lshl_add_u64 v[4:5], v[0:1], 0, s[10:11]
	s_mov_b32 s10, 0x2b7c000
	v_add_co_u32_e32 v0, vcc, s10, v0
	v_cvt_pk_bf16_f32 v2, v43, v44
	v_cvt_pk_bf16_f32 v3, v45, v3
	s_nop 1
	v_addc_co_u32_e32 v1, vcc, 0, v1, vcc
	global_store_dwordx2 v[0:1], v[2:3], off offset:768
	v_cvt_pk_bf16_f32 v0, v32, v33
	v_cvt_pk_bf16_f32 v1, v34, v35
	global_store_dwordx2 v[4:5], v[0:1], off offset:16
	v_cvt_pk_bf16_f32 v0, v36, v37
	v_cvt_pk_bf16_f32 v1, v38, v39
	global_store_dwordx2 v[4:5], v[0:1], off offset:32
	v_cvt_pk_bf16_f32 v0, v16, v17
	v_cvt_pk_bf16_f32 v1, v18, v19
	global_store_dwordx2 v[4:5], v[0:1], off offset:48
	v_cvt_pk_bf16_f32 v0, v46, v47
	v_cvt_pk_bf16_f32 v1, v6, v7
	global_store_dwordx2 v[4:5], v[0:1], off offset:64
	v_cvt_pk_bf16_f32 v0, v20, v21
	v_cvt_pk_bf16_f32 v1, v22, v23
	global_store_dwordx2 v[4:5], v[0:1], off offset:80
	v_cvt_pk_bf16_f32 v0, v8, v9
	v_cvt_pk_bf16_f32 v1, v10, v11
	global_store_dwordx2 v[4:5], v[0:1], off offset:96
	v_cvt_pk_bf16_f32 v0, v12, v13
	v_cvt_pk_bf16_f32 v1, v14, v15
	global_store_dwordx2 v[4:5], v[0:1], off offset:112
	s_or_b64 exec, exec, s[8:9]

; #define MFMA32(a, b, c) __builtin_amdgcn_mfma_f32_32x32x16_bf16((a), (b), (c), 0, 0, 0)
; template <int D>
; DI void attn_pass(const bfr* __restrict__ P, int b, int tq_wave, int qcol, int kcol, int vcol, int key0, int nkt, char* smem, f32x16 (&o)[2]) {
;     ...
;   for (int kt = 0; kt < nkt; ++kt) {
;     bfr* sK = sbase + (kt & 1) * 9216;
;     bfr* sV = sK + 64 * 72;
;     { int c = gt, row = c >> 3, kc = c & 7; *(u32x4*)(sK + row * KP + kc * 8) = kreg[0]; }
;     for (int i = 0; i < 1; ++i) {
;       int c = gt, row = c >> 3, kc = c & 7;
;       unsigned wds[4] = {vreg[i].x, vreg[i].y, vreg[i].z, vreg[i].w};
; #pragma unroll
;       for (int e = 0; e < 4; ++e) {
;         sV[(kc * 8 + 2 * e) * 72 + (row ^ (kc << 3))] = (bfr)(wds[e] & 0xffffu);
;         sV[(kc * 8 + 2 * e + 1) * 72 + (row ^ (kc << 3))] = (bfr)(wds[e] >> 16);
;       }
;     }
;     __syncthreads();
;     if (kt + 1 < nkt) {
;       const bfr* Pn = Pb + (size_t)(kt + 1) * 64 * PW;
;       { int c = gt, row = c >> 3, kc = c & 7; kreg[0] = *(const u32x4*)(Pn + (size_t)row * PW + kcol + kc * 8); vreg[0] = *(const u32x4*)(Pn + (size_t)row * PW + vcol + kc * 8); }
;     }
;     f32x16 s[2];
; #pragma unroll
;     for (int t2 = 0; t2 < 2; ++t2) {
; #pragma unroll
;       for (int i = 0; i < 16; ++i) s[t2][i] = 0.f;
; #pragma unroll
;       for (int ks = 0; ks < KS; ++ks) {
;         bf16x8 a = *(const bf16x8*)(sK + (t2 * 32 + r) * KP + ks * 16 + h * 8);
;         s[t2] = MFMA32(a, qf[ks], s[t2]);
;       }
;     }
;     float mx = s[0][0];
; #pragma unroll
;     for (int i = 0; i < 16; ++i) { mx = fmaxf(mx, s[0][i]); mx = fmaxf(mx, s[1][i]); }
;     mx = fmaxf(mx, __shfl_xor(mx, 32));
;     float mnew = fmaxf(mrun, mx);
;     float alpha = __builtin_amdgcn_exp2f(mrun - mnew);
;     mrun = mnew;
;     float ps = 0.f;
; #pragma unroll
;     for (int i = 0; i < 16; ++i) {
;       s[0][i] = __builtin_amdgcn_exp2f(s[0][i] - mnew); ps += s[0][i];
;       s[1][i] = __builtin_amdgcn_exp2f(s[1][i] - mnew); ps += s[1][i];
.LBB0_412:
	s_bitcmp1_b32 s8, 0
	s_cselect_b32 s9, 0x4800, 0
	s_add_i32 s9, s9, 0
	v_add3_u32 v32, s9, v115, v90
	v_add_u32_e32 v121, s9, v114
	v_mov_b32_e32 v120, v113
	s_waitcnt vmcnt(1)
	ds_write_b128 v32, v[84:87]
	v_add3_u32 v32, s9, v117, v118
	v_add3_u32 v33, s9, v118, v117
	v_add_u32_e32 v113, v121, v152
	s_waitcnt vmcnt(0)
	ds_write_b16 v32, v80 offset:9216
	ds_write_b16_d16_hi v33, v80 offset:9360
	ds_write_b16 v32, v81 offset:9504
	ds_write_b16_d16_hi v33, v81 offset:9648
	ds_write_b16 v32, v82 offset:9792
	ds_write_b16_d16_hi v33, v82 offset:9936
	ds_write_b16 v32, v83 offset:10080
	ds_write_b16_d16_hi v33, v83 offset:10224
	s_waitcnt lgkmcnt(0)
	s_barrier
	global_load_dwordx4 v[84:87], v[92:93], off
	global_load_dwordx4 v[80:83], v[94:95], off
	ds_read_b128 v[126:129], v113
	ds_read_b128 v[130:133], v113 offset:32
	ds_read_b128 v[134:137], v113 offset:64
	ds_read_b128 v[138:141], v113 offset:96
	ds_read_b128 v[142:145], v113 offset:4608
	ds_read_b128 v[146:149], v113 offset:4640
	ds_read_b128 v[156:159], v113 offset:4672
	ds_read_b128 v[164:167], v113 offset:4704
	v_mov_b32_e32 v96, v119
	s_waitcnt lgkmcnt(7)
	v_mfma_f32_32x32x16_bf16 v[32:47], v[126:129], v[76:79], 0
	s_add_i32 s8, s8, 1
	s_waitcnt lgkmcnt(6)
	v_mfma_f32_32x32x16_bf16 v[32:47], v[130:133], v[72:75], v[32:47]
	v_lshl_add_u64 v[92:93], v[92:93], 0, s[10:11]
	s_waitcnt lgkmcnt(5)
	v_mfma_f32_32x32x16_bf16 v[32:47], v[134:137], v[68:71], v[32:47]
	v_lshl_add_u64 v[94:95], v[94:95], 0, s[10:11]
	s_waitcnt lgkmcnt(4)
	v_mfma_f32_32x32x16_bf16 v[32:47], v[138:141], v[64:67], v[32:47]
	s_cmp_lg_u32 s8, 35
	s_waitcnt lgkmcnt(3)
	v_mfma_f32_32x32x16_bf16 v[48:63], v[142:145], v[76:79], 0
	s_waitcnt lgkmcnt(2)
	v_mfma_f32_32x32x16_bf16 v[48:63], v[146:149], v[72:75], v[48:63]
	s_waitcnt lgkmcnt(1)
	v_mfma_f32_32x32x16_bf16 v[48:63], v[156:159], v[68:71], v[48:63]
	s_waitcnt lgkmcnt(0)
	v_mfma_f32_32x32x16_bf16 v[48:63], v[164:167], v[64:67], v[48:63]
	v_add_u32_e32 v154, s9, v116
	v_lshl_add_u32 v168, v112, 1, v121
	v_lshl_add_u32 v169, v111, 1, v121
	v_lshl_add_u32 v170, v110, 1, v154
	v_lshl_add_u32 v171, v109, 1, v154
	v_lshl_add_u32 v172, v108, 1, v121
	v_lshl_add_u32 v173, v107, 1, v121
	v_lshl_add_u32 v174, v106, 1, v154
	v_lshl_add_u32 v175, v105, 1, v154
	v_lshl_add_u32 v176, v104, 1, v121
	v_lshl_add_u32 v177, v103, 1, v154
	v_lshl_add_u32 v178, v102, 1, v154
	v_lshl_add_u32 v179, v100, 1, v121
	v_lshl_add_u32 v180, v101, 1, v121
	v_lshl_add_u32 v181, v99, 1, v154
	v_lshl_add_u32 v160, v98, 1, v154
	v_max_f32_e32 v119, v32, v32
	v_max_f32_e32 v113, v48, v48
	v_max_f32_e32 v113, v119, v113
	v_max3_f32 v113, v113, v33, v49
	v_max3_f32 v113, v113, v34, v50
	v_max3_f32 v113, v113, v35, v51
	v_max3_f32 v113, v113, v36, v52
	v_max3_f32 v113, v113, v37, v53
	v_max3_f32 v113, v113, v38, v54
	v_max3_f32 v113, v113, v39, v55
	v_max3_f32 v113, v113, v40, v56
	v_max3_f32 v113, v113, v41, v57
	v_max3_f32 v113, v113, v42, v58
	v_max3_f32 v113, v113, v43, v59
	v_max3_f32 v113, v113, v44, v60
	v_max3_f32 v113, v113, v45, v61
	v_max3_f32 v113, v113, v46, v62
	v_max3_f32 v113, v113, v47, v63
	v_mov_b32_e32 v119, v113
	s_nop 1
	v_permlane32_swap_b32_e32 v113, v119
	s_waitcnt lgkmcnt(0)
	ds_read_b64 v[126:127], v168 offset:9216
	ds_read_b64 v[128:129], v169 offset:9216
	ds_read_b64 v[130:131], v170 offset:9216
	ds_read_b64 v[132:133], v171 offset:9216
	ds_read_b64 v[134:135], v172 offset:9216
	ds_read_b64 v[136:137], v173 offset:9216
	ds_read_b64 v[138:139], v174 offset:9216
	ds_read_b64 v[140:141], v175 offset:9216
	v_max3_f32 v119, v96, v113, v119
	v_sub_f32_e32 v32, v32, v119
	v_sub_f32_e32 v38, v38, v119
	v_exp_f32_e32 v32, v32
	v_sub_f32_e32 v48, v48, v119
	v_sub_f32_e32 v36, v36, v119
	v_exp_f32_e32 v124, v38
	v_sub_f32_e32 v38, v54, v119
	v_exp_f32_e32 v48, v48
	v_sub_f32_e32 v33, v33, v119
	v_exp_f32_e32 v122, v36
	v_sub_f32_e32 v36, v52, v119
	v_exp_f32_e32 v52, v38
	v_sub_f32_e32 v38, v39, v119
	v_exp_f32_e32 v33, v33
	v_sub_f32_e32 v49, v49, v119
	v_sub_f32_e32 v37, v37, v119
	v_exp_f32_e32 v125, v38
	v_sub_f32_e32 v38, v55, v119
	v_exp_f32_e32 v49, v49
	v_sub_f32_e32 v34, v34, v119
	v_exp_f32_e32 v123, v37
	v_sub_f32_e32 v37, v53, v119
	v_exp_f32_e32 v53, v38
	v_sub_f32_e32 v38, v40, v119
	v_sub_f32_e32 v40, v42, v119
	v_sub_f32_e32 v42, v44, v119
	v_exp_f32_e32 v34, v34
	v_sub_f32_e32 v50, v50, v119
	v_exp_f32_e32 v54, v38
	v_sub_f32_e32 v38, v56, v119
	v_exp_f32_e32 v56, v40
	v_sub_f32_e32 v40, v58, v119
	v_exp_f32_e32 v58, v42
	v_sub_f32_e32 v42, v60, v119
	s_waitcnt lgkmcnt(4)
; #define MFMA32(a, b, c) __builtin_amdgcn_mfma_f32_32x32x16_bf16((a), (b), (c), 0, 0, 0)
; DI unsigned pack2(float a, float b) { unsigned r; asm volatile("v_cvt_pk_bf16_f32 %0, %1, %2" : "=v"(r) : "v"(a), "v"(b)); return r; }
; template <int D>
; DI void attn_pass(const bfr* __restrict__ P, int b, int tq_wave, int qcol, int kcol, int vcol, int key0, int nkt, char* smem, f32x16 (&o)[2]) {
;     ...
;     for (int i = 0; i < 16; ++i) {
;       s[0][i] = __builtin_amdgcn_exp2f(s[0][i] - mnew); ps += s[0][i];
;       s[1][i] = __builtin_amdgcn_exp2f(s[1][i] - mnew); ps += s[1][i];
;     }
;     lsum = lsum * alpha + ps;
; #pragma unroll
;     for (int i = 0; i < 16; ++i) { accO[0][i] *= alpha; accO[1][i] *= alpha; }
; #pragma unroll
;     for (int t2 = 0; t2 < 2; ++t2)
; #pragma unroll
;       for (int j = 0; j < 2; ++j) {
;         unsigned pk[4];
; #pragma unroll
;         for (int e = 0; e < 4; ++e) pk[e] = pack2(s[t2][8 * j + 2 * e], s[t2][8 * j + 2 * e + 1]);
;         u32x4 pku = {pk[0], pk[1], pk[2], pk[3]};
;         bf16x8 pf = __builtin_bit_cast(bf16x8, pku);
; #pragma unroll
;         for (int dt = 0; dt < 2; ++dt) {
;           const int vsw = (((dt * 32 + r) >> 3) & 7) << 3;
;           const bfr* vrow = sV + (dt * 32 + r) * 72;
;           s16x4 lo = *(const s16x4*)(vrow + ((t2 * 32 + 16 * j + 4 * h) ^ vsw));
;           s16x4 hi = *(const s16x4*)(vrow + ((t2 * 32 + 16 * j + 4 * h + 8) ^ vsw));
;           bf16x8 vf = __builtin_shufflevector(lo, hi, 0, 1, 2, 3, 4, 5, 6, 7);
;           accO[dt] = MFMA32(vf, pf, accO[dt]);
;         }
;       }
	ds_read_b64 v[142:143], v168 offset:9280
	ds_read_b64 v[144:145], v176 offset:9216
	ds_read_b64 v[146:147], v177 offset:9216
	ds_read_b64 v[148:149], v178 offset:9216
	ds_read_b64 v[156:157], v179 offset:9216
	ds_read_b64 v[158:159], v180 offset:9216
	ds_read_b64 v[164:165], v181 offset:9216
	ds_read_b64 v[166:167], v160 offset:9216
	v_add_f32_e32 v60, 0, v32
	v_exp_f32_e32 v50, v50
	v_sub_f32_e32 v35, v35, v119
	v_add_f32_e32 v60, v48, v60
	v_exp_f32_e32 v35, v35
	v_sub_f32_e32 v51, v51, v119
	v_add_f32_e32 v60, v33, v60
	v_exp_f32_e32 v51, v51
	v_add_f32_e32 v60, v49, v60
	v_add_f32_e32 v60, v34, v60
	v_exp_f32_e32 v36, v36
	v_add_f32_e32 v60, v50, v60
	v_add_f32_e32 v60, v35, v60
	v_exp_f32_e32 v37, v37
	v_add_f32_e32 v60, v51, v60
	v_add_f32_e32 v60, v122, v60
	v_add_f32_e32 v60, v36, v60
	v_add_f32_e32 v60, v123, v60
	v_add_f32_e32 v60, v37, v60
	v_add_f32_e32 v60, v124, v60
	v_exp_f32_e32 v38, v38
	v_sub_f32_e32 v39, v41, v119
	v_add_f32_e32 v60, v52, v60
	v_exp_f32_e32 v55, v39
	v_sub_f32_e32 v39, v57, v119
	v_add_f32_e32 v60, v125, v60
	v_exp_f32_e32 v39, v39
	v_add_f32_e32 v60, v53, v60
	v_add_f32_e32 v60, v54, v60
	v_exp_f32_e32 v40, v40
	v_sub_f32_e32 v41, v43, v119
	v_add_f32_e32 v60, v38, v60
	v_exp_f32_e32 v57, v41
	v_sub_f32_e32 v41, v59, v119
	v_add_f32_e32 v60, v55, v60
	v_exp_f32_e32 v41, v41
	v_add_f32_e32 v60, v39, v60
	v_add_f32_e32 v60, v56, v60
	v_exp_f32_e32 v42, v42
	v_sub_f32_e32 v43, v45, v119
	v_add_f32_e32 v60, v40, v60
	v_exp_f32_e32 v59, v43
	v_sub_f32_e32 v43, v61, v119
	v_add_f32_e32 v60, v57, v60
	v_exp_f32_e32 v43, v43
	v_sub_f32_e32 v44, v46, v119
	v_add_f32_e32 v60, v41, v60
	v_exp_f32_e32 v46, v44
	v_sub_f32_e32 v44, v62, v119
	v_add_f32_e32 v60, v58, v60
	v_exp_f32_e32 v44, v44
	v_sub_f32_e32 v45, v47, v119
	v_add_f32_e32 v60, v42, v60
	v_exp_f32_e32 v47, v45
	v_sub_f32_e32 v45, v63, v119
	v_add_f32_e32 v60, v59, v60
	v_exp_f32_e32 v45, v45
	v_add_f32_e32 v60, v43, v60
	v_add_f32_e32 v60, v46, v60
	v_add_f32_e32 v60, v44, v60
	v_add_f32_e32 v60, v47, v60
	v_add_f32_e32 v113, v45, v60
	v_cvt_pk_bf16_f32 v32, v32, v33
	v_cvt_pk_bf16_f32 v33, v34, v35
	v_cvt_pk_bf16_f32 v34, v122, v123
	v_cvt_pk_bf16_f32 v35, v124, v125
	v_sub_f32_e32 v96, v96, v119
	v_exp_f32_e32 v96, v96
	s_nop 1
	v_pk_mul_f32 v[30:31], v[30:31], v[96:97] op_sel_hi:[1,0]
	v_pk_mul_f32 v[28:29], v[28:29], v[96:97] op_sel_hi:[1,0]
	v_pk_mul_f32 v[26:27], v[26:27], v[96:97] op_sel_hi:[1,0]
	v_pk_mul_f32 v[24:25], v[24:25], v[96:97] op_sel_hi:[1,0]
	v_pk_mul_f32 v[22:23], v[22:23], v[96:97] op_sel_hi:[1,0]
	v_pk_mul_f32 v[20:21], v[20:21], v[96:97] op_sel_hi:[1,0]
	v_pk_mul_f32 v[18:19], v[18:19], v[96:97] op_sel_hi:[1,0]
	v_pk_mul_f32 v[16:17], v[16:17], v[96:97] op_sel_hi:[1,0]
	v_pk_mul_f32 v[14:15], v[14:15], v[96:97] op_sel_hi:[1,0]
	v_pk_mul_f32 v[12:13], v[12:13], v[96:97] op_sel_hi:[1,0]
	s_waitcnt lgkmcnt(0)
	v_mfma_f32_32x32x16_bf16 v[16:31], v[126:129], v[32:35], v[16:31]
	v_mul_f32_e64 v10, v10, v96
	v_mul_f32_e64 v11, v11, v96
	v_pk_mul_f32 v[8:9], v[8:9], v[96:97] op_sel_hi:[1,0]
	v_pk_mul_f32 v[6:7], v[6:7], v[96:97] op_sel_hi:[1,0]
	v_pk_mul_f32 v[4:5], v[4:5], v[96:97] op_sel_hi:[1,0]
	v_pk_mul_f32 v[2:3], v[2:3], v[96:97] op_sel_hi:[1,0]
	v_pk_mul_f32 v[0:1], v[0:1], v[96:97] op_sel_hi:[1,0]
	v_fmac_f32_e32 v113, v120, v96
	s_nop 1
	v_mfma_f32_32x32x16_bf16 v[0:15], v[130:133], v[32:35], v[0:15]
	v_cvt_pk_bf16_f32 v32, v54, v55
	v_cvt_pk_bf16_f32 v33, v56, v57
	v_cvt_pk_bf16_f32 v34, v58, v59
	v_cvt_pk_bf16_f32 v35, v46, v47
	s_nop 1
	v_mfma_f32_32x32x16_bf16 v[16:31], v[134:137], v[32:35], v[16:31]
	s_nop 1
	v_mfma_f32_32x32x16_bf16 v[0:15], v[138:141], v[32:35], v[0:15]
	v_cvt_pk_bf16_f32 v32, v48, v49
	v_cvt_pk_bf16_f32 v33, v50, v51
	v_cvt_pk_bf16_f32 v34, v36, v37
	v_cvt_pk_bf16_f32 v35, v52, v53
	s_nop 1
	v_mfma_f32_32x32x16_bf16 v[16:31], v[142:145], v[32:35], v[16:31]
	s_nop 1
	v_mfma_f32_32x32x16_bf16 v[0:15], v[146:149], v[32:35], v[0:15]
	v_cvt_pk_bf16_f32 v32, v38, v39
	v_cvt_pk_bf16_f32 v33, v40, v41
	v_cvt_pk_bf16_f32 v34, v42, v43
	v_cvt_pk_bf16_f32 v35, v44, v45
	s_nop 1
	v_mfma_f32_32x32x16_bf16 v[16:31], v[156:159], v[32:35], v[16:31]
	s_nop 1
	v_mfma_f32_32x32x16_bf16 v[0:15], v[164:167], v[32:35], v[0:15]
	s_cbranch_scc1 .LBB0_412
	v_add3_u32 v32, 0, v115, v90
	s_waitcnt vmcnt(1)
	ds_write_b128 v32, v[84:87] offset:18432
	v_add3_u32 v32, 0, v117, v118
	v_add3_u32 v33, 0, v118, v117
	s_waitcnt vmcnt(0)
	ds_write_b16 v32, v80 offset:27648
	ds_write_b16_d16_hi v33, v80 offset:27792
	ds_write_b16 v32, v81 offset:27936
	ds_write_b16_d16_hi v33, v81 offset:28080
	ds_write_b16 v32, v82 offset:28224
	ds_write_b16_d16_hi v33, v82 offset:28368
	ds_write_b16 v32, v83 offset:28512
	ds_write_b16_d16_hi v33, v83 offset:28656
	v_add_u32_e32 v80, 0, v114
	v_add_u32_e32 v81, v80, v152
	s_waitcnt lgkmcnt(0)
	s_barrier
; #define MFMA32(a, b, c) __builtin_amdgcn_mfma_f32_32x32x16_bf16((a), (b), (c), 0, 0, 0)
; DI unsigned pack2(float a, float b) { unsigned r; asm volatile("v_cvt_pk_bf16_f32 %0, %1, %2" : "=v"(r) : "v"(a), "v"(b)); return r; }
; template <int D>
; DI void attn_pass(const bfr* __restrict__ P, int b, int tq_wave, int qcol, int kcol, int vcol, int key0, int nkt, char* smem, f32x16 (&o)[2]) {
;     ...
;     f32x16 s[2];
; #pragma unroll
;     for (int t2 = 0; t2 < 2; ++t2) {
; #pragma unroll
;       for (int i = 0; i < 16; ++i) s[t2][i] = 0.f;
; #pragma unroll
;       for (int ks = 0; ks < KS; ++ks) {
;         bf16x8 a = *(const bf16x8*)(sK + (t2 * 32 + r) * KP + ks * 16 + h * 8);
;         s[t2] = MFMA32(a, qf[ks], s[t2]);
;       }
;     }
;     float mx = s[0][0];
; #pragma unroll
;     for (int i = 0; i < 16; ++i) { mx = fmaxf(mx, s[0][i]); mx = fmaxf(mx, s[1][i]); }
;     mx = fmaxf(mx, __shfl_xor(mx, 32));
;     float mnew = fmaxf(mrun, mx);
;     float alpha = __builtin_amdgcn_exp2f(mrun - mnew);
;     mrun = mnew;
;     float ps = 0.f;
; #pragma unroll
;     for (int i = 0; i < 16; ++i) {
;       s[0][i] = __builtin_amdgcn_exp2f(s[0][i] - mnew); ps += s[0][i];
;       s[1][i] = __builtin_amdgcn_exp2f(s[1][i] - mnew); ps += s[1][i];
;     }
;     lsum = lsum * alpha + ps;
; #pragma unroll
;     for (int i = 0; i < 16; ++i) { accO[0][i] *= alpha; accO[1][i] *= alpha; }
; #pragma unroll
;     for (int t2 = 0; t2 < 2; ++t2)
; #pragma unroll
;       for (int j = 0; j < 2; ++j) {
;         unsigned pk[4];
; #pragma unroll
;         for (int e = 0; e < 4; ++e) pk[e] = pack2(s[t2][8 * j + 2 * e], s[t2][8 * j + 2 * e + 1]);
;         u32x4 pku = {pk[0], pk[1], pk[2], pk[3]};
;         bf16x8 pf = __builtin_bit_cast(bf16x8, pku);
; #pragma unroll
;         for (int dt = 0; dt < 2; ++dt) {
;           const int vsw = (((dt * 32 + r) >> 3) & 7) << 3;
;           const bfr* vrow = sV + (dt * 32 + r) * 72;
;           s16x4 lo = *(const s16x4*)(vrow + ((t2 * 32 + 16 * j + 4 * h) ^ vsw));
;           s16x4 hi = *(const s16x4*)(vrow + ((t2 * 32 + 16 * j + 4 * h + 8) ^ vsw));
;           bf16x8 vf = __builtin_shufflevector(lo, hi, 0, 1, 2, 3, 4, 5, 6, 7);
;           accO[dt] = MFMA32(vf, pf, accO[dt]);
;         }
;       }
	ds_read_b128 v[32:35], v81 offset:18432
	ds_read_b128 v[48:51], v81 offset:18464
	s_waitcnt lgkmcnt(1)
	v_mfma_f32_32x32x16_bf16 v[32:47], v[32:35], v[76:79], 0
	v_lshlrev_b32_e32 v152, 1, v88
	s_waitcnt lgkmcnt(0)
	v_mfma_f32_32x32x16_bf16 v[32:47], v[48:51], v[72:75], v[32:47]
	ds_read_b128 v[48:51], v81 offset:18496
	s_waitcnt lgkmcnt(0)
	v_mfma_f32_32x32x16_bf16 v[32:47], v[48:51], v[68:71], v[32:47]
	ds_read_b128 v[48:51], v81 offset:18528
	s_waitcnt lgkmcnt(0)
	v_mfma_f32_32x32x16_bf16 v[32:47], v[48:51], v[64:67], v[32:47]
	ds_read_b128 v[48:51], v81 offset:23040
	s_waitcnt lgkmcnt(0)
	v_mfma_f32_32x32x16_bf16 v[48:63], v[48:51], v[76:79], 0
	ds_read_b128 v[76:79], v81 offset:23072
	s_waitcnt lgkmcnt(0)
	v_mfma_f32_32x32x16_bf16 v[48:63], v[76:79], v[72:75], v[48:63]
	ds_read_b128 v[72:75], v81 offset:23104
	s_waitcnt lgkmcnt(0)
	v_mfma_f32_32x32x16_bf16 v[48:63], v[72:75], v[68:71], v[48:63]
	ds_read_b128 v[68:71], v81 offset:23136
	s_waitcnt lgkmcnt(0)
	v_mfma_f32_32x32x16_bf16 v[48:63], v[68:71], v[64:67], v[48:63]
	v_max_f32_e32 v65, v32, v32
	v_lshl_add_u32 v66, v112, 1, v80
	v_add_u32_e32 v67, 0x1200, v80
	s_nop 8
	v_max_f32_e32 v64, v48, v48
	v_max_f32_e32 v64, v65, v64
	v_max3_f32 v64, v64, v33, v49
	v_max3_f32 v64, v64, v34, v50
	v_max3_f32 v64, v64, v35, v51
	v_max3_f32 v64, v64, v36, v52
	v_max3_f32 v64, v64, v37, v53
	v_max3_f32 v64, v64, v38, v54
	v_max3_f32 v64, v64, v39, v55
	v_max3_f32 v64, v64, v40, v56
	v_max3_f32 v64, v64, v41, v57
	v_max3_f32 v64, v64, v42, v58
	v_max3_f32 v64, v64, v43, v59
	v_max3_f32 v64, v64, v44, v60
	v_max3_f32 v64, v64, v45, v61
	v_max3_f32 v64, v64, v46, v62
	v_max3_f32 v64, v64, v47, v63
	ds_bpermute_b32 v65, v91, v64
	s_waitcnt lgkmcnt(0)
	v_max3_f32 v65, v119, v64, v65
	v_sub_f32_e32 v64, v119, v65
	v_sub_f32_e32 v32, v32, v65
	v_exp_f32_e32 v64, v64
	v_exp_f32_e32 v32, v32
	v_sub_f32_e32 v48, v48, v65
	v_exp_f32_e32 v48, v48
	v_sub_f32_e32 v33, v33, v65
	v_exp_f32_e32 v33, v33
	v_sub_f32_e32 v49, v49, v65
	v_exp_f32_e32 v49, v49
	v_sub_f32_e32 v34, v34, v65
	v_exp_f32_e32 v34, v34
	v_sub_f32_e32 v50, v50, v65
	v_sub_f32_e32 v35, v35, v65
	v_sub_f32_e32 v51, v51, v65
	v_sub_f32_e32 v36, v36, v65
	v_sub_f32_e32 v52, v52, v65
	v_sub_f32_e32 v37, v37, v65
	v_sub_f32_e32 v53, v53, v65
	v_sub_f32_e32 v38, v38, v65
	v_sub_f32_e32 v54, v54, v65
	v_sub_f32_e32 v39, v39, v65
	v_sub_f32_e32 v55, v55, v65
	v_sub_f32_e32 v40, v40, v65
	v_sub_f32_e32 v56, v56, v65
	v_sub_f32_e32 v41, v41, v65
	v_sub_f32_e32 v57, v57, v65
	v_sub_f32_e32 v42, v42, v65
	v_sub_f32_e32 v58, v58, v65
	v_sub_f32_e32 v43, v43, v65
	v_sub_f32_e32 v59, v59, v65
	v_sub_f32_e32 v44, v44, v65
	v_sub_f32_e32 v60, v60, v65
	v_sub_f32_e32 v45, v45, v65
	v_sub_f32_e32 v61, v61, v65
	v_sub_f32_e32 v46, v46, v65
	v_sub_f32_e32 v62, v62, v65
	v_sub_f32_e32 v47, v47, v65
	v_sub_f32_e32 v63, v63, v65
	v_pk_mul_f32 v[30:31], v[30:31], v[64:65] op_sel_hi:[1,0]
	v_pk_mul_f32 v[28:29], v[28:29], v[64:65] op_sel_hi:[1,0]
	v_pk_mul_f32 v[26:27], v[26:27], v[64:65] op_sel_hi:[1,0]
	v_pk_mul_f32 v[24:25], v[24:25], v[64:65] op_sel_hi:[1,0]
	v_pk_mul_f32 v[22:23], v[22:23], v[64:65] op_sel_hi:[1,0]
	v_pk_mul_f32 v[20:21], v[20:21], v[64:65] op_sel_hi:[1,0]
	v_pk_mul_f32 v[18:19], v[18:19], v[64:65] op_sel_hi:[1,0]
	v_pk_mul_f32 v[16:17], v[16:17], v[64:65] op_sel_hi:[1,0]
	v_pk_mul_f32 v[14:15], v[14:15], v[64:65] op_sel_hi:[1,0]
	v_pk_mul_f32 v[12:13], v[12:13], v[64:65] op_sel_hi:[1,0]
	v_pk_mul_f32 v[10:11], v[10:11], v[64:65] op_sel_hi:[1,0]
	v_pk_mul_f32 v[8:9], v[8:9], v[64:65] op_sel_hi:[1,0]
	v_pk_mul_f32 v[6:7], v[6:7], v[64:65] op_sel_hi:[1,0]
	v_pk_mul_f32 v[4:5], v[4:5], v[64:65] op_sel_hi:[1,0]
	v_pk_mul_f32 v[2:3], v[2:3], v[64:65] op_sel_hi:[1,0]
	v_pk_mul_f32 v[0:1], v[0:1], v[64:65] op_sel_hi:[1,0]
	v_add_f32_e32 v65, 0, v32
	v_exp_f32_e32 v50, v50
	v_add_f32_e32 v65, v48, v65
	v_exp_f32_e32 v35, v35
	v_add_f32_e32 v65, v33, v65
	v_exp_f32_e32 v51, v51
	v_add_f32_e32 v65, v49, v65
	v_exp_f32_e32 v36, v36
	v_add_f32_e32 v65, v34, v65
	v_exp_f32_e32 v52, v52
	v_add_f32_e32 v65, v50, v65
	v_exp_f32_e32 v37, v37
	v_add_f32_e32 v65, v35, v65
	v_exp_f32_e32 v53, v53
	v_add_f32_e32 v65, v51, v65
	v_exp_f32_e32 v38, v38
	v_add_f32_e32 v65, v36, v65
	v_exp_f32_e32 v54, v54
	v_add_f32_e32 v65, v52, v65
	v_exp_f32_e32 v39, v39
	v_add_f32_e32 v65, v37, v65
	v_add_f32_e32 v65, v53, v65
	v_add_f32_e32 v65, v38, v65
	v_add_f32_e32 v65, v54, v65
	v_cvt_pk_bf16_f32 v32, v32, v33
	v_cvt_pk_bf16_f32 v33, v34, v35
	v_cvt_pk_bf16_f32 v34, v36, v37
	v_cvt_pk_bf16_f32 v35, v38, v39
	v_lshl_add_u32 v38, v111, 1, v80
	v_add_f32_e32 v65, v39, v65
	ds_read_b64 v[36:37], v66 offset:27648
	ds_read_b64 v[38:39], v38 offset:27648
	s_waitcnt lgkmcnt(0)
	v_mfma_f32_32x32x16_bf16 v[16:31], v[36:39], v[32:35], v[16:31]
	v_lshl_add_u32 v36, v110, 1, v67
	v_lshl_add_u32 v38, v109, 1, v67
	ds_read_b64 v[36:37], v36 offset:27648
	ds_read_b64 v[38:39], v38 offset:27648
	v_exp_f32_e32 v40, v40
	v_exp_f32_e32 v41, v41
	v_exp_f32_e32 v42, v42
	s_waitcnt lgkmcnt(0)
; #define MFMA32(a, b, c) __builtin_amdgcn_mfma_f32_32x32x16_bf16((a), (b), (c), 0, 0, 0)
; DI unsigned pack2(float a, float b) { unsigned r; asm volatile("v_cvt_pk_bf16_f32 %0, %1, %2" : "=v"(r) : "v"(a), "v"(b)); return r; }
; template <int D>
; DI void attn_pass(const bfr* __restrict__ P, int b, int tq_wave, int qcol, int kcol, int vcol, int key0, int nkt, char* smem, f32x16 (&o)[2]) {
;     ...
; #pragma unroll
;     for (int t2 = 0; t2 < 2; ++t2)
; #pragma unroll
;       for (int j = 0; j < 2; ++j) {
;         unsigned pk[4];
; #pragma unroll
;         for (int e = 0; e < 4; ++e) pk[e] = pack2(s[t2][8 * j + 2 * e], s[t2][8 * j + 2 * e + 1]);
;         u32x4 pku = {pk[0], pk[1], pk[2], pk[3]};
;         bf16x8 pf = __builtin_bit_cast(bf16x8, pku);
; #pragma unroll
;         for (int dt = 0; dt < 2; ++dt) {
;           const int vsw = (((dt * 32 + r) >> 3) & 7) << 3;
;           const bfr* vrow = sV + (dt * 32 + r) * 72;
;           s16x4 lo = *(const s16x4*)(vrow + ((t2 * 32 + 16 * j + 4 * h) ^ vsw));
;           s16x4 hi = *(const s16x4*)(vrow + ((t2 * 32 + 16 * j + 4 * h + 8) ^ vsw));
;           bf16x8 vf = __builtin_shufflevector(lo, hi, 0, 1, 2, 3, 4, 5, 6, 7);
;           accO[dt] = MFMA32(vf, pf, accO[dt]);
;         }
;       }
;   }
;   lsum += __shfl_xor(lsum, 32);
;   float inv = 1.f / lsum;
; #pragma unroll
;   for (int i = 0; i < 16; ++i) { o[0][i] = accO[0][i] * inv; o[1][i] = accO[1][i] * inv; }
; DI void store_o(bfr* O, int m, int colbase, int h, const f32x16 (&o)[2]) {
; #pragma unroll
;   for (int dt = 0; dt < 2; ++dt)
; #pragma unroll
;     for (int g4 = 0; g4 < 4; ++g4) {
;       int dv = dt * 32 + 8 * g4 + 4 * h;
;       uint2 pk; pk.x = pack2(o[dt][4 * g4], o[dt][4 * g4 + 1]); pk.y = pack2(o[dt][4 * g4 + 2], o[dt][4 * g4 + 3]);
;       *(uint2*)(O + (size_t)m * DM + colbase + dv) = pk;
;     }
; }
	v_mfma_f32_32x32x16_bf16 v[0:15], v[36:39], v[32:35], v[0:15]
	v_lshl_add_u32 v36, v108, 1, v80
	v_lshl_add_u32 v38, v107, 1, v80
	v_exp_f32_e32 v43, v43
	v_exp_f32_e32 v44, v44
	v_exp_f32_e32 v45, v45
	v_exp_f32_e32 v46, v46
	v_exp_f32_e32 v47, v47
	v_cvt_pk_bf16_f32 v32, v40, v41
	v_cvt_pk_bf16_f32 v33, v42, v43
	v_cvt_pk_bf16_f32 v34, v44, v45
	v_cvt_pk_bf16_f32 v35, v46, v47
	ds_read_b64 v[36:37], v36 offset:27648
	ds_read_b64 v[38:39], v38 offset:27648
	s_waitcnt lgkmcnt(0)
	v_mfma_f32_32x32x16_bf16 v[16:31], v[36:39], v[32:35], v[16:31]
	v_lshl_add_u32 v36, v106, 1, v67
	v_lshl_add_u32 v38, v105, 1, v67
	ds_read_b64 v[36:37], v36 offset:27648
	ds_read_b64 v[38:39], v38 offset:27648
	v_exp_f32_e32 v55, v55
	v_exp_f32_e32 v56, v56
	v_exp_f32_e32 v57, v57
	s_waitcnt lgkmcnt(0)
	v_mfma_f32_32x32x16_bf16 v[0:15], v[36:39], v[32:35], v[0:15]
	v_lshl_add_u32 v38, v104, 1, v80
	v_cvt_pk_bf16_f32 v32, v48, v49
	v_cvt_pk_bf16_f32 v33, v50, v51
	v_cvt_pk_bf16_f32 v34, v52, v53
	v_cvt_pk_bf16_f32 v35, v54, v55
	ds_read_b64 v[36:37], v66 offset:27712
	ds_read_b64 v[38:39], v38 offset:27648
	s_waitcnt lgkmcnt(0)
	v_mfma_f32_32x32x16_bf16 v[16:31], v[36:39], v[32:35], v[16:31]
	v_lshl_add_u32 v36, v103, 1, v67
	v_lshl_add_u32 v38, v102, 1, v67
	ds_read_b64 v[36:37], v36 offset:27648
	ds_read_b64 v[38:39], v38 offset:27648
	v_exp_f32_e32 v58, v58
	v_exp_f32_e32 v59, v59
	v_exp_f32_e32 v60, v60
	s_waitcnt lgkmcnt(0)
	v_mfma_f32_32x32x16_bf16 v[0:15], v[36:39], v[32:35], v[0:15]
	v_lshl_add_u32 v36, v100, 1, v80
	v_lshl_add_u32 v38, v101, 1, v80
	v_exp_f32_e32 v61, v61
	v_exp_f32_e32 v62, v62
	v_exp_f32_e32 v63, v63
	v_cvt_pk_bf16_f32 v32, v56, v57
	v_cvt_pk_bf16_f32 v33, v58, v59
	v_cvt_pk_bf16_f32 v34, v60, v61
	v_cvt_pk_bf16_f32 v35, v62, v63
	ds_read_b64 v[36:37], v36 offset:27648
	ds_read_b64 v[38:39], v38 offset:27648
	v_add_f32_e32 v65, v55, v65
	v_add_f32_e32 v65, v40, v65
	v_add_f32_e32 v65, v56, v65
	v_add_f32_e32 v65, v41, v65
	v_add_f32_e32 v65, v57, v65
	v_add_f32_e32 v65, v42, v65
	v_add_f32_e32 v65, v58, v65
	v_add_f32_e32 v65, v43, v65
	v_add_f32_e32 v65, v59, v65
	s_waitcnt lgkmcnt(0)
	v_mfma_f32_32x32x16_bf16 v[16:31], v[36:39], v[32:35], v[16:31]
	v_lshl_add_u32 v36, v99, 1, v67
	v_lshl_add_u32 v38, v98, 1, v67
	v_add_f32_e32 v65, v44, v65
	ds_read_b64 v[36:37], v36 offset:27648
	ds_read_b64 v[38:39], v38 offset:27648
	v_add_f32_e32 v65, v60, v65
	v_add_f32_e32 v65, v45, v65
	v_add_f32_e32 v65, v61, v65
	v_add_f32_e32 v65, v46, v65
	v_add_f32_e32 v65, v62, v65
	v_add_f32_e32 v65, v47, v65
	v_add_f32_e32 v65, v63, v65
	v_fmac_f32_e32 v65, v113, v64
	s_waitcnt lgkmcnt(0)
	v_mfma_f32_32x32x16_bf16 v[0:15], v[36:39], v[32:35], v[0:15]
	ds_bpermute_b32 v32, v91, v65
	s_waitcnt lgkmcnt(0)
	v_add_f32_e32 v32, v65, v32
	v_div_scale_f32 v33, s[8:9], v32, v32, 1.0
	v_rcp_f32_e32 v34, v33
	s_load_dwordx4 s[8:11], s[0:1], 0x100
	s_waitcnt lgkmcnt(0)
	s_mov_b64 s[8:9], 0x2b7c700
	v_fma_f32 v35, -v33, v34, 1.0
	v_fmac_f32_e32 v34, v35, v34
	v_div_scale_f32 v35, vcc, 1.0, v32, 1.0
	v_mul_f32_e32 v36, v35, v34
	v_fma_f32 v37, -v33, v36, v35
	v_fmac_f32_e32 v36, v37, v34
	v_fma_f32 v33, -v33, v36, v35
	v_div_fmas_f32 v33, v33, v34, v36
	v_div_fixup_f32 v32, v33, v32, 1.0
	v_mul_f32_e32 v33, v0, v32
	v_and_or_b32 v0, v89, 31, v97
	v_mul_f32_e32 v34, v1, v32
	v_ashrrev_i32_e32 v1, 31, v0
	v_lshlrev_b64 v[0:1], 11, v[0:1]
	v_mul_f32_e32 v37, v4, v32
	v_lshl_add_u64 v[0:1], s[10:11], 0, v[0:1]
	v_lshrrev_b32_e32 v4, 2, v89
	v_lshl_add_u64 v[0:1], v[0:1], 0, v[152:153]
	v_and_b32_e32 v152, 8, v4
	v_lshl_add_u64 v[0:1], v[0:1], 0, v[152:153]
	v_mul_f32_e32 v38, v5, v32
	v_lshl_add_u64 v[4:5], v[0:1], 0, s[8:9]
	s_mov_b32 s8, 0x2b7c000
	v_add_co_u32_e32 v0, vcc, s8, v0
	v_mul_f32_e32 v16, v16, v32
	s_nop 0
	v_addc_co_u32_e32 v1, vcc, 0, v1, vcc
	v_mul_f32_e32 v17, v17, v32
	v_mul_f32_e32 v18, v18, v32
	v_mul_f32_e32 v35, v2, v32
	v_mul_f32_e32 v19, v19, v32
	v_mul_f32_e32 v36, v3, v32
	v_mul_f32_e32 v20, v20, v32
	v_mul_f32_e32 v21, v21, v32
	v_mul_f32_e32 v22, v22, v32
	v_mul_f32_e32 v23, v23, v32
	v_cvt_pk_bf16_f32 v2, v16, v17
	v_cvt_pk_bf16_f32 v3, v18, v19
	global_store_dwordx2 v[0:1], v[2:3], off offset:1792
	v_cvt_pk_bf16_f32 v0, v20, v21
	v_cvt_pk_bf16_f32 v1, v22, v23
	v_mul_f32_e32 v24, v24, v32
	v_mul_f32_e32 v25, v25, v32
	v_mul_f32_e32 v26, v26, v32
	v_mul_f32_e32 v27, v27, v32
	global_store_dwordx2 v[4:5], v[0:1], off offset:16
	v_cvt_pk_bf16_f32 v0, v24, v25
	v_cvt_pk_bf16_f32 v1, v26, v27
	v_mul_f32_e32 v28, v28, v32
	v_mul_f32_e32 v29, v29, v32
	v_mul_f32_e32 v30, v30, v32
	v_mul_f32_e32 v31, v31, v32
	global_store_dwordx2 v[4:5], v[0:1], off offset:32
	v_cvt_pk_bf16_f32 v0, v28, v29
	v_cvt_pk_bf16_f32 v1, v30, v31
	global_store_dwordx2 v[4:5], v[0:1], off offset:48
	v_cvt_pk_bf16_f32 v0, v33, v34
	v_cvt_pk_bf16_f32 v1, v35, v36
	v_mul_f32_e32 v6, v6, v32
	v_mul_f32_e32 v7, v7, v32
	global_store_dwordx2 v[4:5], v[0:1], off offset:64
	v_cvt_pk_bf16_f32 v0, v37, v38
	v_cvt_pk_bf16_f32 v1, v6, v7
	v_mul_f32_e32 v8, v8, v32
	v_mul_f32_e32 v9, v9, v32
	v_mul_f32_e32 v10, v10, v32
	v_mul_f32_e32 v11, v11, v32
	global_store_dwordx2 v[4:5], v[0:1], off offset:80
	v_cvt_pk_bf16_f32 v0, v8, v9
	v_cvt_pk_bf16_f32 v1, v10, v11
	v_mul_f32_e32 v12, v12, v32
	v_mul_f32_e32 v13, v13, v32
	v_mul_f32_e32 v14, v14, v32
	v_mul_f32_e32 v15, v15, v32
	global_store_dwordx2 v[4:5], v[0:1], off offset:96
	v_cvt_pk_bf16_f32 v0, v12, v13
	v_cvt_pk_bf16_f32 v1, v14, v15
	global_store_dwordx2 v[4:5], v[0:1], off offset:112

; DI void attn_pass_da(const bfr* __restrict__ P, int b, int tq_wave, int qcol, int kcol, int vcol, int key0, int nkt, char* smem, f32x16 (&o0)[2], f32x16 (&o1)[2]) {
;     ...
;   for (int kt = 0; kt < nkt; ++kt) {
;     bfr* sK = sbase + (kt & 1) * 9216;
;     bfr* sV = sK + 64 * 72;
;     { int c = gt, row = c >> 3, kc = c & 7; *(u32x4*)(sK + row * KP + kc * 8) = kreg[0]; }
;     for (int i = 0; i < 1; ++i) {
;       int c = gt, row = c >> 3, kc = c & 7;
;       unsigned wds[4] = {vreg[i].x, vreg[i].y, vreg[i].z, vreg[i].w};
; #pragma unroll
;       for (int e = 0; e < 4; ++e) {
;         sV[(kc * 8 + 2 * e) * 72 + (row ^ (kc << 3))] = (bfr)(wds[e] & 0xffffu);
;         sV[(kc * 8 + 2 * e + 1) * 72 + (row ^ (kc << 3))] = (bfr)(wds[e] >> 16);
;       }
;     }
;     __syncthreads();
;     if (kt + 1 < nkt) {
;       const bfr* Pn = Pb + (size_t)(kt + 1) * 64 * PW;
;       { int c = gt, row = c >> 3, kc = c & 7; kreg[0] = *(const u32x4*)(Pn + (size_t)row * PW + kcol + kc * 8); vreg[0] = *(const u32x4*)(Pn + (size_t)row * PW + vcol + kc * 8); }
;     }
;     f32x16 s0[2], s1[2];
; #pragma unroll
;     for (int t2 = 0; t2 < 2; ++t2) {
; #pragma unroll
;       for (int i = 0; i < 16; ++i) { s0[t2][i] = 0.f; s1[t2][i] = 0.f; }
; #pragma unroll
;       for (int ks = 0; ks < 2; ++ks) {
;         bf16x8 a0 = *(const bf16x8*)(sK + (t2 * 32 + r) * KP + ks * 16 + h * 8);
;         bf16x8 a1 = *(const bf16x8*)(sK + (t2 * 32 + r) * KP + 32 + ks * 16 + h * 8);
;         s0[t2] = MFMA32(a0, qf[ks], s0[t2]);
;         s1[t2] = MFMA32(a1, qf[2 + ks], s1[t2]);
;       }
;     }
;     float mx0 = s0[0][0], mx1 = s1[0][0];
; #pragma unroll
;     for (int i = 0; i < 16; ++i) { mx0 = fmaxf(mx0, fmaxf(s0[0][i], s0[1][i])); mx1 = fmaxf(mx1, fmaxf(s1[0][i], s1[1][i])); }
;     mx0 = fmaxf(mx0, __shfl_xor(mx0, 32)); mx1 = fmaxf(mx1, __shfl_xor(mx1, 32));
;     const float mn0 = fmaxf(m0, mx0), mn1 = fmaxf(m1, mx1);
;     const float al0 = __builtin_amdgcn_exp2f(m0 - mn0), al1 = __builtin_amdgcn_exp2f(m1 - mn1);
;     m0 = mn0; m1 = mn1;
;     float ps0 = 0.f, ps1 = 0.f;
; #pragma unroll
;     for (int i = 0; i < 16; ++i) {
;       s0[0][i] = __builtin_amdgcn_exp2f(s0[0][i] - mn0); ps0 += s0[0][i];
;       s0[1][i] = __builtin_amdgcn_exp2f(s0[1][i] - mn0); ps0 += s0[1][i];
;       s1[0][i] = __builtin_amdgcn_exp2f(s1[0][i] - mn1); ps1 += s1[0][i];
.LBB0_421:
	s_bitcmp1_b32 s10, 0
	s_cselect_b32 s11, 0x4800, 0
	s_add_i32 s11, s11, 0
	v_add3_u32 v64, s11, v206, v152
	v_add_u32_e32 v194, s11, v205
	s_waitcnt vmcnt(1)
	ds_write_b128 v64, v[148:151]
	v_add3_u32 v64, s11, v207, v208
	v_add3_u32 v65, s11, v208, v207
	v_add_u32_e32 v100, v194, v204
	s_waitcnt vmcnt(0)
	ds_write_b16 v64, v144 offset:9216
	ds_write_b16_d16_hi v65, v144 offset:9360
	ds_write_b16 v64, v145 offset:9504
	ds_write_b16_d16_hi v65, v145 offset:9648
	ds_write_b16 v64, v146 offset:9792
	ds_write_b16_d16_hi v65, v146 offset:9936
	ds_write_b16 v64, v147 offset:10080
	ds_write_b16_d16_hi v65, v147 offset:10224
	s_waitcnt lgkmcnt(0)
	s_barrier
	global_load_dwordx4 v[148:151], v[158:159], off
	global_load_dwordx4 v[144:147], v[158:159], off offset:512
	ds_read_b128 v[64:67], v100 offset:64
	ds_read_b128 v[68:71], v100
	ds_read_b128 v[96:99], v100 offset:32
	ds_read_b128 v[100:103], v100 offset:96
	s_waitcnt lgkmcnt(2)
	v_mfma_f32_32x32x16_bf16 v[80:95], v[68:71], v[140:143], 0
	v_add_u32_e32 v195, s11, v211
	v_add_u32_e32 v192, v195, v204
	v_mov_b32_e32 v160, v209
	v_mov_b32_e32 v161, v210
	s_add_i32 s10, s10, 1
	v_lshl_add_u64 v[158:159], v[158:159], 0, s[12:13]
	s_cmp_lg_u32 s10, 35
	v_mfma_f32_32x32x16_bf16 v[64:79], v[64:67], v[136:139], 0
	s_waitcnt lgkmcnt(1)
	v_mfma_f32_32x32x16_bf16 v[80:95], v[96:99], v[132:135], v[80:95]
	s_waitcnt lgkmcnt(0)
	v_mfma_f32_32x32x16_bf16 v[64:79], v[100:103], v[128:131], v[64:79]
	ds_read_b128 v[96:99], v192 offset:64
	ds_read_b128 v[100:103], v192
	ds_read_b128 v[212:215], v192 offset:32
	ds_read_b128 v[216:219], v192 offset:96
	s_nop 5
	v_max3_f32 v209, v80, v81, v82
	v_max3_f32 v209, v209, v83, v84
	v_max3_f32 v193, v64, v65, v66
	s_waitcnt lgkmcnt(2)
	v_mfma_f32_32x32x16_bf16 v[112:127], v[100:103], v[140:143], 0
	v_mfma_f32_32x32x16_bf16 v[96:111], v[96:99], v[136:139], 0
	s_waitcnt lgkmcnt(1)
	v_mfma_f32_32x32x16_bf16 v[112:127], v[212:215], v[132:135], v[112:127]
	v_max3_f32 v193, v193, v67, v68
	v_max3_f32 v209, v209, v85, v86
	s_waitcnt lgkmcnt(0)
	v_mfma_f32_32x32x16_bf16 v[96:111], v[216:219], v[128:131], v[96:111]
	v_max3_f32 v193, v193, v69, v70
	v_max3_f32 v209, v209, v87, v88
	v_max3_f32 v193, v193, v71, v72
	v_max3_f32 v209, v209, v89, v90
	v_max3_f32 v193, v193, v73, v74
	v_max3_f32 v209, v209, v91, v92
	v_max3_f32 v193, v193, v75, v76
	v_max3_f32 v209, v209, v93, v94
	v_max3_f32 v193, v193, v77, v78
	v_max3_f32 v209, v209, v95, v112
	v_max3_f32 v209, v209, v113, v114
	v_max3_f32 v209, v209, v115, v116
	v_max3_f32 v209, v209, v117, v118
	v_max3_f32 v209, v209, v119, v120
	v_max3_f32 v209, v209, v121, v122
	v_max3_f32 v209, v209, v123, v124
	v_max3_f32 v209, v209, v125, v126
	v_max_f32_e32 v192, v209, v127
	v_max3_f32 v193, v193, v79, v96
	v_max3_f32 v193, v193, v97, v98
	v_max3_f32 v193, v193, v99, v100
	v_max3_f32 v193, v193, v101, v102
	v_max3_f32 v193, v193, v103, v104
	v_max3_f32 v193, v193, v105, v106
	v_max3_f32 v193, v193, v107, v108
	v_max3_f32 v193, v193, v109, v110
	v_max_f32_e32 v193, v193, v111
	v_mov_b32_e32 v210, v193
	v_mov_b32_e32 v209, v192
	s_nop 1
	v_permlane32_swap_b32_e32 v193, v210
	v_permlane32_swap_b32_e32 v192, v209
	s_waitcnt lgkmcnt(1)
	v_max3_f32 v210, v161, v193, v210
	s_waitcnt lgkmcnt(0)
	v_max3_f32 v209, v160, v192, v209
	v_sub_f32_e32 v64, v64, v210
	v_sub_f32_e32 v80, v80, v209
	v_exp_f32_e32 v193, v64
	v_sub_f32_e32 v64, v96, v210
	v_exp_f32_e32 v192, v80
	v_sub_f32_e32 v80, v112, v209
	v_exp_f32_e32 v213, v64
	v_sub_f32_e32 v64, v81, v209
	v_exp_f32_e32 v212, v80
	v_exp_f32_e32 v80, v64
	v_sub_f32_e32 v64, v113, v209
	v_exp_f32_e32 v96, v64
	v_sub_f32_e32 v64, v65, v210
	v_exp_f32_e32 v81, v64
	v_sub_f32_e32 v64, v97, v210
	v_exp_f32_e32 v97, v64
	v_sub_f32_e32 v64, v82, v209
	v_exp_f32_e32 v112, v64
	v_sub_f32_e32 v64, v114, v209
	v_exp_f32_e32 v214, v64
	v_sub_f32_e32 v64, v66, v210
	v_exp_f32_e32 v113, v64
	v_sub_f32_e32 v64, v98, v210
	v_exp_f32_e32 v215, v64
	v_sub_f32_e32 v64, v83, v209
	v_exp_f32_e32 v82, v64
	v_sub_f32_e32 v64, v115, v209
	v_exp_f32_e32 v98, v64
	v_sub_f32_e32 v64, v67, v210
	v_exp_f32_e32 v83, v64
	v_sub_f32_e32 v64, v99, v210
	v_exp_f32_e32 v99, v64
	v_sub_f32_e32 v64, v84, v209
	v_exp_f32_e32 v114, v64
	v_sub_f32_e32 v64, v116, v209
	v_exp_f32_e32 v216, v64
	v_sub_f32_e32 v64, v68, v210
	v_exp_f32_e32 v115, v64
	v_sub_f32_e32 v64, v100, v210
	v_exp_f32_e32 v217, v64
	v_sub_f32_e32 v64, v85, v209
	v_exp_f32_e32 v84, v64
	v_sub_f32_e32 v64, v117, v209
	v_exp_f32_e32 v100, v64
	v_sub_f32_e32 v64, v69, v210
	v_exp_f32_e32 v85, v64
	v_sub_f32_e32 v64, v101, v210
	v_exp_f32_e32 v101, v64
	v_sub_f32_e32 v64, v86, v209
	v_exp_f32_e32 v116, v64
	v_sub_f32_e32 v64, v118, v209
	v_exp_f32_e32 v218, v64
	v_sub_f32_e32 v64, v70, v210
	v_exp_f32_e32 v117, v64
	v_sub_f32_e32 v64, v102, v210
	v_exp_f32_e32 v219, v64
	v_sub_f32_e32 v64, v87, v209
	v_exp_f32_e32 v70, v64
	v_sub_f32_e32 v64, v119, v209
	v_exp_f32_e32 v86, v64
	v_sub_f32_e32 v64, v71, v210
	v_exp_f32_e32 v71, v64
	v_sub_f32_e32 v64, v103, v210
	v_exp_f32_e32 v87, v64
	v_sub_f32_e32 v64, v88, v209
	v_exp_f32_e32 v102, v64
	v_sub_f32_e32 v64, v120, v209
	v_exp_f32_e32 v118, v64
	v_sub_f32_e32 v64, v72, v210
	v_exp_f32_e32 v103, v64
	v_sub_f32_e32 v64, v104, v210
	v_exp_f32_e32 v119, v64
	v_sub_f32_e32 v64, v89, v209
	v_exp_f32_e32 v88, v64
	v_sub_f32_e32 v64, v121, v209
	v_exp_f32_e32 v104, v64
	v_sub_f32_e32 v64, v73, v210
	v_exp_f32_e32 v89, v64
	v_sub_f32_e32 v64, v105, v210
	v_exp_f32_e32 v105, v64
	v_sub_f32_e32 v64, v90, v209
	v_exp_f32_e32 v120, v64
	v_sub_f32_e32 v64, v122, v209
	v_exp_f32_e32 v220, v64
	v_sub_f32_e32 v64, v74, v210
	v_exp_f32_e32 v121, v64
; #define MFMA32(a, b, c) __builtin_amdgcn_mfma_f32_32x32x16_bf16((a), (b), (c), 0, 0, 0)
; DI unsigned pack2(float a, float b) { unsigned r; asm volatile("v_cvt_pk_bf16_f32 %0, %1, %2" : "=v"(r) : "v"(a), "v"(b)); return r; }
; DI void attn_pass_da(const bfr* __restrict__ P, int b, int tq_wave, int qcol, int kcol, int vcol, int key0, int nkt, char* smem, f32x16 (&o0)[2], f32x16 (&o1)[2]) {
;     ...
;     const float mn0 = fmaxf(m0, mx0), mn1 = fmaxf(m1, mx1);
;     const float al0 = __builtin_amdgcn_exp2f(m0 - mn0), al1 = __builtin_amdgcn_exp2f(m1 - mn1);
;     m0 = mn0; m1 = mn1;
;     float ps0 = 0.f, ps1 = 0.f;
; #pragma unroll
;     for (int i = 0; i < 16; ++i) {
;       s0[0][i] = __builtin_amdgcn_exp2f(s0[0][i] - mn0); ps0 += s0[0][i];
;       s0[1][i] = __builtin_amdgcn_exp2f(s0[1][i] - mn0); ps0 += s0[1][i];
;       s1[0][i] = __builtin_amdgcn_exp2f(s1[0][i] - mn1); ps1 += s1[0][i];
;       s1[1][i] = __builtin_amdgcn_exp2f(s1[1][i] - mn1); ps1 += s1[1][i];
;     }
;     l0 = l0 * al0 + ps0; l1 = l1 * al1 + ps1;
; #pragma unroll
;     for (int i = 0; i < 16; ++i) { acc0[0][i] *= al0; acc0[1][i] *= al0; acc1[0][i] *= al1; acc1[1][i] *= al1; }
; #pragma unroll
;     for (int t2 = 0; t2 < 2; ++t2)
; #pragma unroll
;       for (int j = 0; j < 2; ++j) {
;         u32x4 pk0, pk1;
;         pk0.x = pack2(s0[t2][8 * j + 0], s0[t2][8 * j + 1]); pk0.y = pack2(s0[t2][8 * j + 2], s0[t2][8 * j + 3]);
;         pk0.z = pack2(s0[t2][8 * j + 4], s0[t2][8 * j + 5]); pk0.w = pack2(s0[t2][8 * j + 6], s0[t2][8 * j + 7]);
;         pk1.x = pack2(s1[t2][8 * j + 0], s1[t2][8 * j + 1]); pk1.y = pack2(s1[t2][8 * j + 2], s1[t2][8 * j + 3]);
;         pk1.z = pack2(s1[t2][8 * j + 4], s1[t2][8 * j + 5]); pk1.w = pack2(s1[t2][8 * j + 6], s1[t2][8 * j + 7]);
;         const bf16x8 pf0 = __builtin_bit_cast(bf16x8, pk0), pf1 = __builtin_bit_cast(bf16x8, pk1);
; #pragma unroll
;         for (int dt = 0; dt < 2; ++dt) {
;           const int vsw = (((dt * 32 + r) >> 3) & 7) << 3;
;           const bfr* vrow = sV + (dt * 32 + r) * 72;
;           s16x4 lo = *(const s16x4*)(vrow + ((t2 * 32 + 16 * j + 4 * h) ^ vsw));
;           s16x4 hi = *(const s16x4*)(vrow + ((t2 * 32 + 16 * j + 4 * h + 8) ^ vsw));
;           bf16x8 vf = __builtin_shufflevector(lo, hi, 0, 1, 2, 3, 4, 5, 6, 7);
;           acc0[dt] = MFMA32(vf, pf0, acc0[dt]);
;           acc1[dt] = MFMA32(vf, pf1, acc1[dt]);
;         }
	v_sub_f32_e32 v64, v106, v210
	v_exp_f32_e32 v221, v64
	v_sub_f32_e32 v64, v91, v209
	v_exp_f32_e32 v90, v64
	v_sub_f32_e32 v64, v123, v209
	v_exp_f32_e32 v106, v64
	v_sub_f32_e32 v64, v75, v210
	v_exp_f32_e32 v91, v64
	v_sub_f32_e32 v64, v107, v210
	v_exp_f32_e32 v107, v64
	v_sub_f32_e32 v64, v92, v209
	v_exp_f32_e32 v122, v64
	v_sub_f32_e32 v64, v124, v209
	v_exp_f32_e32 v222, v64
	v_sub_f32_e32 v64, v76, v210
	v_exp_f32_e32 v123, v64
	v_sub_f32_e32 v64, v108, v210
	v_exp_f32_e32 v223, v64
	v_sub_f32_e32 v64, v93, v209
	v_exp_f32_e32 v92, v64
	v_sub_f32_e32 v64, v125, v209
	v_exp_f32_e32 v108, v64
	v_sub_f32_e32 v64, v77, v210
	v_exp_f32_e32 v93, v64
	v_sub_f32_e32 v64, v109, v210
	v_exp_f32_e32 v109, v64
	v_sub_f32_e32 v64, v94, v209
	v_exp_f32_e32 v124, v64
	v_sub_f32_e32 v64, v126, v209
	v_exp_f32_e32 v224, v64
	v_sub_f32_e32 v64, v78, v210
	v_exp_f32_e32 v125, v64
	v_sub_f32_e32 v64, v110, v210
	v_exp_f32_e32 v225, v64
	v_sub_f32_e32 v64, v95, v209
	v_exp_f32_e32 v94, v64
	v_sub_f32_e32 v64, v127, v209
	v_exp_f32_e32 v110, v64
	v_sub_f32_e32 v64, v79, v210
	v_exp_f32_e32 v95, v64
	v_sub_f32_e32 v64, v111, v210
	v_exp_f32_e32 v111, v64
	v_pk_add_f32 v[64:65], v[192:193], 0 op_sel_hi:[1,0]
	v_sub_f32_e32 v161, v161, v210
	v_pk_add_f32 v[64:65], v[212:213], v[64:65]
	v_exp_f32_e32 v161, v161
	v_pk_add_f32 v[64:65], v[80:81], v[64:65]
	v_lshl_add_u32 v74, v180, 1, v194
	v_pk_add_f32 v[64:65], v[96:97], v[64:65]
	v_lshl_add_u32 v76, v179, 1, v195
	v_pk_add_f32 v[64:65], v[112:113], v[64:65]
	v_lshl_add_u32 v78, v178, 1, v195
	v_pk_add_f32 v[64:65], v[214:215], v[64:65]
	v_sub_f32_e32 v160, v160, v209
	v_pk_add_f32 v[64:65], v[82:83], v[64:65]
	v_exp_f32_e32 v160, v160
	v_pk_add_f32 v[64:65], v[98:99], v[64:65]
	v_pk_mul_f32 v[62:63], v[62:63], v[160:161] op_sel_hi:[1,0]
	v_pk_add_f32 v[64:65], v[114:115], v[64:65]
	v_pk_mul_f32 v[60:61], v[60:61], v[160:161] op_sel_hi:[1,0]
	v_pk_add_f32 v[64:65], v[216:217], v[64:65]
	v_pk_mul_f32 v[58:59], v[58:59], v[160:161] op_sel_hi:[1,0]
	v_pk_add_f32 v[64:65], v[84:85], v[64:65]
	v_pk_mul_f32 v[56:57], v[56:57], v[160:161] op_sel_hi:[1,0]
	v_pk_add_f32 v[64:65], v[100:101], v[64:65]
	v_pk_mul_f32 v[54:55], v[54:55], v[160:161] op_sel_hi:[1,0]
	v_pk_add_f32 v[64:65], v[116:117], v[64:65]
	v_pk_mul_f32 v[52:53], v[52:53], v[160:161] op_sel_hi:[1,0]
	v_pk_add_f32 v[64:65], v[218:219], v[64:65]
	v_pk_mul_f32 v[50:51], v[50:51], v[160:161] op_sel_hi:[1,0]
	v_pk_add_f32 v[64:65], v[70:71], v[64:65]
	v_pk_mul_f32 v[48:49], v[48:49], v[160:161] op_sel_hi:[1,0]
	v_pk_add_f32 v[64:65], v[86:87], v[64:65]
	v_pk_mul_f32 v[30:31], v[30:31], v[160:161] op_sel_hi:[1,0]
	v_pk_add_f32 v[64:65], v[102:103], v[64:65]
	v_pk_mul_f32 v[28:29], v[28:29], v[160:161] op_sel_hi:[1,0]
	v_pk_add_f32 v[64:65], v[118:119], v[64:65]
	v_pk_mul_f32 v[26:27], v[26:27], v[160:161] op_sel_hi:[1,0]
	v_pk_add_f32 v[64:65], v[88:89], v[64:65]
	v_pk_mul_f32 v[24:25], v[24:25], v[160:161] op_sel_hi:[1,0]
	v_pk_add_f32 v[64:65], v[104:105], v[64:65]
	v_pk_mul_f32 v[22:23], v[22:23], v[160:161] op_sel_hi:[1,0]
	v_pk_add_f32 v[64:65], v[120:121], v[64:65]
	v_pk_mul_f32 v[20:21], v[20:21], v[160:161] op_sel_hi:[1,0]
	v_pk_add_f32 v[126:127], v[220:221], v[64:65]
	v_cvt_pk_bf16_f32 v64, v192, v80
	v_cvt_pk_bf16_f32 v65, v112, v82
	v_lshl_add_u32 v112, v181, 1, v194
	v_cvt_pk_bf16_f32 v66, v114, v84
	v_cvt_pk_bf16_f32 v67, v116, v70
	v_cvt_pk_bf16_f32 v68, v193, v81
	v_cvt_pk_bf16_f32 v69, v113, v83
	v_cvt_pk_bf16_f32 v70, v115, v85
	v_cvt_pk_bf16_f32 v71, v117, v71
	ds_read_b64 v[72:73], v112 offset:9216
	ds_read_b64 v[74:75], v74 offset:9216
	ds_read_b64 v[76:77], v76 offset:9216
	ds_read_b64 v[78:79], v78 offset:9216
	v_mov_b32_e32 v82, v161
	v_pk_mul_f32 v[46:47], v[46:47], v[82:83] op_sel_hi:[1,0]
	v_pk_mul_f32 v[44:45], v[44:45], v[82:83] op_sel_hi:[1,0]
	v_pk_mul_f32 v[42:43], v[42:43], v[82:83] op_sel_hi:[1,0]
	v_pk_mul_f32 v[40:41], v[40:41], v[82:83] op_sel_hi:[1,0]
	v_pk_mul_f32 v[38:39], v[38:39], v[82:83] op_sel_hi:[1,0]
	v_pk_mul_f32 v[36:37], v[36:37], v[82:83] op_sel_hi:[1,0]
	v_pk_mul_f32 v[34:35], v[34:35], v[82:83] op_sel_hi:[1,0]
	v_pk_mul_f32 v[32:33], v[32:33], v[82:83] op_sel_hi:[1,0]
	v_pk_mul_f32 v[14:15], v[14:15], v[82:83] op_sel_hi:[1,0]
	v_pk_mul_f32 v[12:13], v[12:13], v[82:83] op_sel_hi:[1,0]
	v_pk_mul_f32 v[10:11], v[10:11], v[82:83] op_sel_hi:[1,0]
	v_pk_mul_f32 v[8:9], v[8:9], v[82:83] op_sel_hi:[1,0]
	v_pk_mul_f32 v[6:7], v[6:7], v[82:83] op_sel_hi:[1,0]
	v_pk_mul_f32 v[4:5], v[4:5], v[82:83] op_sel_hi:[1,0]
	v_pk_mul_f32 v[2:3], v[2:3], v[82:83] op_sel_hi:[1,0]
	v_pk_mul_f32 v[0:1], v[0:1], v[82:83] op_sel_hi:[1,0]
	v_pk_add_f32 v[82:83], v[90:91], v[126:127]
	s_waitcnt lgkmcnt(2)
	v_mfma_f32_32x32x16_bf16 v[48:63], v[72:75], v[64:67], v[48:63]
	v_add_f32_e64 v82, v106, v82
	v_add_f32_e64 v83, v107, v83
	v_cvt_pk_bf16_f32 v80, v102, v88
	v_lshl_add_u32 v88, v177, 1, v194
	v_add_f32_e64 v82, v122, v82
	v_add_f32_e64 v83, v123, v83
	v_pk_mul_f32 v[18:19], v[18:19], v[160:161] op_sel_hi:[1,0]
	v_pk_add_f32 v[82:83], v[222:223], v[82:83]
	v_pk_mul_f32 v[16:17], v[16:17], v[160:161] op_sel_hi:[1,0]
	v_pk_add_f32 v[82:83], v[92:93], v[82:83]
	v_mfma_f32_32x32x16_bf16 v[32:47], v[72:75], v[68:71], v[32:47]
	v_add_f32_e64 v82, v108, v82
	v_add_f32_e64 v83, v109, v83
	v_cvt_pk_bf16_f32 v81, v120, v90
	v_lshl_add_u32 v102, v176, 1, v194
	v_add_f32_e64 v82, v124, v82
	v_add_f32_e64 v83, v125, v83
	v_lshl_add_u32 v113, v175, 1, v195
	v_pk_add_f32 v[82:83], v[224:225], v[82:83]
	v_lshl_add_u32 v114, v174, 1, v195
	v_pk_add_f32 v[82:83], v[94:95], v[82:83]
	s_waitcnt lgkmcnt(0)
; DI void attn_pass_da(const bfr* __restrict__ P, int b, int tq_wave, int qcol, int kcol, int vcol, int key0, int nkt, char* smem, f32x16 (&o0)[2], f32x16 (&o1)[2]) {
;     ...
;   for (int kt = 0; kt < nkt; ++kt) {
;     bfr* sK = sbase + (kt & 1) * 9216;
;     bfr* sV = sK + 64 * 72;
;     { int c = gt, row = c >> 3, kc = c & 7; *(u32x4*)(sK + row * KP + kc * 8) = kreg[0]; }
;     for (int i = 0; i < 1; ++i) {
;       int c = gt, row = c >> 3, kc = c & 7;
;       unsigned wds[4] = {vreg[i].x, vreg[i].y, vreg[i].z, vreg[i].w};
; #pragma unroll
;       for (int e = 0; e < 4; ++e) {
;         sV[(kc * 8 + 2 * e) * 72 + (row ^ (kc << 3))] = (bfr)(wds[e] & 0xffffu);
;         sV[(kc * 8 + 2 * e + 1) * 72 + (row ^ (kc << 3))] = (bfr)(wds[e] >> 16);
;       }
;     }
;     __syncthreads();
;     if (kt + 1 < nkt) {
;       const bfr* Pn = Pb + (size_t)(kt + 1) * 64 * PW;
;       { int c = gt, row = c >> 3, kc = c & 7; kreg[0] = *(const u32x4*)(Pn + (size_t)row * PW + kcol + kc * 8); vreg[0] = *(const u32x4*)(Pn + (size_t)row * PW + vcol + kc * 8); }
;     }
;     f32x16 s0[2], s1[2];
; #pragma unroll
;     for (int t2 = 0; t2 < 2; ++t2) {
; #pragma unroll
;     ...
;     for (int t2 = 0; t2 < 2; ++t2)
; #pragma unroll
;       for (int j = 0; j < 2; ++j) {
;         u32x4 pk0, pk1;
;         pk0.x = pack2(s0[t2][8 * j + 0], s0[t2][8 * j + 1]); pk0.y = pack2(s0[t2][8 * j + 2], s0[t2][8 * j + 3]);
;         pk0.z = pack2(s0[t2][8 * j + 4], s0[t2][8 * j + 5]); pk0.w = pack2(s0[t2][8 * j + 6], s0[t2][8 * j + 7]);
;         pk1.x = pack2(s1[t2][8 * j + 0], s1[t2][8 * j + 1]); pk1.y = pack2(s1[t2][8 * j + 2], s1[t2][8 * j + 3]);
;         pk1.z = pack2(s1[t2][8 * j + 4], s1[t2][8 * j + 5]); pk1.w = pack2(s1[t2][8 * j + 6], s1[t2][8 * j + 7]);
;         const bf16x8 pf0 = __builtin_bit_cast(bf16x8, pk0), pf1 = __builtin_bit_cast(bf16x8, pk1);
; #pragma unroll
;         for (int dt = 0; dt < 2; ++dt) {
;           const int vsw = (((dt * 32 + r) >> 3) & 7) << 3;
;           const bfr* vrow = sV + (dt * 32 + r) * 72;
;           s16x4 lo = *(const s16x4*)(vrow + ((t2 * 32 + 16 * j + 4 * h) ^ vsw));
;           s16x4 hi = *(const s16x4*)(vrow + ((t2 * 32 + 16 * j + 4 * h + 8) ^ vsw));
;           bf16x8 vf = __builtin_shufflevector(lo, hi, 0, 1, 2, 3, 4, 5, 6, 7);
;           acc0[dt] = MFMA32(vf, pf0, acc0[dt]);
;           acc1[dt] = MFMA32(vf, pf1, acc1[dt]);
;         }
	v_mfma_f32_32x32x16_bf16 v[16:31], v[76:79], v[64:67], v[16:31]
	v_add_f32_e64 v84, v110, v82
	v_add_f32_e64 v85, v111, v83
	v_cvt_pk_bf16_f32 v82, v122, v92
	v_cvt_pk_bf16_f32 v83, v124, v94
	v_cvt_pk_bf16_f32 v64, v103, v89
	v_cvt_pk_bf16_f32 v65, v121, v91
	v_cvt_pk_bf16_f32 v66, v123, v93
	v_cvt_pk_bf16_f32 v67, v125, v95
	v_mfma_f32_32x32x16_bf16 v[0:15], v[76:79], v[68:71], v[0:15]
	ds_read_b64 v[68:69], v88 offset:9216
	ds_read_b64 v[70:71], v102 offset:9216
	v_lshl_add_u32 v115, v173, 1, v194
	v_lshl_add_u32 v116, v172, 1, v195
	v_lshl_add_u32 v117, v171, 1, v195
	v_lshl_add_u32 v120, v169, 1, v194
	v_lshl_add_u32 v192, v170, 1, v194
	v_lshl_add_u32 v193, v168, 1, v195
	s_waitcnt lgkmcnt(0)
	v_mfma_f32_32x32x16_bf16 v[48:63], v[68:71], v[80:83], v[48:63]
	v_lshl_add_u32 v194, v167, 1, v195
	v_fma_f32 v156, v156, v160, v84
	v_fma_f32 v157, v157, v161, v85
	v_mfma_f32_32x32x16_bf16 v[32:47], v[68:71], v[64:67], v[32:47]
	ds_read_b64 v[68:69], v113 offset:9216
	ds_read_b64 v[70:71], v114 offset:9216
	s_waitcnt lgkmcnt(0)
	v_mfma_f32_32x32x16_bf16 v[16:31], v[68:71], v[80:83], v[16:31]
	v_mfma_f32_32x32x16_bf16 v[0:15], v[68:71], v[64:67], v[0:15]
	v_cvt_pk_bf16_f32 v64, v212, v96
	v_cvt_pk_bf16_f32 v65, v214, v98
	v_cvt_pk_bf16_f32 v66, v216, v100
	v_cvt_pk_bf16_f32 v67, v218, v86
	v_cvt_pk_bf16_f32 v68, v213, v97
	v_cvt_pk_bf16_f32 v69, v215, v99
	v_cvt_pk_bf16_f32 v70, v217, v101
	v_cvt_pk_bf16_f32 v71, v219, v87
	ds_read_b64 v[72:73], v112 offset:9280
	ds_read_b64 v[74:75], v115 offset:9216
	s_waitcnt lgkmcnt(0)
	v_mfma_f32_32x32x16_bf16 v[48:63], v[72:75], v[64:67], v[48:63]
	v_mfma_f32_32x32x16_bf16 v[32:47], v[72:75], v[68:71], v[32:47]
	ds_read_b64 v[72:73], v116 offset:9216
	ds_read_b64 v[74:75], v117 offset:9216
	s_waitcnt lgkmcnt(0)
	v_mfma_f32_32x32x16_bf16 v[16:31], v[72:75], v[64:67], v[16:31]
	v_cvt_pk_bf16_f32 v64, v118, v104
	v_cvt_pk_bf16_f32 v65, v220, v106
	v_cvt_pk_bf16_f32 v66, v222, v108
	v_cvt_pk_bf16_f32 v67, v224, v110
	v_mfma_f32_32x32x16_bf16 v[0:15], v[72:75], v[68:71], v[0:15]
	v_cvt_pk_bf16_f32 v68, v119, v105
	v_cvt_pk_bf16_f32 v69, v221, v107
	v_cvt_pk_bf16_f32 v70, v223, v109
	v_cvt_pk_bf16_f32 v71, v225, v111
	ds_read_b64 v[72:73], v120 offset:9216
	ds_read_b64 v[74:75], v192 offset:9216
	s_waitcnt lgkmcnt(0)
	v_mfma_f32_32x32x16_bf16 v[48:63], v[72:75], v[64:67], v[48:63]
	v_mfma_f32_32x32x16_bf16 v[32:47], v[72:75], v[68:71], v[32:47]
	ds_read_b64 v[72:73], v193 offset:9216
	ds_read_b64 v[74:75], v194 offset:9216
	s_waitcnt lgkmcnt(0)
	v_mfma_f32_32x32x16_bf16 v[16:31], v[72:75], v[64:67], v[16:31]
	v_mfma_f32_32x32x16_bf16 v[0:15], v[72:75], v[68:71], v[0:15]
	s_cbranch_scc1 .LBB0_421
	v_add3_u32 v64, 0, v206, v152
	s_waitcnt vmcnt(1)
	ds_write_b128 v64, v[148:151] offset:18432
	v_add3_u32 v64, 0, v207, v208
	v_add3_u32 v65, 0, v208, v207
	s_waitcnt vmcnt(0)
	ds_write_b16 v64, v144 offset:27648
	ds_write_b16_d16_hi v65, v144 offset:27792
	ds_write_b16 v64, v145 offset:27936
	ds_write_b16_d16_hi v65, v145 offset:28080
	ds_write_b16 v64, v146 offset:28224
	ds_write_b16_d16_hi v65, v146 offset:28368
	ds_write_b16 v64, v147 offset:28512
	ds_write_b16_d16_hi v65, v147 offset:28656
	v_add_u32_e32 v144, 0, v205
	v_add_u32_e32 v102, v144, v204
	s_waitcnt lgkmcnt(0)
	s_barrier
	ds_read_b128 v[64:67], v102 offset:18432
	ds_read_b128 v[96:99], v102 offset:18464
	s_waitcnt lgkmcnt(1)
	v_mfma_f32_32x32x16_bf16 v[64:79], v[64:67], v[140:143], 0
	ds_read_b128 v[80:83], v102 offset:18496
	v_readlane_b32 s10, v203, 16
	v_readlane_b32 s11, v203, 48
	v_add_u32_e32 v145, 0x1200, v144
	v_mov_b32_e32 v100, s10
	v_mov_b32_e32 v101, s11
	v_pk_add_f32 v[100:101], s[8:9], v[100:101]
	s_mov_b32 s10, 0x3fb8aa3b
	v_add_f32_e32 v146, v100, v101
	v_mul_f32_e32 v104, 0x3fb8aa3b, v146
	v_fma_f32 v105, v146, s10, -v104
	v_rndne_f32_e32 v106, v104
	s_waitcnt lgkmcnt(1)
	v_mfma_f32_32x32x16_bf16 v[64:79], v[96:99], v[132:135], v[64:79]
	v_fmac_f32_e32 v105, 0x32a5705f, v146
	v_sub_f32_e32 v96, v104, v106
	v_add_u32_e32 v147, v145, v204
	v_add_f32_e32 v104, v96, v105
	ds_read_b128 v[96:99], v147 offset:18432
	ds_read_b128 v[100:103], v102 offset:18528
	ds_read_b128 v[112:115], v147 offset:18496
	s_waitcnt lgkmcnt(3)
	v_mfma_f32_32x32x16_bf16 v[80:95], v[80:83], v[136:139], 0
	v_readlane_b32 s8, v202, 16
	v_readlane_b32 s9, v202, 48
	s_mov_b32 s11, 0xc2ce8ed0
	v_mov_b32_e32 v116, s8
	v_mov_b32_e32 v117, s9
	v_pk_add_f32 v[116:117], s[6:7], v[116:117]
	v_cmp_ngt_f32_e32 vcc, s11, v146
	s_waitcnt lgkmcnt(1)
	v_mfma_f32_32x32x16_bf16 v[80:95], v[100:103], v[128:131], v[80:95]
	v_exp_f32_e32 v100, v104
	v_cvt_i32_f32_e32 v101, v106
	v_add_f32_e32 v149, v116, v117
	v_mul_f32_e32 v150, 0x3fb8aa3b, v149
	v_rndne_f32_e32 v151, v150
	v_ldexp_f32 v148, v100, v101
	s_mov_b32 s6, 0x42b17218
	s_waitcnt lgkmcnt(0)
	v_mfma_f32_32x32x16_bf16 v[112:127], v[112:115], v[136:139], 0
	v_fma_f32 v136, v149, s10, -v150
	v_fmac_f32_e32 v136, 0x32a5705f, v149
	v_sub_f32_e32 v137, v150, v151
	v_add_f32_e32 v136, v137, v136
	v_exp_f32_e32 v150, v136
	ds_read_b128 v[136:139], v147 offset:18528
	v_readlane_b32 s8, v253, 28
	v_mfma_f32_32x32x16_bf16 v[96:111], v[96:99], v[140:143], 0
	ds_read_b128 v[140:143], v147 offset:18464
	v_readlane_b32 s9, v253, 29
	s_waitcnt lgkmcnt(0)
; DI void attn_pass_da(const bfr* __restrict__ P, int b, int tq_wave, int qcol, int kcol, int vcol, int key0, int nkt, char* smem, f32x16 (&o0)[2], f32x16 (&o1)[2]) {
;     ...
;     float mx0 = s0[0][0], mx1 = s1[0][0];
; #pragma unroll
;     for (int i = 0; i < 16; ++i) { mx0 = fmaxf(mx0, fmaxf(s0[0][i], s0[1][i])); mx1 = fmaxf(mx1, fmaxf(s1[0][i], s1[1][i])); }
;     mx0 = fmaxf(mx0, __shfl_xor(mx0, 32)); mx1 = fmaxf(mx1, __shfl_xor(mx1, 32));
;     const float mn0 = fmaxf(m0, mx0), mn1 = fmaxf(m1, mx1);
;     const float al0 = __builtin_amdgcn_exp2f(m0 - mn0), al1 = __builtin_amdgcn_exp2f(m1 - mn1);
;     m0 = mn0; m1 = mn1;
;     float ps0 = 0.f, ps1 = 0.f;
; #pragma unroll
;     for (int i = 0; i < 16; ++i) {
;       s0[0][i] = __builtin_amdgcn_exp2f(s0[0][i] - mn0); ps0 += s0[0][i];
;       s0[1][i] = __builtin_amdgcn_exp2f(s0[1][i] - mn0); ps0 += s0[1][i];
;       s1[0][i] = __builtin_amdgcn_exp2f(s1[0][i] - mn1); ps1 += s1[0][i];
;       s1[1][i] = __builtin_amdgcn_exp2f(s1[1][i] - mn1); ps1 += s1[1][i];
;     }
; DN void da_item(const Params& p, int l, int b, int hd, int tq0, int key0, int nkt, char* smem) {
;     ...
;   float lam_init = 0.8f - 0.6f * expf(-0.3f * (float)l);
;   float lam = expf(d01) - expf(d23) + lam_init;
	v_mfma_f32_32x32x16_bf16 v[96:111], v[140:143], v[132:135], v[96:111]
	v_max_f32_e32 v134, v82, v82
	v_max_f32_e32 v135, v67, v67
	v_cvt_i32_f32_e32 v132, v151
	v_cndmask_b32_e32 v133, 0, v148, vcc
	v_cmp_nlt_f32_e32 vcc, s6, v146
	v_ldexp_f32 v132, v150, v132
	v_mfma_f32_32x32x16_bf16 v[112:127], v[136:139], v[128:131], v[112:127]
	s_nop 4
	v_max_f32_e32 v128, v97, v97
	v_max_f32_e32 v129, v65, v65
	v_max_f32_e32 v128, v129, v128
	v_max_f32_e32 v130, v81, v81
	v_max_f32_e32 v131, v66, v66
	v_max3_f32 v128, v64, v96, v128
	v_cndmask_b32_e32 v133, v201, v133, vcc
	v_max_f32_e32 v129, v113, v113
	v_max_f32_e32 v129, v130, v129
	v_max_f32_e32 v130, v98, v98
	v_max_f32_e32 v130, v131, v130
	v_max_f32_e32 v131, v114, v114
	v_max_f32_e32 v131, v134, v131
	v_max_f32_e32 v134, v99, v99
	v_max_f32_e32 v134, v135, v134
	v_max3_f32 v128, v128, v130, v134
	v_max_f32_e32 v130, v115, v115
	v_max_f32_e32 v134, v83, v83
	v_max3_f32 v129, v80, v112, v129
	v_max_f32_e32 v130, v134, v130
	v_max3_f32 v129, v129, v131, v130
	v_max_f32_e32 v130, v100, v100
	v_max_f32_e32 v131, v68, v68
	v_max_f32_e32 v130, v131, v130
	v_max_f32_e32 v131, v116, v116
	v_max_f32_e32 v134, v84, v84
	v_max_f32_e32 v131, v134, v131
	v_max_f32_e32 v134, v101, v101
	v_max_f32_e32 v135, v69, v69
	v_max_f32_e32 v134, v135, v134
	v_max3_f32 v128, v128, v130, v134
	v_max_f32_e32 v130, v117, v117
	v_max_f32_e32 v134, v85, v85
	v_max_f32_e32 v130, v134, v130
	v_max3_f32 v129, v129, v131, v130
	v_max_f32_e32 v130, v102, v102
	v_max_f32_e32 v131, v70, v70
	v_max_f32_e32 v130, v131, v130
	v_max_f32_e32 v131, v118, v118
	v_max_f32_e32 v134, v86, v86
	v_max_f32_e32 v131, v134, v131
	v_max_f32_e32 v134, v103, v103
	v_max_f32_e32 v135, v71, v71
	v_max_f32_e32 v134, v135, v134
	v_max3_f32 v128, v128, v130, v134
	v_max_f32_e32 v130, v119, v119
	v_max_f32_e32 v134, v87, v87
	v_max_f32_e32 v130, v134, v130
	v_max3_f32 v129, v129, v131, v130
	v_max_f32_e32 v130, v104, v104
	v_max_f32_e32 v131, v72, v72
	v_max_f32_e32 v130, v131, v130
	v_max_f32_e32 v131, v120, v120
	v_max_f32_e32 v134, v88, v88
	v_max_f32_e32 v131, v134, v131
	v_max_f32_e32 v134, v105, v105
	v_max_f32_e32 v135, v73, v73
	v_max_f32_e32 v134, v135, v134
	v_max3_f32 v128, v128, v130, v134
	v_max_f32_e32 v130, v121, v121
	v_max_f32_e32 v134, v89, v89
	v_max_f32_e32 v130, v134, v130
	v_max3_f32 v129, v129, v131, v130
	v_max_f32_e32 v130, v106, v106
	v_max_f32_e32 v131, v74, v74
	v_max_f32_e32 v130, v131, v130
	v_max_f32_e32 v131, v122, v122
	v_max_f32_e32 v134, v90, v90
	v_max_f32_e32 v131, v134, v131
	v_max_f32_e32 v134, v107, v107
	v_max_f32_e32 v135, v75, v75
	v_max_f32_e32 v134, v135, v134
	v_max3_f32 v128, v128, v130, v134
	v_max_f32_e32 v130, v123, v123
	v_max_f32_e32 v134, v91, v91
	v_max_f32_e32 v130, v134, v130
	v_max3_f32 v129, v129, v131, v130
	v_max_f32_e32 v130, v108, v108
	v_max_f32_e32 v131, v76, v76
	v_max_f32_e32 v130, v131, v130
	v_max_f32_e32 v131, v124, v124
	v_max_f32_e32 v134, v92, v92
	v_max_f32_e32 v131, v134, v131
	v_max_f32_e32 v134, v109, v109
	v_max_f32_e32 v135, v77, v77
	v_max_f32_e32 v134, v135, v134
	v_max3_f32 v128, v128, v130, v134
	v_max_f32_e32 v130, v125, v125
	v_max_f32_e32 v134, v93, v93
	v_max_f32_e32 v130, v134, v130
	v_max3_f32 v129, v129, v131, v130
	v_max_f32_e32 v130, v110, v110
	v_max_f32_e32 v131, v78, v78
	v_max_f32_e32 v130, v131, v130
	v_max_f32_e32 v131, v126, v126
	v_max_f32_e32 v134, v94, v94
	v_max_f32_e32 v131, v134, v131
	v_max_f32_e32 v134, v111, v111
	v_max_f32_e32 v135, v79, v79
	v_max_f32_e32 v134, v135, v134
	v_max3_f32 v128, v128, v130, v134
	v_max_f32_e32 v130, v127, v127
	v_max_f32_e32 v134, v95, v95
	v_max_f32_e32 v130, v134, v130
	v_max3_f32 v130, v129, v131, v130
	ds_bpermute_b32 v131, v166, v128
	ds_bpermute_b32 v134, v166, v130
	v_cmp_ngt_f32_e32 vcc, s11, v149
	s_waitcnt lgkmcnt(0)
	v_max3_f32 v150, v210, v130, v134
	v_cndmask_b32_e32 v132, 0, v132, vcc
	v_cmp_nlt_f32_e32 vcc, s6, v149
	v_max3_f32 v149, v209, v128, v131
	v_sub_f32_e32 v64, v64, v149
	v_exp_f32_e32 v148, v64
	v_sub_f32_e32 v64, v96, v149
	v_exp_f32_e32 v131, v64
	v_sub_f32_e32 v64, v80, v150
	v_exp_f32_e32 v151, v64
	v_sub_f32_e32 v64, v112, v150
	v_exp_f32_e32 v96, v64
	v_sub_f32_e32 v64, v65, v149
	v_exp_f32_e32 v152, v64
	v_sub_f32_e32 v64, v97, v149
	v_exp_f32_e32 v112, v64
	v_sub_f32_e32 v64, v81, v150
	v_exp_f32_e32 v158, v64
	v_sub_f32_e32 v64, v113, v150
	v_exp_f32_e32 v97, v64
	v_sub_f32_e32 v64, v66, v149
	v_exp_f32_e32 v143, v64
	v_sub_f32_e32 v64, v98, v149
	v_exp_f32_e32 v113, v64
	v_sub_f32_e32 v64, v82, v150
	v_exp_f32_e32 v146, v64
	v_sub_f32_e32 v64, v114, v150
	v_exp_f32_e32 v98, v64
	v_sub_f32_e32 v64, v67, v149
	v_exp_f32_e32 v147, v64
	v_sub_f32_e32 v64, v99, v149
	v_exp_f32_e32 v114, v64
	v_sub_f32_e32 v64, v83, v150
	v_exp_f32_e32 v138, v64
	v_sub_f32_e32 v64, v115, v150
	v_exp_f32_e32 v99, v64
	v_sub_f32_e32 v64, v68, v149
	v_exp_f32_e32 v139, v64
	v_sub_f32_e32 v64, v100, v149
	v_exp_f32_e32 v115, v64
	v_sub_f32_e32 v64, v84, v150
	v_exp_f32_e32 v140, v64
	v_sub_f32_e32 v64, v116, v150
	v_exp_f32_e32 v100, v64
	v_sub_f32_e32 v64, v69, v149
	v_exp_f32_e32 v141, v64
	v_sub_f32_e32 v64, v101, v149
	v_exp_f32_e32 v116, v64
	v_sub_f32_e32 v64, v85, v150
	v_exp_f32_e32 v142, v64
	v_sub_f32_e32 v64, v117, v150
	v_exp_f32_e32 v101, v64
	v_sub_f32_e32 v64, v70, v149
	v_exp_f32_e32 v134, v64
	v_sub_f32_e32 v64, v102, v149
	v_cndmask_b32_e32 v129, v201, v132, vcc
	v_exp_f32_e32 v132, v64
	v_sub_f32_e32 v64, v86, v150
	v_exp_f32_e32 v135, v64
	v_sub_f32_e32 v64, v118, v150
	v_exp_f32_e32 v117, v64
	v_sub_f32_e32 v64, v71, v149
	v_exp_f32_e32 v136, v64
	v_sub_f32_e32 v64, v103, v149
; #define MFMA32(a, b, c) __builtin_amdgcn_mfma_f32_32x32x16_bf16((a), (b), (c), 0, 0, 0)
; DI unsigned pack2(float a, float b) { unsigned r; asm volatile("v_cvt_pk_bf16_f32 %0, %1, %2" : "=v"(r) : "v"(a), "v"(b)); return r; }
; DI void attn_pass_da(const bfr* __restrict__ P, int b, int tq_wave, int qcol, int kcol, int vcol, int key0, int nkt, char* smem, f32x16 (&o0)[2], f32x16 (&o1)[2]) {
;     ...
;     const float mn0 = fmaxf(m0, mx0), mn1 = fmaxf(m1, mx1);
;     const float al0 = __builtin_amdgcn_exp2f(m0 - mn0), al1 = __builtin_amdgcn_exp2f(m1 - mn1);
;     m0 = mn0; m1 = mn1;
;     float ps0 = 0.f, ps1 = 0.f;
; #pragma unroll
;     for (int i = 0; i < 16; ++i) {
;       s0[0][i] = __builtin_amdgcn_exp2f(s0[0][i] - mn0); ps0 += s0[0][i];
;       s0[1][i] = __builtin_amdgcn_exp2f(s0[1][i] - mn0); ps0 += s0[1][i];
;       s1[0][i] = __builtin_amdgcn_exp2f(s1[0][i] - mn1); ps1 += s1[0][i];
;       s1[1][i] = __builtin_amdgcn_exp2f(s1[1][i] - mn1); ps1 += s1[1][i];
;     }
;     l0 = l0 * al0 + ps0; l1 = l1 * al1 + ps1;
; #pragma unroll
;     for (int i = 0; i < 16; ++i) { acc0[0][i] *= al0; acc0[1][i] *= al0; acc1[0][i] *= al1; acc1[1][i] *= al1; }
; #pragma unroll
;     for (int t2 = 0; t2 < 2; ++t2)
; #pragma unroll
;       for (int j = 0; j < 2; ++j) {
;         u32x4 pk0, pk1;
;         pk0.x = pack2(s0[t2][8 * j + 0], s0[t2][8 * j + 1]); pk0.y = pack2(s0[t2][8 * j + 2], s0[t2][8 * j + 3]);
;         pk0.z = pack2(s0[t2][8 * j + 4], s0[t2][8 * j + 5]); pk0.w = pack2(s0[t2][8 * j + 6], s0[t2][8 * j + 7]);
;         pk1.x = pack2(s1[t2][8 * j + 0], s1[t2][8 * j + 1]); pk1.y = pack2(s1[t2][8 * j + 2], s1[t2][8 * j + 3]);
;         pk1.z = pack2(s1[t2][8 * j + 4], s1[t2][8 * j + 5]); pk1.w = pack2(s1[t2][8 * j + 6], s1[t2][8 * j + 7]);
;         const bf16x8 pf0 = __builtin_bit_cast(bf16x8, pk0), pf1 = __builtin_bit_cast(bf16x8, pk1);
; #pragma unroll
;         for (int dt = 0; dt < 2; ++dt) {
;           const int vsw = (((dt * 32 + r) >> 3) & 7) << 3;
;           const bfr* vrow = sV + (dt * 32 + r) * 72;
;           s16x4 lo = *(const s16x4*)(vrow + ((t2 * 32 + 16 * j + 4 * h) ^ vsw));
;           s16x4 hi = *(const s16x4*)(vrow + ((t2 * 32 + 16 * j + 4 * h + 8) ^ vsw));
;           bf16x8 vf = __builtin_shufflevector(lo, hi, 0, 1, 2, 3, 4, 5, 6, 7);
;           acc0[dt] = MFMA32(vf, pf0, acc0[dt]);
;           acc1[dt] = MFMA32(vf, pf1, acc1[dt]);
;         }
	v_sub_f32_e32 v129, v133, v129
	v_exp_f32_e32 v133, v64
	v_sub_f32_e32 v64, v87, v150
	v_exp_f32_e32 v137, v64
	v_sub_f32_e32 v64, v119, v150
	v_exp_f32_e32 v102, v64
	v_sub_f32_e32 v64, v72, v149
	v_exp_f32_e32 v103, v64
	v_sub_f32_e32 v64, v104, v149
	v_exp_f32_e32 v71, v64
	v_sub_f32_e32 v64, v88, v150
	v_exp_f32_e32 v104, v64
	v_sub_f32_e32 v64, v120, v150
	v_exp_f32_e32 v70, v64
	v_sub_f32_e32 v64, v73, v149
	v_exp_f32_e32 v118, v64
	v_sub_f32_e32 v64, v105, v149
	v_exp_f32_e32 v73, v64
	v_sub_f32_e32 v64, v89, v150
	v_exp_f32_e32 v105, v64
	v_sub_f32_e32 v64, v121, v150
	v_exp_f32_e32 v72, v64
	v_sub_f32_e32 v64, v74, v149
	v_exp_f32_e32 v119, v64
	v_sub_f32_e32 v64, v106, v149
	v_exp_f32_e32 v81, v64
	v_sub_f32_e32 v64, v90, v150
	v_exp_f32_e32 v89, v64
	v_sub_f32_e32 v64, v122, v150
	v_exp_f32_e32 v80, v64
	v_sub_f32_e32 v64, v75, v149
	v_exp_f32_e32 v90, v64
	v_sub_f32_e32 v64, v107, v149
	v_exp_f32_e32 v87, v64
	v_sub_f32_e32 v64, v91, v150
	v_exp_f32_e32 v91, v64
	v_sub_f32_e32 v64, v123, v150
	v_exp_f32_e32 v86, v64
	v_sub_f32_e32 v64, v76, v149
	v_exp_f32_e32 v74, v64
	v_sub_f32_e32 v64, v108, v149
	v_exp_f32_e32 v75, v64
	v_sub_f32_e32 v64, v92, v150
	v_exp_f32_e32 v76, v64
	v_sub_f32_e32 v64, v124, v150
	v_exp_f32_e32 v82, v64
	v_sub_f32_e32 v64, v77, v149
	v_exp_f32_e32 v77, v64
	v_sub_f32_e32 v64, v109, v149
	v_exp_f32_e32 v83, v64
	v_sub_f32_e32 v64, v93, v150
	v_exp_f32_e32 v84, v64
	v_sub_f32_e32 v64, v125, v150
	v_exp_f32_e32 v85, v64
	v_sub_f32_e32 v64, v78, v149
	v_exp_f32_e32 v78, v64
	v_sub_f32_e32 v64, v110, v149
	v_exp_f32_e32 v88, v64
	v_sub_f32_e32 v64, v94, v150
	v_exp_f32_e32 v66, v64
	v_sub_f32_e32 v64, v126, v150
	v_exp_f32_e32 v67, v64
	v_sub_f32_e32 v64, v79, v149
	v_exp_f32_e32 v68, v64
	v_sub_f32_e32 v64, v111, v149
	v_lshl_add_u32 v79, v181, 1, v144
	v_lshl_add_u32 v110, v180, 1, v144
	v_lshl_add_u32 v124, v179, 1, v145
	v_lshl_add_u32 v126, v178, 1, v145
	v_exp_f32_e32 v69, v64
	v_sub_f32_e32 v64, v95, v150
	v_sub_f32_e32 v65, v127, v150
	v_cvt_pk_bf16_f32 v92, v148, v152
	v_cvt_pk_bf16_f32 v93, v143, v147
	v_cvt_pk_bf16_f32 v94, v139, v141
	v_cvt_pk_bf16_f32 v95, v134, v136
	v_cvt_pk_bf16_f32 v106, v151, v158
	v_cvt_pk_bf16_f32 v107, v146, v138
	v_cvt_pk_bf16_f32 v108, v140, v142
	v_cvt_pk_bf16_f32 v109, v135, v137
	ds_read_b64 v[120:121], v79 offset:27648
	ds_read_b64 v[122:123], v110 offset:27648
	ds_read_b64 v[124:125], v124 offset:27648
	ds_read_b64 v[126:127], v126 offset:27648
	v_sub_f32_e32 v128, v209, v149
	v_exp_f32_e32 v130, v128
	v_sub_f32_e32 v128, v210, v150
	v_add_f32_e32 v111, 0, v151
	v_exp_f32_e32 v128, v128
	v_add_f32_e32 v110, 0, v148
	v_add_f32_e32 v111, v96, v111
	v_add_f32_e32 v110, v131, v110
	v_add_f32_e32 v111, v158, v111
	v_add_f32_e32 v110, v152, v110
	v_add_f32_e32 v111, v97, v111
	v_add_f32_e32 v110, v112, v110
	v_add_f32_e32 v111, v146, v111
	v_pk_mul_f32 v[46:47], v[46:47], v[128:129] op_sel_hi:[1,0]
	v_pk_mul_f32 v[44:45], v[44:45], v[128:129] op_sel_hi:[1,0]
	v_pk_mul_f32 v[42:43], v[42:43], v[128:129] op_sel_hi:[1,0]
	v_pk_mul_f32 v[40:41], v[40:41], v[128:129] op_sel_hi:[1,0]
	v_pk_mul_f32 v[38:39], v[38:39], v[128:129] op_sel_hi:[1,0]
	v_pk_mul_f32 v[36:37], v[36:37], v[128:129] op_sel_hi:[1,0]
	v_pk_mul_f32 v[34:35], v[34:35], v[128:129] op_sel_hi:[1,0]
	v_pk_mul_f32 v[32:33], v[32:33], v[128:129] op_sel_hi:[1,0]
	v_pk_mul_f32 v[14:15], v[14:15], v[128:129] op_sel_hi:[1,0]
	v_pk_mul_f32 v[12:13], v[12:13], v[128:129] op_sel_hi:[1,0]
	v_pk_mul_f32 v[10:11], v[10:11], v[128:129] op_sel_hi:[1,0]
	v_pk_mul_f32 v[8:9], v[8:9], v[128:129] op_sel_hi:[1,0]
	v_pk_mul_f32 v[6:7], v[6:7], v[128:129] op_sel_hi:[1,0]
	v_pk_mul_f32 v[4:5], v[4:5], v[128:129] op_sel_hi:[1,0]
	v_pk_mul_f32 v[2:3], v[2:3], v[128:129] op_sel_hi:[1,0]
	v_pk_mul_f32 v[0:1], v[0:1], v[128:129] op_sel_hi:[1,0]
	v_add_f32_e32 v110, v143, v110
	v_add_f32_e32 v111, v98, v111
	s_waitcnt lgkmcnt(2)
	v_mfma_f32_32x32x16_bf16 v[32:47], v[120:123], v[106:109], v[32:47]
	v_add_f32_e32 v110, v113, v110
	v_add_f32_e32 v110, v147, v110
	v_add_f32_e32 v110, v114, v110
	v_mul_f32_e64 v62, v62, v130
	v_mul_f32_e64 v63, v63, v130
	v_pk_mul_f32 v[60:61], v[60:61], v[130:131] op_sel_hi:[1,0]
	v_pk_mul_f32 v[58:59], v[58:59], v[130:131] op_sel_hi:[1,0]
	v_pk_mul_f32 v[56:57], v[56:57], v[130:131] op_sel_hi:[1,0]
	s_waitcnt lgkmcnt(0)
	v_mfma_f32_32x32x16_bf16 v[0:15], v[124:127], v[106:109], v[0:15]
	v_add_f32_e32 v106, v138, v111
	v_add_f32_e32 v106, v99, v106
	v_add_f32_e32 v106, v140, v106
	v_add_f32_e32 v107, v139, v110
	v_add_f32_e32 v106, v100, v106
	v_add_f32_e32 v107, v115, v107
	v_add_f32_e32 v106, v142, v106
	v_pk_mul_f32 v[54:55], v[54:55], v[130:131] op_sel_hi:[1,0]
	v_pk_mul_f32 v[52:53], v[52:53], v[130:131] op_sel_hi:[1,0]
	v_pk_mul_f32 v[50:51], v[50:51], v[130:131] op_sel_hi:[1,0]
	v_pk_mul_f32 v[48:49], v[48:49], v[130:131] op_sel_hi:[1,0]
	v_pk_mul_f32 v[30:31], v[30:31], v[130:131] op_sel_hi:[1,0]
	v_pk_mul_f32 v[28:29], v[28:29], v[130:131] op_sel_hi:[1,0]
	v_pk_mul_f32 v[26:27], v[26:27], v[130:131] op_sel_hi:[1,0]
	v_pk_mul_f32 v[24:25], v[24:25], v[130:131] op_sel_hi:[1,0]
	v_pk_mul_f32 v[22:23], v[22:23], v[130:131] op_sel_hi:[1,0]
	v_pk_mul_f32 v[20:21], v[20:21], v[130:131] op_sel_hi:[1,0]
	v_pk_mul_f32 v[18:19], v[18:19], v[130:131] op_sel_hi:[1,0]
	v_pk_mul_f32 v[16:17], v[16:17], v[130:131] op_sel_hi:[1,0]
	v_lshl_add_u32 v143, v177, 1, v144
	v_add_f32_e32 v107, v141, v107
	v_add_f32_e32 v111, v101, v106
	v_lshl_add_u32 v106, v175, 1, v145
	v_lshl_add_u32 v108, v174, 1, v145
	v_exp_f32_e32 v64, v64
	v_mfma_f32_32x32x16_bf16 v[48:63], v[120:123], v[92:95], v[48:63]
	v_add_f32_e32 v110, v116, v107
	v_add_f32_e32 v110, v134, v110
	v_add_f32_e32 v110, v132, v110
	v_add_f32_e32 v110, v136, v110
	v_add_f32_e32 v111, v135, v111
	v_add_f32_e32 v111, v117, v111
	v_exp_f32_e32 v65, v65
	v_mfma_f32_32x32x16_bf16 v[16:31], v[124:127], v[92:95], v[16:31]
	v_cvt_pk_bf16_f32 v92, v103, v118
	v_cvt_pk_bf16_f32 v93, v119, v90
	v_cvt_pk_bf16_f32 v94, v74, v77
	v_cvt_pk_bf16_f32 v95, v78, v68
	v_cvt_pk_bf16_f32 v120, v104, v105
	v_cvt_pk_bf16_f32 v121, v89, v91
	v_cvt_pk_bf16_f32 v122, v76, v84
	v_cvt_pk_bf16_f32 v123, v66, v64
	ds_read_b64 v[146:147], v143 offset:27648
	ds_read_b64 v[106:107], v106 offset:27648
	ds_read_b64 v[108:109], v108 offset:27648
	v_lshl_add_u32 v143, v176, 1, v144
	ds_read_b64 v[148:149], v143 offset:27648
	v_add_f32_e32 v124, v133, v110
	s_waitcnt lgkmcnt(0)
; DI int oidx(int i) { asm volatile("" : "+s"(i)); return i; }
; DI void attn_pass_da(const bfr* __restrict__ P, int b, int tq_wave, int qcol, int kcol, int vcol, int key0, int nkt, char* smem, f32x16 (&o0)[2], f32x16 (&o1)[2]) {
;     ...
;   l0 += __shfl_xor(l0, 32); l1 += __shfl_xor(l1, 32);
;   const float i0 = 1.f / l0, i1 = 1.f / l1;
; #pragma unroll
;   for (int i = 0; i < 16; ++i) { o0[0][i] = acc0[0][i] * i0; o0[1][i] = acc0[1][i] * i0; o1[0][i] = acc1[0][i] * i1; o1[1][i] = acc1[1][i] * i1; }
; DN void da_item(const Params& p, int l, int b, int hd, int tq0, int key0, int nkt, char* smem) {
;     ...
;   float ss = 0.f;
; #pragma unroll
;   for (int dt = 0; dt < 2; ++dt)
; #pragma unroll
;     for (int i = 0; i < 16; ++i) { float v = o0[dt][i] - lam * o1[dt][i]; o0[dt][i] = v; ss += v * v; }
;   ss += __shfl_xor(ss, 32);
;   float rstd = rsqrtf(ss * (1.f / 64.f) + 1e-6f) * (1.f - lam_init);
;   const float* sg = p.in[oidx(23)] + l * 64;
	v_mfma_f32_32x32x16_bf16 v[48:63], v[146:149], v[92:95], v[48:63]
	v_add_f32_e32 v125, v137, v111
	v_lshlrev_b32_e32 v152, 1, v154
	v_mfma_f32_32x32x16_bf16 v[16:31], v[106:109], v[92:95], v[16:31]
	v_cvt_pk_bf16_f32 v92, v131, v112
	v_cvt_pk_bf16_f32 v93, v113, v114
	v_cvt_pk_bf16_f32 v94, v115, v116
	v_cvt_pk_bf16_f32 v95, v132, v133
	v_cvt_pk_bf16_f32 v96, v96, v97
	v_cvt_pk_bf16_f32 v97, v98, v99
	v_cvt_pk_bf16_f32 v98, v100, v101
	v_add_f32_e32 v100, v103, v124
	v_add_f32_e32 v100, v71, v100
	v_cvt_pk_bf16_f32 v99, v117, v102
	ds_read_b64 v[110:111], v79 offset:27712
	v_lshl_add_u32 v79, v173, 1, v144
	v_add_f32_e32 v100, v118, v100
	ds_read_b64 v[112:113], v79 offset:27648
	v_add_f32_e32 v79, v102, v125
	v_add_f32_e32 v100, v73, v100
	v_add_f32_e32 v79, v104, v79
	v_add_f32_e32 v104, v119, v100
	v_lshl_add_u32 v100, v172, 1, v145
	v_lshl_add_u32 v102, v171, 1, v145
	ds_read_b64 v[100:101], v100 offset:27648
	ds_read_b64 v[102:103], v102 offset:27648
	v_add_f32_e32 v79, v70, v79
	v_add_f32_e32 v79, v105, v79
	v_add_f32_e32 v79, v72, v79
	v_add_f32_e32 v104, v81, v104
	v_add_f32_e32 v79, v89, v79
	v_add_f32_e32 v79, v80, v79
	v_add_f32_e32 v89, v90, v104
	v_add_f32_e32 v89, v87, v89
	v_add_f32_e32 v79, v91, v79
	v_add_f32_e32 v79, v86, v79
	v_add_f32_e32 v74, v74, v89
	s_waitcnt lgkmcnt(2)
	v_mfma_f32_32x32x16_bf16 v[48:63], v[110:113], v[92:95], v[48:63]
	v_cvt_pk_bf16_f32 v90, v71, v73
	v_cvt_pk_bf16_f32 v91, v81, v87
	v_add_f32_e32 v74, v75, v74
	v_add_f32_e32 v74, v77, v74
	v_add_f32_e32 v74, v83, v74
	v_add_f32_e32 v74, v78, v74
	v_add_f32_e32 v78, v88, v74
	s_waitcnt lgkmcnt(0)
	v_mfma_f32_32x32x16_bf16 v[16:31], v[100:103], v[92:95], v[16:31]
	v_cvt_pk_bf16_f32 v92, v75, v83
	v_add_f32_e32 v75, v76, v79
	v_add_f32_e32 v75, v82, v75
	v_add_f32_e32 v75, v84, v75
	v_add_f32_e32 v79, v85, v75
	v_add_f32_e32 v66, v66, v79
	v_cvt_pk_bf16_f32 v93, v88, v69
	v_mfma_f32_32x32x16_bf16 v[32:47], v[146:149], v[120:123], v[32:47]
	v_cvt_pk_bf16_f32 v70, v70, v72
	v_cvt_pk_bf16_f32 v71, v80, v86
	v_cvt_pk_bf16_f32 v72, v82, v85
	v_cvt_pk_bf16_f32 v73, v67, v65
	v_add_f32_e32 v66, v67, v66
	v_add_f32_e32 v67, v68, v78
	v_add_f32_e32 v67, v69, v67
	v_mfma_f32_32x32x16_bf16 v[0:15], v[106:109], v[120:123], v[0:15]
	v_fmac_f32_e32 v67, v156, v130
	ds_bpermute_b32 v68, v166, v67
	v_lshl_add_u32 v80, v169, 1, v144
	v_lshl_add_u32 v74, v168, 1, v145
	v_lshl_add_u32 v76, v167, 1, v145
	ds_read_b64 v[104:105], v80 offset:27648
	ds_read_b64 v[74:75], v74 offset:27648
	ds_read_b64 v[76:77], v76 offset:27648
	v_lshl_add_u32 v80, v170, 1, v144
	v_add_f32_e32 v64, v64, v66
	ds_read_b64 v[106:107], v80 offset:27648
	v_add_f32_e32 v65, v65, v64
	v_mfma_f32_32x32x16_bf16 v[32:47], v[110:113], v[96:99], v[32:47]
	v_fmac_f32_e32 v65, v157, v128
	s_waitcnt lgkmcnt(4)
	v_add_f32_e32 v66, v67, v68
	ds_bpermute_b32 v67, v166, v65
	v_div_scale_f32 v68, s[6:7], v66, v66, 1.0
	v_rcp_f32_e32 v69, v68
	v_add_f32_e32 v64, v155, v129
	v_mfma_f32_32x32x16_bf16 v[0:15], v[100:103], v[96:99], v[0:15]
	s_waitcnt lgkmcnt(0)
	v_add_f32_e32 v65, v65, v67
	v_fma_f32 v67, -v68, v69, 1.0
	v_fmac_f32_e32 v69, v67, v69
	v_div_scale_f32 v67, vcc, 1.0, v66, 1.0
	v_mfma_f32_32x32x16_bf16 v[32:47], v[104:107], v[70:73], v[32:47]
	v_mfma_f32_32x32x16_bf16 v[0:15], v[74:77], v[70:73], v[0:15]
	v_mul_f32_e32 v70, v67, v69
	v_fma_f32 v71, -v68, v70, v67
	v_fmac_f32_e32 v70, v71, v69
	v_fma_f32 v67, -v68, v70, v67
	v_div_scale_f32 v68, s[6:7], v65, v65, 1.0
	v_rcp_f32_e32 v71, v68
	v_div_fmas_f32 v67, v67, v69, v70
	v_div_fixup_f32 v66, v67, v66, 1.0
	v_mfma_f32_32x32x16_bf16 v[48:63], v[104:107], v[90:93], v[48:63]
	v_fma_f32 v67, -v68, v71, 1.0
	v_fmac_f32_e32 v71, v67, v71
	v_div_scale_f32 v67, vcc, 1.0, v65, 1.0
	v_mul_f32_e32 v69, v67, v71
	v_fma_f32 v70, -v68, v69, v67
	v_fmac_f32_e32 v69, v70, v71
	v_fma_f32 v67, -v68, v69, v67
	v_div_fmas_f32 v67, v67, v71, v69
	v_div_fixup_f32 v68, v67, v65, 1.0
	v_mul_f32_e32 v65, v0, v68
	v_mul_f32_e32 v0, v33, v68
	v_mul_f32_e32 v67, v1, v68
	v_mul_f32_e32 v1, v34, v68
	v_mul_f32_e32 v0, v64, v0
	v_mul_f32_e32 v32, v32, v68
	v_mul_f32_e32 v69, v2, v68
	v_mul_f32_e32 v2, v35, v68
	v_mul_f32_e32 v33, v37, v68
	v_mul_f32_e32 v37, v41, v68
	v_mul_f32_e32 v41, v45, v68
	v_fma_f32 v45, v49, v66, -v0
	v_mul_f32_e32 v0, v64, v1
	v_mul_f32_e32 v70, v3, v68
	v_mul_f32_e32 v3, v36, v68
	v_mul_f32_e32 v35, v39, v68
	v_mul_f32_e32 v39, v43, v68
	v_mul_f32_e32 v43, v47, v68
	v_mul_f32_e32 v32, v64, v32
	v_fma_f32 v47, v50, v66, -v0
	v_mul_f32_e32 v0, v64, v2
	v_mul_f32_e32 v36, v40, v68
	v_mul_f32_e32 v40, v44, v68
	v_fma_f32 v44, v48, v66, -v32
	v_fma_f32 v48, v51, v66, -v0
	v_mul_f32_e32 v0, v64, v3
	v_mul_f32_e32 v34, v38, v68
	v_fma_f32 v49, v52, v66, -v0
	v_mul_f32_e32 v0, v64, v33
	s_mov_b32 s6, 23
	v_fma_f32 v50, v53, v66, -v0
	v_mul_f32_e32 v0, v64, v34
	s_ashr_i32 s7, s6, 31
	v_fma_f32 v51, v54, v66, -v0
	v_mul_f32_e32 v0, v64, v35
	s_lshl_b64 s[6:7], s[6:7], 3
	v_fma_f32 v52, v55, v66, -v0
	v_mul_f32_e32 v0, v64, v36
	s_add_u32 s6, s0, s6
	v_mul_f32_e32 v38, v42, v68
	v_fma_f32 v53, v56, v66, -v0
	v_mul_f32_e32 v0, v64, v37
	s_addc_u32 s7, s1, s7
	v_fma_f32 v54, v57, v66, -v0
	v_mul_f32_e32 v0, v64, v38
	s_load_dwordx2 s[6:7], s[6:7], 0x0
	v_mul_f32_e32 v42, v46, v68
	v_mul_f32_e32 v46, v45, v45
	v_fma_f32 v55, v58, v66, -v0
	v_mul_f32_e32 v0, v64, v39
	v_fmac_f32_e32 v46, v44, v44
	v_fma_f32 v56, v59, v66, -v0
	v_mul_f32_e32 v0, v64, v40
	v_fmac_f32_e32 v46, v47, v47
	v_fma_f32 v57, v60, v66, -v0
	v_mul_f32_e32 v0, v64, v41
	v_fmac_f32_e32 v46, v48, v48
	v_fma_f32 v58, v61, v66, -v0
	s_lshl_b64 s[8:9], s[8:9], 2
	v_lshrrev_b32_e32 v0, 3, v164
	v_fmac_f32_e32 v46, v49, v49
	s_waitcnt lgkmcnt(0)
; DI int oidx(int i) { asm volatile("" : "+s"(i)); return i; }
; DI unsigned pack2(float a, float b) { unsigned r; asm volatile("v_cvt_pk_bf16_f32 %0, %1, %2" : "=v"(r) : "v"(a), "v"(b)); return r; }
; DI void store_o(bfr* O, int m, int colbase, int h, const f32x16 (&o)[2]) {
; #pragma unroll
;   for (int dt = 0; dt < 2; ++dt)
; #pragma unroll
;     for (int g4 = 0; g4 < 4; ++g4) {
;       int dv = dt * 32 + 8 * g4 + 4 * h;
;       uint2 pk; pk.x = pack2(o[dt][4 * g4], o[dt][4 * g4 + 1]); pk.y = pack2(o[dt][4 * g4 + 2], o[dt][4 * g4 + 3]);
;       *(uint2*)(O + (size_t)m * DM + colbase + dv) = pk;
;     }
; }
; DN void da_item(const Params& p, int l, int b, int hd, int tq0, int key0, int nkt, char* smem) {
;     ...
;     for (int i = 0; i < 16; ++i) { float v = o0[dt][i] - lam * o1[dt][i]; o0[dt][i] = v; ss += v * v; }
;   ss += __shfl_xor(ss, 32);
;   float rstd = rsqrtf(ss * (1.f / 64.f) + 1e-6f) * (1.f - lam_init);
;   const float* sg = p.in[oidx(23)] + l * 64;
; #pragma unroll
;   for (int dt = 0; dt < 2; ++dt)
; #pragma unroll
;     for (int i = 0; i < 16; ++i) { int dv = dt * 32 + 8 * (i >> 2) + 4 * h + (i & 3); o0[dt][i] = o0[dt][i] * rstd * sg[dv]; }
;   store_o(O, b * TT + tqw + r, 256 + hd * 64, h, o0);
	s_add_u32 s6, s6, s8
	v_and_b32_e32 v59, 4, v0
	v_fmac_f32_e32 v46, v50, v50
	s_addc_u32 s7, s7, s9
	v_lshlrev_b32_e32 v60, 2, v59
	v_mfma_f32_32x32x16_bf16 v[16:31], v[74:77], v[90:93], v[16:31]
	v_fmac_f32_e32 v46, v51, v51
	global_load_dwordx4 v[0:3], v60, s[6:7]
	v_fmac_f32_e32 v46, v52, v52
	v_fmac_f32_e32 v46, v53, v53
	v_mul_f32_e32 v32, v64, v42
	v_fmac_f32_e32 v46, v54, v54
	v_fma_f32 v61, v62, v66, -v32
	v_mul_f32_e32 v32, v64, v43
	v_fmac_f32_e32 v46, v55, v55
	v_fma_f32 v62, v63, v66, -v32
	global_load_dwordx4 v[32:35], v60, s[6:7] offset:32
	v_fmac_f32_e32 v46, v56, v56
	v_fmac_f32_e32 v46, v57, v57
	v_fmac_f32_e32 v46, v58, v58
	v_mul_f32_e32 v36, v64, v65
	v_fmac_f32_e32 v46, v61, v61
	v_fma_f32 v63, v16, v66, -v36
	v_mul_f32_e32 v16, v64, v67
	global_load_dwordx4 v[36:39], v60, s[6:7] offset:64
	v_mul_f32_e32 v4, v4, v68
	v_fmac_f32_e32 v46, v62, v62
	v_fma_f32 v65, v17, v66, -v16
	v_mul_f32_e32 v16, v64, v69
	v_mul_f32_e32 v5, v5, v68
	v_fmac_f32_e32 v46, v63, v63
	v_fma_f32 v67, v18, v66, -v16
	v_mul_f32_e32 v16, v64, v70
	v_mul_f32_e32 v4, v64, v4
	v_fmac_f32_e32 v46, v65, v65
	v_fma_f32 v69, v19, v66, -v16
	v_fma_f32 v70, v20, v66, -v4
	v_mul_f32_e32 v4, v64, v5
	v_fmac_f32_e32 v46, v67, v67
	global_load_dwordx4 v[16:19], v60, s[6:7] offset:96
	v_fma_f32 v71, v21, v66, -v4
	v_pk_mul_f32 v[4:5], v[6:7], v[68:69] op_sel_hi:[1,0]
	v_fmac_f32_e32 v46, v69, v69
	v_pk_mul_f32 v[4:5], v[64:65], v[4:5] op_sel_hi:[0,1]
	v_fmac_f32_e32 v46, v70, v70
	v_pk_fma_f32 v[40:41], v[22:23], v[66:67], v[4:5] op_sel_hi:[1,0,1] neg_lo:[0,0,1] neg_hi:[0,0,1]
	v_pk_mul_f32 v[8:9], v[8:9], v[68:69] op_sel_hi:[1,0]
	v_fmac_f32_e32 v46, v71, v71
	v_pk_mul_f32 v[20:21], v[40:41], v[40:41]
	v_pk_mul_f32 v[8:9], v[64:65], v[8:9] op_sel_hi:[0,1]
	global_load_dwordx4 v[4:7], v60, s[6:7] offset:128
	v_add_f32_e32 v20, v20, v46
	v_pk_fma_f32 v[24:25], v[24:25], v[66:67], v[8:9] op_sel_hi:[1,0,1] neg_lo:[0,0,1] neg_hi:[0,0,1]
	v_add_f32_e32 v20, v21, v20
	v_pk_mul_f32 v[8:9], v[24:25], v[24:25]
	v_pk_mul_f32 v[12:13], v[12:13], v[68:69] op_sel_hi:[1,0]
	v_add_f32_e32 v8, v8, v20
	v_add_f32_e32 v42, v9, v8
	v_pk_mul_f32 v[8:9], v[10:11], v[68:69] op_sel_hi:[1,0]
	global_load_dwordx4 v[20:23], v60, s[6:7] offset:160
	v_pk_mul_f32 v[8:9], v[64:65], v[8:9] op_sel_hi:[0,1]
	v_pk_fma_f32 v[26:27], v[26:27], v[66:67], v[8:9] op_sel_hi:[1,0,1] neg_lo:[0,0,1] neg_hi:[0,0,1]
	v_pk_mul_f32 v[12:13], v[64:65], v[12:13] op_sel_hi:[0,1]
	v_pk_mul_f32 v[8:9], v[26:27], v[26:27]
	v_pk_fma_f32 v[28:29], v[28:29], v[66:67], v[12:13] op_sel_hi:[1,0,1] neg_lo:[0,0,1] neg_hi:[0,0,1]
	v_add_f32_e32 v8, v8, v42
	v_add_f32_e32 v42, v9, v8
	global_load_dwordx4 v[8:11], v60, s[6:7] offset:192
	v_pk_mul_f32 v[12:13], v[28:29], v[28:29]
	s_load_dwordx4 s[8:11], s[0:1], 0x100
	v_add_f32_e32 v12, v12, v42
	v_add_f32_e32 v46, v13, v12
	v_pk_mul_f32 v[42:43], v[14:15], v[68:69] op_sel_hi:[1,0]
	global_load_dwordx4 v[12:15], v60, s[6:7] offset:224
	v_pk_mul_f32 v[42:43], v[64:65], v[42:43] op_sel_hi:[0,1]
	v_pk_fma_f32 v[30:31], v[30:31], v[66:67], v[42:43] op_sel_hi:[1,0,1] neg_lo:[0,0,1] neg_hi:[0,0,1]
	s_mov_b64 s[6:7], 0x2b7c300
	v_pk_mul_f32 v[42:43], v[30:31], v[30:31]
	s_nop 0
	v_add_f32_e32 v42, v42, v46
	v_add_f32_e32 v42, v43, v42
	ds_bpermute_b32 v43, v166, v42
	s_waitcnt lgkmcnt(0)
	v_add_f32_e32 v42, v42, v43
	v_fmamk_f32 v42, v42, 0x3c800000, v186
	v_cmp_gt_f32_e32 vcc, s33, v42
	v_mul_f32_e32 v43, 0x4b800000, v42
	s_nop 0
	v_cndmask_b32_e32 v42, v42, v43, vcc
	v_rsq_f32_e32 v42, v42
	s_nop 0
	v_mul_f32_e32 v43, 0x45800000, v42
	v_cndmask_b32_e32 v42, v42, v43, vcc
	v_mul_f32_e32 v42, v162, v42
	v_mul_f32_e32 v43, v44, v42
	s_waitcnt vmcnt(7)
	v_mul_f32_e32 v43, v0, v43
	v_mul_f32_e32 v0, v45, v42
	v_mul_f32_e32 v44, v1, v0
	v_mul_f32_e32 v0, v47, v42
	v_mul_f32_e32 v45, v2, v0
	v_mul_f32_e32 v0, v48, v42
	v_mul_f32_e32 v3, v3, v0
	v_mul_f32_e32 v0, v49, v42
	s_waitcnt vmcnt(6)
	v_mul_f32_e32 v32, v32, v0
	v_mul_f32_e32 v0, v50, v42
	v_mul_f32_e32 v33, v33, v0
	v_mul_f32_e32 v0, v51, v42
	v_mul_f32_e32 v34, v34, v0
	v_mul_f32_e32 v0, v52, v42
	v_mul_f32_e32 v35, v35, v0
	v_mul_f32_e32 v0, v53, v42
	s_waitcnt vmcnt(5)
	v_mul_f32_e32 v36, v36, v0
	v_mul_f32_e32 v0, v54, v42
	v_mul_f32_e32 v37, v37, v0
	v_mul_f32_e32 v0, v55, v42
	v_mul_f32_e32 v38, v38, v0
	v_mul_f32_e32 v0, v56, v42
	v_mul_f32_e32 v39, v39, v0
	v_mul_f32_e32 v0, v57, v42
	s_waitcnt vmcnt(4)
	v_mul_f32_e32 v16, v16, v0
	v_mul_f32_e32 v0, v58, v42
	v_mul_f32_e32 v17, v17, v0
	v_mul_f32_e32 v0, v61, v42
	v_mul_f32_e32 v18, v18, v0
	v_mul_f32_e32 v0, v62, v42
	v_mul_f32_e32 v19, v19, v0
	v_mul_f32_e32 v0, v63, v42
	s_waitcnt vmcnt(3)
	v_mul_f32_e32 v46, v4, v0
	v_mul_f32_e32 v0, v65, v42
	v_mul_f32_e32 v47, v5, v0
	v_mul_f32_e32 v0, v67, v42
	v_mul_f32_e32 v6, v6, v0
	v_mul_f32_e32 v0, v69, v42
	v_mul_f32_e32 v7, v7, v0
	v_mul_f32_e32 v0, v70, v42
	s_waitcnt vmcnt(2)
	v_mul_f32_e32 v20, v20, v0
	v_mul_f32_e32 v0, v71, v42
	v_mul_f32_e32 v21, v21, v0
	v_mul_f32_e32 v0, v40, v42
	v_mul_f32_e32 v22, v22, v0
	v_mul_f32_e32 v0, v41, v42
	v_mul_f32_e32 v23, v23, v0
	v_mul_f32_e32 v0, v24, v42
	s_waitcnt vmcnt(1)
	v_mul_f32_e32 v8, v8, v0
	v_mul_f32_e32 v0, v25, v42
	v_mul_f32_e32 v9, v9, v0
	v_mul_f32_e32 v0, v26, v42
	v_mul_f32_e32 v10, v10, v0
	v_mul_f32_e32 v0, v27, v42
	v_mul_f32_e32 v11, v11, v0
	v_mul_f32_e32 v0, v28, v42
	s_waitcnt vmcnt(0)
	v_mul_f32_e32 v12, v12, v0
	v_mul_f32_e32 v0, v29, v42
	v_mul_f32_e32 v13, v13, v0
	v_mul_f32_e32 v0, v30, v42
	v_mul_f32_e32 v14, v14, v0
	v_mul_f32_e32 v0, v31, v42
	v_mul_f32_e32 v15, v15, v0
	v_and_or_b32 v0, v164, 31, v165
	v_ashrrev_i32_e32 v1, 31, v0
	v_lshlrev_b64 v[0:1], 11, v[0:1]
	v_lshl_add_u64 v[0:1], s[10:11], 0, v[0:1]
	v_lshl_add_u64 v[0:1], v[0:1], 0, v[152:153]
	v_lshlrev_b32_e32 v152, 1, v59
	v_lshl_add_u64 v[0:1], v[0:1], 0, v[152:153]
	v_lshl_add_u64 v[4:5], v[0:1], 0, s[6:7]
	s_mov_b32 s6, 0x2b7c000
	v_add_co_u32_e32 v0, vcc, s6, v0
	v_cvt_pk_bf16_f32 v2, v43, v44
	v_cvt_pk_bf16_f32 v3, v45, v3
	s_nop 1
	v_addc_co_u32_e32 v1, vcc, 0, v1, vcc
	global_store_dwordx2 v[0:1], v[2:3], off offset:768
	v_cvt_pk_bf16_f32 v0, v32, v33
	v_cvt_pk_bf16_f32 v1, v34, v35
	global_store_dwordx2 v[4:5], v[0:1], off offset:16
	v_cvt_pk_bf16_f32 v0, v36, v37
	v_cvt_pk_bf16_f32 v1, v38, v39
	global_store_dwordx2 v[4:5], v[0:1], off offset:32
	v_cvt_pk_bf16_f32 v0, v16, v17
	v_cvt_pk_bf16_f32 v1, v18, v19
	global_store_dwordx2 v[4:5], v[0:1], off offset:48
	v_cvt_pk_bf16_f32 v0, v46, v47
	v_cvt_pk_bf16_f32 v1, v6, v7
	global_store_dwordx2 v[4:5], v[0:1], off offset:64
	v_cvt_pk_bf16_f32 v0, v20, v21
	v_cvt_pk_bf16_f32 v1, v22, v23
	global_store_dwordx2 v[4:5], v[0:1], off offset:80
	v_cvt_pk_bf16_f32 v0, v8, v9
	v_cvt_pk_bf16_f32 v1, v10, v11
	global_store_dwordx2 v[4:5], v[0:1], off offset:96
	v_cvt_pk_bf16_f32 v0, v12, v13
	v_cvt_pk_bf16_f32 v1, v14, v15
	global_store_dwordx2 v[4:5], v[0:1], off offset:112
